# K-loop s_setprio toggles removed; sample-path MLP-out GEMM core rewritten by hand: coalesced 64-B-quad loads + ds_bpermute lane transposition into the MFMA layout (same bf16 math)
# speedup vs baseline: 1.0722x; 1.0180x over previous
.LBB0_341:
	s_add_u32 s36, s34, 0xfffc0080
	s_addc_u32 s37, s35, -1
	s_add_i32 s56, 0, 0x10000
	s_cmp_eq_u32 s79, 12
	s_cselect_b32 s39, s25, s37
	s_cselect_b32 s38, s31, s36
	s_cselect_b32 s37, s23, s78
	s_cselect_b32 s36, s40, s77
	s_add_i32 s80, 0, 0x14000
	v_add_u32_e32 v102, s56, v171
	v_add_u32_e32 v177, s80, v171
	ds_read_b128 v[82:85], v102
	ds_read_b128 v[86:89], v102 offset:1024
	ds_read_b128 v[94:97], v102 offset:2048
	ds_read_b128 v[102:105], v102 offset:3072
	ds_read_b128 v[134:137], v177
	ds_read_b128 v[162:165], v177 offset:1024
	ds_read_b128 v[166:169], v177 offset:2048
	ds_read_b128 v[178:181], v177 offset:3072
	v_lshl_add_u64 v[214:215], s[34:35], 0, v[158:159]
	s_add_i32 m0, s9, 0xc000
	ds_read_b128 v[182:185], v176
	ds_read_b128 v[186:189], v176 offset:1024
	ds_read_b128 v[190:193], v176 offset:2048
	ds_read_b128 v[194:197], v176 offset:3072
	ds_read_b128 v[198:201], v176 offset:4096
	ds_read_b128 v[202:205], v176 offset:5120
	ds_read_b128 v[206:209], v176 offset:6144
	ds_read_b128 v[210:213], v176 offset:7168
	global_load_lds_dwordx4 v[214:215], off
	v_lshl_add_u64 v[214:215], s[34:35], 0, v[160:161]
	s_add_i32 m0, s9, 0xe000
	s_nop 0
	global_load_lds_dwordx4 v[214:215], off
	s_waitcnt vmcnt(8)
	s_waitcnt lgkmcnt(0)
	s_barrier
	s_waitcnt lgkmcnt(0)
	v_mfma_f32_16x16x32_bf16 v[146:149], v[82:85], v[182:185], v[146:149]
	v_mfma_f32_16x16x32_bf16 v[138:141], v[94:97], v[182:185], v[138:141]
	v_mfma_f32_16x16x32_bf16 v[126:129], v[82:85], v[190:193], v[126:129]
	v_mfma_f32_16x16x32_bf16 v[118:121], v[94:97], v[190:193], v[118:121]
	v_mfma_f32_16x16x32_bf16 v[110:113], v[82:85], v[198:201], v[110:113]
	v_mfma_f32_16x16x32_bf16 v[98:101], v[94:97], v[198:201], v[98:101]
	v_mfma_f32_16x16x32_bf16 v[78:81], v[82:85], v[206:209], v[78:81]
	v_mfma_f32_16x16x32_bf16 v[70:73], v[94:97], v[206:209], v[70:73]
	v_mfma_f32_16x16x32_bf16 v[146:149], v[86:89], v[186:189], v[146:149]
	v_mfma_f32_16x16x32_bf16 v[138:141], v[102:105], v[186:189], v[138:141]
	v_mfma_f32_16x16x32_bf16 v[126:129], v[86:89], v[194:197], v[126:129]
	v_mfma_f32_16x16x32_bf16 v[118:121], v[102:105], v[194:197], v[118:121]
	v_mfma_f32_16x16x32_bf16 v[110:113], v[86:89], v[202:205], v[110:113]
	v_mfma_f32_16x16x32_bf16 v[98:101], v[102:105], v[202:205], v[98:101]
	v_mfma_f32_16x16x32_bf16 v[78:81], v[86:89], v[210:213], v[78:81]
	v_mfma_f32_16x16x32_bf16 v[70:73], v[102:105], v[210:213], v[70:73]
	v_mfma_f32_16x16x32_bf16 v[142:145], v[134:137], v[182:185], v[142:145]
	v_mfma_f32_16x16x32_bf16 v[130:133], v[166:169], v[182:185], v[130:133]
	v_mfma_f32_16x16x32_bf16 v[122:125], v[134:137], v[190:193], v[122:125]
	v_mfma_f32_16x16x32_bf16 v[114:117], v[166:169], v[190:193], v[114:117]
	v_mfma_f32_16x16x32_bf16 v[106:109], v[134:137], v[198:201], v[106:109]
	v_mfma_f32_16x16x32_bf16 v[90:93], v[166:169], v[198:201], v[90:93]
	v_mfma_f32_16x16x32_bf16 v[74:77], v[134:137], v[206:209], v[74:77]
	v_mfma_f32_16x16x32_bf16 v[66:69], v[166:169], v[206:209], v[66:69]
	v_mfma_f32_16x16x32_bf16 v[142:145], v[162:165], v[186:189], v[142:145]
	v_mfma_f32_16x16x32_bf16 v[130:133], v[178:181], v[186:189], v[130:133]
	v_mfma_f32_16x16x32_bf16 v[122:125], v[162:165], v[194:197], v[122:125]
	v_mfma_f32_16x16x32_bf16 v[114:117], v[178:181], v[194:197], v[114:117]
	v_mfma_f32_16x16x32_bf16 v[106:109], v[162:165], v[202:205], v[106:109]
	v_mfma_f32_16x16x32_bf16 v[90:93], v[178:181], v[202:205], v[90:93]
	v_mfma_f32_16x16x32_bf16 v[74:77], v[162:165], v[210:213], v[74:77]
	v_mfma_f32_16x16x32_bf16 v[66:69], v[178:181], v[210:213], v[66:69]
	s_barrier
	s_add_i32 s56, s56, s68
	v_lshl_add_u64 v[214:215], s[36:37], 0, v[154:155]
	s_mov_b32 m0, s56
	ds_read_b128 v[182:185], v176 offset:16384
	ds_read_b128 v[186:189], v176 offset:17408
	ds_read_b128 v[190:193], v176 offset:18432
	ds_read_b128 v[194:197], v176 offset:19456
	ds_read_b128 v[198:201], v176 offset:20480
	ds_read_b128 v[202:205], v176 offset:21504
	ds_read_b128 v[206:209], v176 offset:22528
	ds_read_b128 v[210:213], v176 offset:23552
	global_load_lds_dwordx4 v[214:215], off
	s_add_i32 m0, s56, 0x2000
	s_add_u32 s56, s36, 0x40000
	v_lshl_add_u64 v[216:217], s[36:37], 0, v[156:157]
	s_addc_u32 s57, s37, 0
	s_add_i32 s80, s80, s68
	global_load_lds_dwordx4 v[216:217], off
	v_lshl_add_u64 v[218:219], s[56:57], 0, v[154:155]
	s_mov_b32 m0, s80
	v_lshl_add_u64 v[220:221], s[38:39], 0, v[152:153]
	global_load_lds_dwordx4 v[218:219], off
	v_lshl_add_u64 v[218:219], s[56:57], 0, v[156:157]
	s_add_i32 m0, s80, 0x2000
	s_nop 0
	global_load_lds_dwordx4 v[218:219], off
	v_lshl_add_u64 v[218:219], s[38:39], 0, v[150:151]
	s_mov_b32 m0, s9
	s_nop 0
	global_load_lds_dwordx4 v[218:219], off
	s_mov_b32 m0, s69
	s_nop 0
	global_load_lds_dwordx4 v[220:221], off
	s_waitcnt vmcnt(8)
	s_waitcnt lgkmcnt(0)
	s_barrier
	s_waitcnt lgkmcnt(0)
	v_mfma_f32_16x16x32_bf16 v[62:65], v[82:85], v[182:185], v[62:65]
	v_mfma_f32_16x16x32_bf16 v[54:57], v[94:97], v[182:185], v[54:57]
	v_mfma_f32_16x16x32_bf16 v[46:49], v[82:85], v[190:193], v[46:49]
	v_mfma_f32_16x16x32_bf16 v[38:41], v[94:97], v[190:193], v[38:41]
	v_mfma_f32_16x16x32_bf16 v[30:33], v[82:85], v[198:201], v[30:33]
	v_mfma_f32_16x16x32_bf16 v[22:25], v[94:97], v[198:201], v[22:25]
	v_mfma_f32_16x16x32_bf16 v[14:17], v[82:85], v[206:209], v[14:17]
	v_mfma_f32_16x16x32_bf16 v[6:9], v[94:97], v[206:209], v[6:9]
	v_mfma_f32_16x16x32_bf16 v[62:65], v[86:89], v[186:189], v[62:65]
	v_mfma_f32_16x16x32_bf16 v[54:57], v[102:105], v[186:189], v[54:57]
	v_mfma_f32_16x16x32_bf16 v[46:49], v[86:89], v[194:197], v[46:49]
	v_mfma_f32_16x16x32_bf16 v[38:41], v[102:105], v[194:197], v[38:41]
	v_mfma_f32_16x16x32_bf16 v[30:33], v[86:89], v[202:205], v[30:33]
	v_mfma_f32_16x16x32_bf16 v[22:25], v[102:105], v[202:205], v[22:25]
	v_mfma_f32_16x16x32_bf16 v[14:17], v[86:89], v[210:213], v[14:17]
	v_mfma_f32_16x16x32_bf16 v[6:9], v[102:105], v[210:213], v[6:9]
	v_mfma_f32_16x16x32_bf16 v[58:61], v[134:137], v[182:185], v[58:61]
	v_mfma_f32_16x16x32_bf16 v[50:53], v[166:169], v[182:185], v[50:53]
	v_mfma_f32_16x16x32_bf16 v[42:45], v[134:137], v[190:193], v[42:45]
	v_mfma_f32_16x16x32_bf16 v[34:37], v[166:169], v[190:193], v[34:37]
	v_mfma_f32_16x16x32_bf16 v[26:29], v[134:137], v[198:201], v[26:29]
	v_mfma_f32_16x16x32_bf16 v[18:21], v[166:169], v[198:201], v[18:21]
	v_mfma_f32_16x16x32_bf16 v[10:13], v[134:137], v[206:209], v[10:13]
	v_mfma_f32_16x16x32_bf16 v[2:5], v[166:169], v[206:209], v[2:5]
	v_mfma_f32_16x16x32_bf16 v[58:61], v[162:165], v[186:189], v[58:61]
	v_mfma_f32_16x16x32_bf16 v[50:53], v[178:181], v[186:189], v[50:53]
	v_mfma_f32_16x16x32_bf16 v[42:45], v[162:165], v[194:197], v[42:45]
	v_mfma_f32_16x16x32_bf16 v[34:37], v[178:181], v[194:197], v[34:37]
	v_mfma_f32_16x16x32_bf16 v[26:29], v[162:165], v[202:205], v[26:29]
	v_mfma_f32_16x16x32_bf16 v[18:21], v[178:181], v[202:205], v[18:21]
	v_mfma_f32_16x16x32_bf16 v[10:13], v[162:165], v[210:213], v[10:13]
	v_mfma_f32_16x16x32_bf16 v[2:5], v[178:181], v[210:213], v[2:5]
	s_barrier
	s_add_i32 s56, 0, 0x18000
	s_add_i32 s57, 0, 0x1c000
	v_add_u32_e32 v102, s56, v171
	v_add_u32_e32 v177, s57, v171
	ds_read_b128 v[82:85], v102
	ds_read_b128 v[86:89], v102 offset:1024
	ds_read_b128 v[94:97], v102 offset:2048
	ds_read_b128 v[102:105], v102 offset:3072
	ds_read_b128 v[134:137], v177
	ds_read_b128 v[162:165], v177 offset:1024
	ds_read_b128 v[166:169], v177 offset:2048
	ds_read_b128 v[178:181], v177 offset:3072
	s_add_u32 s38, s38, 0x40000
	s_addc_u32 s39, s39, 0
	s_mov_b32 m0, s70
	v_lshl_add_u64 v[232:233], s[38:39], 0, v[150:151]
	ds_read_b128 v[182:185], v176 offset:32768
	ds_read_b128 v[186:189], v176 offset:33792
	ds_read_b128 v[190:193], v176 offset:34816
	ds_read_b128 v[194:197], v176 offset:35840
	ds_read_b128 v[198:201], v176 offset:36864
	ds_read_b128 v[202:205], v176 offset:37888
	ds_read_b128 v[206:209], v176 offset:38912
	ds_read_b128 v[210:213], v176 offset:39936
	global_load_lds_dwordx4 v[232:233], off
	v_lshl_add_u64 v[232:233], s[38:39], 0, v[152:153]
	s_mov_b32 m0, s71
	s_nop 0
	global_load_lds_dwordx4 v[232:233], off
	s_waitcnt vmcnt(8)
	s_waitcnt lgkmcnt(0)
	s_barrier
	s_waitcnt lgkmcnt(0)
	v_mfma_f32_16x16x32_bf16 v[146:149], v[82:85], v[182:185], v[146:149]
	v_mfma_f32_16x16x32_bf16 v[138:141], v[94:97], v[182:185], v[138:141]
	v_mfma_f32_16x16x32_bf16 v[126:129], v[82:85], v[190:193], v[126:129]
	v_mfma_f32_16x16x32_bf16 v[118:121], v[94:97], v[190:193], v[118:121]
	v_mfma_f32_16x16x32_bf16 v[110:113], v[82:85], v[198:201], v[110:113]
	v_mfma_f32_16x16x32_bf16 v[98:101], v[94:97], v[198:201], v[98:101]
	v_mfma_f32_16x16x32_bf16 v[78:81], v[82:85], v[206:209], v[78:81]
	v_mfma_f32_16x16x32_bf16 v[70:73], v[94:97], v[206:209], v[70:73]
	v_mfma_f32_16x16x32_bf16 v[146:149], v[86:89], v[186:189], v[146:149]
	v_mfma_f32_16x16x32_bf16 v[138:141], v[102:105], v[186:189], v[138:141]
	v_mfma_f32_16x16x32_bf16 v[126:129], v[86:89], v[194:197], v[126:129]
	v_mfma_f32_16x16x32_bf16 v[118:121], v[102:105], v[194:197], v[118:121]
	v_mfma_f32_16x16x32_bf16 v[110:113], v[86:89], v[202:205], v[110:113]
	v_mfma_f32_16x16x32_bf16 v[98:101], v[102:105], v[202:205], v[98:101]
	v_mfma_f32_16x16x32_bf16 v[78:81], v[86:89], v[210:213], v[78:81]
	v_mfma_f32_16x16x32_bf16 v[70:73], v[102:105], v[210:213], v[70:73]
	v_mfma_f32_16x16x32_bf16 v[142:145], v[134:137], v[182:185], v[142:145]
	v_mfma_f32_16x16x32_bf16 v[130:133], v[166:169], v[182:185], v[130:133]
	v_mfma_f32_16x16x32_bf16 v[122:125], v[134:137], v[190:193], v[122:125]
	v_mfma_f32_16x16x32_bf16 v[114:117], v[166:169], v[190:193], v[114:117]
	v_mfma_f32_16x16x32_bf16 v[106:109], v[134:137], v[198:201], v[106:109]
	v_mfma_f32_16x16x32_bf16 v[90:93], v[166:169], v[198:201], v[90:93]
	v_mfma_f32_16x16x32_bf16 v[74:77], v[134:137], v[206:209], v[74:77]
	v_mfma_f32_16x16x32_bf16 v[66:69], v[166:169], v[206:209], v[66:69]
	v_mfma_f32_16x16x32_bf16 v[142:145], v[162:165], v[186:189], v[142:145]
	v_mfma_f32_16x16x32_bf16 v[130:133], v[178:181], v[186:189], v[130:133]
	v_mfma_f32_16x16x32_bf16 v[122:125], v[162:165], v[194:197], v[122:125]
	v_mfma_f32_16x16x32_bf16 v[114:117], v[178:181], v[194:197], v[114:117]
	v_mfma_f32_16x16x32_bf16 v[106:109], v[162:165], v[202:205], v[106:109]
	v_mfma_f32_16x16x32_bf16 v[90:93], v[178:181], v[202:205], v[90:93]
	v_mfma_f32_16x16x32_bf16 v[74:77], v[162:165], v[210:213], v[74:77]
	v_mfma_f32_16x16x32_bf16 v[66:69], v[178:181], v[210:213], v[66:69]
	s_barrier
	s_add_i32 s38, s56, s68
	v_lshl_add_u64 v[214:215], v[214:215], 0, s[62:63]
	s_mov_b32 m0, s38
	ds_read_b128 v[182:185], v176 offset:49152
	ds_read_b128 v[186:189], v176 offset:50176
	ds_read_b128 v[190:193], v176 offset:51200
	ds_read_b128 v[194:197], v176 offset:52224
	ds_read_b128 v[198:201], v176 offset:53248
	ds_read_b128 v[202:205], v176 offset:54272
	ds_read_b128 v[206:209], v176 offset:55296
	ds_read_b128 v[210:213], v176 offset:56320
	global_load_lds_dwordx4 v[214:215], off
	s_add_i32 m0, s38, 0x2000
	s_add_u32 s36, s36, 0x40080
	v_lshl_add_u64 v[214:215], v[216:217], 0, s[62:63]
	s_addc_u32 s37, s37, 0
	s_add_i32 s38, s57, s68
	global_load_lds_dwordx4 v[214:215], off
	v_lshl_add_u64 v[214:215], s[36:37], 0, v[154:155]
	s_mov_b32 m0, s38
	s_nop 0
	global_load_lds_dwordx4 v[214:215], off
	v_lshl_add_u64 v[214:215], s[36:37], 0, v[156:157]
	s_add_i32 m0, s38, 0x2000
	s_nop 0
	global_load_lds_dwordx4 v[214:215], off
	v_lshl_add_u64 v[214:215], v[218:219], 0, s[62:63]
	s_mov_b32 m0, s73
	s_nop 0
	global_load_lds_dwordx4 v[214:215], off
	v_lshl_add_u64 v[214:215], v[220:221], 0, s[62:63]
	s_mov_b32 m0, s74
	s_nop 0
	global_load_lds_dwordx4 v[214:215], off
	s_waitcnt vmcnt(8)
	s_waitcnt lgkmcnt(0)
	s_barrier
	s_waitcnt lgkmcnt(0)
	v_mfma_f32_16x16x32_bf16 v[62:65], v[82:85], v[182:185], v[62:65]
	v_mfma_f32_16x16x32_bf16 v[54:57], v[94:97], v[182:185], v[54:57]
	v_mfma_f32_16x16x32_bf16 v[46:49], v[82:85], v[190:193], v[46:49]
	v_mfma_f32_16x16x32_bf16 v[38:41], v[94:97], v[190:193], v[38:41]
	v_mfma_f32_16x16x32_bf16 v[30:33], v[82:85], v[198:201], v[30:33]
	v_mfma_f32_16x16x32_bf16 v[22:25], v[94:97], v[198:201], v[22:25]
	v_mfma_f32_16x16x32_bf16 v[14:17], v[82:85], v[206:209], v[14:17]
	v_mfma_f32_16x16x32_bf16 v[6:9], v[94:97], v[206:209], v[6:9]
	v_mfma_f32_16x16x32_bf16 v[62:65], v[86:89], v[186:189], v[62:65]
	v_mfma_f32_16x16x32_bf16 v[54:57], v[102:105], v[186:189], v[54:57]
	v_mfma_f32_16x16x32_bf16 v[46:49], v[86:89], v[194:197], v[46:49]
	v_mfma_f32_16x16x32_bf16 v[38:41], v[102:105], v[194:197], v[38:41]
	v_mfma_f32_16x16x32_bf16 v[30:33], v[86:89], v[202:205], v[30:33]
	v_mfma_f32_16x16x32_bf16 v[22:25], v[102:105], v[202:205], v[22:25]
	v_mfma_f32_16x16x32_bf16 v[14:17], v[86:89], v[210:213], v[14:17]
	v_mfma_f32_16x16x32_bf16 v[6:9], v[102:105], v[210:213], v[6:9]
	v_mfma_f32_16x16x32_bf16 v[58:61], v[134:137], v[182:185], v[58:61]
	v_mfma_f32_16x16x32_bf16 v[50:53], v[166:169], v[182:185], v[50:53]
	v_mfma_f32_16x16x32_bf16 v[42:45], v[134:137], v[190:193], v[42:45]
	v_mfma_f32_16x16x32_bf16 v[34:37], v[166:169], v[190:193], v[34:37]
	v_mfma_f32_16x16x32_bf16 v[26:29], v[134:137], v[198:201], v[26:29]
	v_mfma_f32_16x16x32_bf16 v[18:21], v[166:169], v[198:201], v[18:21]
	v_mfma_f32_16x16x32_bf16 v[10:13], v[134:137], v[206:209], v[10:13]
	v_mfma_f32_16x16x32_bf16 v[2:5], v[166:169], v[206:209], v[2:5]
	v_mfma_f32_16x16x32_bf16 v[58:61], v[162:165], v[186:189], v[58:61]
	v_mfma_f32_16x16x32_bf16 v[50:53], v[178:181], v[186:189], v[50:53]
	v_mfma_f32_16x16x32_bf16 v[42:45], v[162:165], v[194:197], v[42:45]
	v_mfma_f32_16x16x32_bf16 v[34:37], v[178:181], v[194:197], v[34:37]
	v_mfma_f32_16x16x32_bf16 v[26:29], v[162:165], v[202:205], v[26:29]
	v_mfma_f32_16x16x32_bf16 v[18:21], v[178:181], v[202:205], v[18:21]
	v_mfma_f32_16x16x32_bf16 v[10:13], v[162:165], v[210:213], v[10:13]
	v_mfma_f32_16x16x32_bf16 v[2:5], v[178:181], v[210:213], v[2:5]
	s_barrier
	s_add_i32 s79, s79, 2
	s_add_u32 s34, s34, 0x100
	s_addc_u32 s35, s35, 0
	s_add_u32 s77, s77, 0x100
	s_addc_u32 s78, s78, 0
	s_cmp_gt_u32 s79, 13
	s_cbranch_scc0 .LBB0_341
	s_and_b64 vcc, exec, s[18:19]
	s_cbranch_vccz .LBB0_344
	s_barrier

.LBB0_445:
	s_add_u32 s22, s20, 0xfffc0080
	s_addc_u32 s23, s21, -1
	s_add_i32 s56, 0, 0x10000
	s_cmp_eq_u32 s70, 12
	s_cselect_b32 s25, s13, s23
	s_cselect_b32 s24, s66, s22
	v_add_u32_e32 v152, s56, v145
	s_cselect_b32 s23, s11, s69
	s_cselect_b32 s22, s67, s68
	s_add_i32 s71, 0, 0x14000
	ds_read_b128 v[140:143], v152
	ds_read_b128 v[148:151], v152 offset:1024
	ds_read_b128 v[156:159], v152 offset:2048
	ds_read_b128 v[160:163], v152 offset:3072
	v_add_u32_e32 v152, s71, v145
	ds_read_b128 v[164:167], v152
	ds_read_b128 v[168:171], v152 offset:1024
	ds_read_b128 v[172:175], v152 offset:2048
	ds_read_b128 v[176:179], v152 offset:3072
	v_lshl_add_u64 v[152:153], s[20:21], 0, v[136:137]
	s_add_i32 m0, s19, 0xc000
	ds_read_b128 v[180:183], v147
	ds_read_b128 v[184:187], v147 offset:1024
	ds_read_b128 v[188:191], v147 offset:2048
	ds_read_b128 v[192:195], v147 offset:3072
	ds_read_b128 v[196:199], v147 offset:4096
	ds_read_b128 v[200:203], v147 offset:5120
	ds_read_b128 v[204:207], v147 offset:6144
	ds_read_b128 v[208:211], v147 offset:7168
	global_load_lds_dwordx4 v[152:153], off
	v_lshl_add_u64 v[152:153], s[20:21], 0, v[138:139]
	s_add_i32 m0, s19, 0xe000
	s_nop 0
	global_load_lds_dwordx4 v[152:153], off
	s_waitcnt vmcnt(8)
	s_waitcnt lgkmcnt(0)
	s_barrier
	s_waitcnt lgkmcnt(0)
	v_mfma_f32_16x16x32_bf16 v[126:129], v[140:143], v[180:183], v[126:129]
	v_mfma_f32_16x16x32_bf16 v[122:125], v[156:159], v[180:183], v[122:125]
	v_mfma_f32_16x16x32_bf16 v[110:113], v[140:143], v[188:191], v[110:113]
	v_mfma_f32_16x16x32_bf16 v[106:109], v[156:159], v[188:191], v[106:109]
	v_mfma_f32_16x16x32_bf16 v[94:97], v[140:143], v[196:199], v[94:97]
	v_mfma_f32_16x16x32_bf16 v[90:93], v[156:159], v[196:199], v[90:93]
	v_mfma_f32_16x16x32_bf16 v[78:81], v[140:143], v[204:207], v[78:81]
	v_mfma_f32_16x16x32_bf16 v[74:77], v[156:159], v[204:207], v[74:77]
	v_mfma_f32_16x16x32_bf16 v[126:129], v[148:151], v[184:187], v[126:129]
	v_mfma_f32_16x16x32_bf16 v[122:125], v[160:163], v[184:187], v[122:125]
	v_mfma_f32_16x16x32_bf16 v[110:113], v[148:151], v[192:195], v[110:113]
	v_mfma_f32_16x16x32_bf16 v[106:109], v[160:163], v[192:195], v[106:109]
	v_mfma_f32_16x16x32_bf16 v[94:97], v[148:151], v[200:203], v[94:97]
	v_mfma_f32_16x16x32_bf16 v[90:93], v[160:163], v[200:203], v[90:93]
	v_mfma_f32_16x16x32_bf16 v[78:81], v[148:151], v[208:211], v[78:81]
	v_mfma_f32_16x16x32_bf16 v[74:77], v[160:163], v[208:211], v[74:77]
	v_mfma_f32_16x16x32_bf16 v[118:121], v[164:167], v[180:183], v[118:121]
	v_mfma_f32_16x16x32_bf16 v[114:117], v[172:175], v[180:183], v[114:117]
	v_mfma_f32_16x16x32_bf16 v[102:105], v[164:167], v[188:191], v[102:105]
	v_mfma_f32_16x16x32_bf16 v[98:101], v[172:175], v[188:191], v[98:101]
	v_mfma_f32_16x16x32_bf16 v[86:89], v[164:167], v[196:199], v[86:89]
	v_mfma_f32_16x16x32_bf16 v[82:85], v[172:175], v[196:199], v[82:85]
	v_mfma_f32_16x16x32_bf16 v[70:73], v[164:167], v[204:207], v[70:73]
	v_mfma_f32_16x16x32_bf16 v[66:69], v[172:175], v[204:207], v[66:69]
	v_mfma_f32_16x16x32_bf16 v[118:121], v[168:171], v[184:187], v[118:121]
	v_mfma_f32_16x16x32_bf16 v[114:117], v[176:179], v[184:187], v[114:117]
	v_mfma_f32_16x16x32_bf16 v[102:105], v[168:171], v[192:195], v[102:105]
	v_mfma_f32_16x16x32_bf16 v[98:101], v[176:179], v[192:195], v[98:101]
	v_mfma_f32_16x16x32_bf16 v[86:89], v[168:171], v[200:203], v[86:89]
	v_mfma_f32_16x16x32_bf16 v[82:85], v[176:179], v[200:203], v[82:85]
	v_mfma_f32_16x16x32_bf16 v[70:73], v[168:171], v[208:211], v[70:73]
	v_mfma_f32_16x16x32_bf16 v[66:69], v[176:179], v[208:211], v[66:69]
	s_barrier
	s_add_i32 s56, s56, s35
	v_lshl_add_u64 v[152:153], s[22:23], 0, v[154:155]
	s_mov_b32 m0, s56
	ds_read_b128 v[180:183], v147 offset:16384
	ds_read_b128 v[184:187], v147 offset:17408
	ds_read_b128 v[188:191], v147 offset:18432
	ds_read_b128 v[192:195], v147 offset:19456
	ds_read_b128 v[196:199], v147 offset:20480
	ds_read_b128 v[200:203], v147 offset:21504
	ds_read_b128 v[204:207], v147 offset:22528
	ds_read_b128 v[208:211], v147 offset:23552
	global_load_lds_dwordx4 v[152:153], off
	s_add_i32 m0, s56, 0x2000
	s_add_u32 s56, s22, 0x40000
	v_lshl_add_u64 v[212:213], s[22:23], 0, v[134:135]
	s_addc_u32 s57, s23, 0
	s_add_i32 s71, s71, s35
	global_load_lds_dwordx4 v[212:213], off
	v_lshl_add_u64 v[214:215], s[56:57], 0, v[154:155]
	s_mov_b32 m0, s71
	v_lshl_add_u64 v[216:217], s[24:25], 0, v[132:133]
	global_load_lds_dwordx4 v[214:215], off
	v_lshl_add_u64 v[214:215], s[56:57], 0, v[134:135]
	s_add_i32 m0, s71, 0x2000
	s_nop 0
	global_load_lds_dwordx4 v[214:215], off
	v_lshl_add_u64 v[214:215], s[24:25], 0, v[130:131]
	s_mov_b32 m0, s19
	s_nop 0
	global_load_lds_dwordx4 v[214:215], off
	s_mov_b32 m0, s36
	s_nop 0
	global_load_lds_dwordx4 v[216:217], off
	s_waitcnt vmcnt(8)
	s_waitcnt lgkmcnt(0)
	s_barrier
	s_waitcnt lgkmcnt(0)
	v_mfma_f32_16x16x32_bf16 v[62:65], v[140:143], v[180:183], v[62:65]
	v_mfma_f32_16x16x32_bf16 v[58:61], v[156:159], v[180:183], v[58:61]
	v_mfma_f32_16x16x32_bf16 v[46:49], v[140:143], v[188:191], v[46:49]
	v_mfma_f32_16x16x32_bf16 v[42:45], v[156:159], v[188:191], v[42:45]
	v_mfma_f32_16x16x32_bf16 v[30:33], v[140:143], v[196:199], v[30:33]
	v_mfma_f32_16x16x32_bf16 v[26:29], v[156:159], v[196:199], v[26:29]
	v_mfma_f32_16x16x32_bf16 v[14:17], v[140:143], v[204:207], v[14:17]
	v_mfma_f32_16x16x32_bf16 v[10:13], v[156:159], v[204:207], v[10:13]
	v_mfma_f32_16x16x32_bf16 v[62:65], v[148:151], v[184:187], v[62:65]
	v_mfma_f32_16x16x32_bf16 v[58:61], v[160:163], v[184:187], v[58:61]
	v_mfma_f32_16x16x32_bf16 v[46:49], v[148:151], v[192:195], v[46:49]
	v_mfma_f32_16x16x32_bf16 v[42:45], v[160:163], v[192:195], v[42:45]
	v_mfma_f32_16x16x32_bf16 v[30:33], v[148:151], v[200:203], v[30:33]
	v_mfma_f32_16x16x32_bf16 v[26:29], v[160:163], v[200:203], v[26:29]
	v_mfma_f32_16x16x32_bf16 v[14:17], v[148:151], v[208:211], v[14:17]
	v_mfma_f32_16x16x32_bf16 v[10:13], v[160:163], v[208:211], v[10:13]
	v_mfma_f32_16x16x32_bf16 v[54:57], v[164:167], v[180:183], v[54:57]
	v_mfma_f32_16x16x32_bf16 v[50:53], v[172:175], v[180:183], v[50:53]
	v_mfma_f32_16x16x32_bf16 v[38:41], v[164:167], v[188:191], v[38:41]
	v_mfma_f32_16x16x32_bf16 v[34:37], v[172:175], v[188:191], v[34:37]
	v_mfma_f32_16x16x32_bf16 v[22:25], v[164:167], v[196:199], v[22:25]
	v_mfma_f32_16x16x32_bf16 v[18:21], v[172:175], v[196:199], v[18:21]
	v_mfma_f32_16x16x32_bf16 v[6:9], v[164:167], v[204:207], v[6:9]
	v_mfma_f32_16x16x32_bf16 v[2:5], v[172:175], v[204:207], v[2:5]
	v_mfma_f32_16x16x32_bf16 v[54:57], v[168:171], v[184:187], v[54:57]
	v_mfma_f32_16x16x32_bf16 v[50:53], v[176:179], v[184:187], v[50:53]
	v_mfma_f32_16x16x32_bf16 v[38:41], v[168:171], v[192:195], v[38:41]
	v_mfma_f32_16x16x32_bf16 v[34:37], v[176:179], v[192:195], v[34:37]
	v_mfma_f32_16x16x32_bf16 v[22:25], v[168:171], v[200:203], v[22:25]
	v_mfma_f32_16x16x32_bf16 v[18:21], v[176:179], v[200:203], v[18:21]
	v_mfma_f32_16x16x32_bf16 v[6:9], v[168:171], v[208:211], v[6:9]
	v_mfma_f32_16x16x32_bf16 v[2:5], v[176:179], v[208:211], v[2:5]
	s_barrier
	s_add_i32 s56, 0, 0x18000
	s_add_i32 s57, 0, 0x1c000
	v_add_u32_e32 v160, s56, v145
	v_add_u32_e32 v176, s57, v145
	ds_read_b128 v[140:143], v160
	ds_read_b128 v[148:151], v160 offset:1024
	ds_read_b128 v[156:159], v160 offset:2048
	ds_read_b128 v[160:163], v160 offset:3072
	ds_read_b128 v[164:167], v176
	ds_read_b128 v[168:171], v176 offset:1024
	ds_read_b128 v[172:175], v176 offset:2048
	ds_read_b128 v[176:179], v176 offset:3072
	s_add_u32 s24, s24, 0x40000
	s_addc_u32 s25, s25, 0
	s_mov_b32 m0, s37
	v_lshl_add_u64 v[218:219], s[24:25], 0, v[130:131]
	ds_read_b128 v[180:183], v147 offset:32768
	ds_read_b128 v[184:187], v147 offset:33792
	ds_read_b128 v[188:191], v147 offset:34816
	ds_read_b128 v[192:195], v147 offset:35840
	ds_read_b128 v[196:199], v147 offset:36864
	ds_read_b128 v[200:203], v147 offset:37888
	ds_read_b128 v[204:207], v147 offset:38912
	ds_read_b128 v[208:211], v147 offset:39936
	global_load_lds_dwordx4 v[218:219], off
	v_lshl_add_u64 v[218:219], s[24:25], 0, v[132:133]
	s_mov_b32 m0, s38
	s_nop 0
	global_load_lds_dwordx4 v[218:219], off
	s_waitcnt vmcnt(8)
	s_waitcnt lgkmcnt(0)
	s_barrier
	s_waitcnt lgkmcnt(0)
	v_mfma_f32_16x16x32_bf16 v[126:129], v[140:143], v[180:183], v[126:129]
	v_mfma_f32_16x16x32_bf16 v[122:125], v[156:159], v[180:183], v[122:125]
	v_mfma_f32_16x16x32_bf16 v[110:113], v[140:143], v[188:191], v[110:113]
	v_mfma_f32_16x16x32_bf16 v[106:109], v[156:159], v[188:191], v[106:109]
	v_mfma_f32_16x16x32_bf16 v[94:97], v[140:143], v[196:199], v[94:97]
	v_mfma_f32_16x16x32_bf16 v[90:93], v[156:159], v[196:199], v[90:93]
	v_mfma_f32_16x16x32_bf16 v[78:81], v[140:143], v[204:207], v[78:81]
	v_mfma_f32_16x16x32_bf16 v[74:77], v[156:159], v[204:207], v[74:77]
	v_mfma_f32_16x16x32_bf16 v[126:129], v[148:151], v[184:187], v[126:129]
	v_mfma_f32_16x16x32_bf16 v[122:125], v[160:163], v[184:187], v[122:125]
	v_mfma_f32_16x16x32_bf16 v[110:113], v[148:151], v[192:195], v[110:113]
	v_mfma_f32_16x16x32_bf16 v[106:109], v[160:163], v[192:195], v[106:109]
	v_mfma_f32_16x16x32_bf16 v[94:97], v[148:151], v[200:203], v[94:97]
	v_mfma_f32_16x16x32_bf16 v[90:93], v[160:163], v[200:203], v[90:93]
	v_mfma_f32_16x16x32_bf16 v[78:81], v[148:151], v[208:211], v[78:81]
	v_mfma_f32_16x16x32_bf16 v[74:77], v[160:163], v[208:211], v[74:77]
	v_mfma_f32_16x16x32_bf16 v[118:121], v[164:167], v[180:183], v[118:121]
	v_mfma_f32_16x16x32_bf16 v[114:117], v[172:175], v[180:183], v[114:117]
	v_mfma_f32_16x16x32_bf16 v[102:105], v[164:167], v[188:191], v[102:105]
	v_mfma_f32_16x16x32_bf16 v[98:101], v[172:175], v[188:191], v[98:101]
	v_mfma_f32_16x16x32_bf16 v[86:89], v[164:167], v[196:199], v[86:89]
	v_mfma_f32_16x16x32_bf16 v[82:85], v[172:175], v[196:199], v[82:85]
	v_mfma_f32_16x16x32_bf16 v[70:73], v[164:167], v[204:207], v[70:73]
	v_mfma_f32_16x16x32_bf16 v[66:69], v[172:175], v[204:207], v[66:69]
	v_mfma_f32_16x16x32_bf16 v[118:121], v[168:171], v[184:187], v[118:121]
	v_mfma_f32_16x16x32_bf16 v[114:117], v[176:179], v[184:187], v[114:117]
	v_mfma_f32_16x16x32_bf16 v[102:105], v[168:171], v[192:195], v[102:105]
	v_mfma_f32_16x16x32_bf16 v[98:101], v[176:179], v[192:195], v[98:101]
	v_mfma_f32_16x16x32_bf16 v[86:89], v[168:171], v[200:203], v[86:89]
	v_mfma_f32_16x16x32_bf16 v[82:85], v[176:179], v[200:203], v[82:85]
	v_mfma_f32_16x16x32_bf16 v[70:73], v[168:171], v[208:211], v[70:73]
	v_mfma_f32_16x16x32_bf16 v[66:69], v[176:179], v[208:211], v[66:69]
	s_barrier
	s_add_i32 s24, s56, s35
	v_lshl_add_u64 v[152:153], v[152:153], 0, s[62:63]
	s_mov_b32 m0, s24
	ds_read_b128 v[180:183], v147 offset:49152
	ds_read_b128 v[184:187], v147 offset:50176
	ds_read_b128 v[188:191], v147 offset:51200
	ds_read_b128 v[192:195], v147 offset:52224
	ds_read_b128 v[196:199], v147 offset:53248
	ds_read_b128 v[200:203], v147 offset:54272
	ds_read_b128 v[204:207], v147 offset:55296
	ds_read_b128 v[208:211], v147 offset:56320
	global_load_lds_dwordx4 v[152:153], off
	s_add_i32 m0, s24, 0x2000
	s_add_u32 s22, s22, 0x40080
	v_lshl_add_u64 v[152:153], v[212:213], 0, s[62:63]
	s_addc_u32 s23, s23, 0
	s_add_i32 s24, s57, s35
	global_load_lds_dwordx4 v[152:153], off
	v_lshl_add_u64 v[152:153], s[22:23], 0, v[154:155]
	s_mov_b32 m0, s24
	s_nop 0
	global_load_lds_dwordx4 v[152:153], off
	v_lshl_add_u64 v[152:153], s[22:23], 0, v[134:135]
	s_add_i32 m0, s24, 0x2000
	s_nop 0
	global_load_lds_dwordx4 v[152:153], off
	v_lshl_add_u64 v[152:153], v[214:215], 0, s[62:63]
	s_mov_b32 m0, s39
	s_nop 0
	global_load_lds_dwordx4 v[152:153], off
	v_lshl_add_u64 v[152:153], v[216:217], 0, s[62:63]
	s_mov_b32 m0, s40
	s_nop 0
	global_load_lds_dwordx4 v[152:153], off
	s_waitcnt vmcnt(8)
	s_waitcnt lgkmcnt(0)
	s_barrier
	s_waitcnt lgkmcnt(0)
	v_mfma_f32_16x16x32_bf16 v[62:65], v[140:143], v[180:183], v[62:65]
	v_mfma_f32_16x16x32_bf16 v[58:61], v[156:159], v[180:183], v[58:61]
	v_mfma_f32_16x16x32_bf16 v[46:49], v[140:143], v[188:191], v[46:49]
	v_mfma_f32_16x16x32_bf16 v[42:45], v[156:159], v[188:191], v[42:45]
	v_mfma_f32_16x16x32_bf16 v[30:33], v[140:143], v[196:199], v[30:33]
	v_mfma_f32_16x16x32_bf16 v[26:29], v[156:159], v[196:199], v[26:29]
	v_mfma_f32_16x16x32_bf16 v[14:17], v[140:143], v[204:207], v[14:17]
	v_mfma_f32_16x16x32_bf16 v[10:13], v[156:159], v[204:207], v[10:13]
	v_mfma_f32_16x16x32_bf16 v[62:65], v[148:151], v[184:187], v[62:65]
	v_mfma_f32_16x16x32_bf16 v[58:61], v[160:163], v[184:187], v[58:61]
	v_mfma_f32_16x16x32_bf16 v[46:49], v[148:151], v[192:195], v[46:49]
	v_mfma_f32_16x16x32_bf16 v[42:45], v[160:163], v[192:195], v[42:45]
	v_mfma_f32_16x16x32_bf16 v[30:33], v[148:151], v[200:203], v[30:33]
	v_mfma_f32_16x16x32_bf16 v[26:29], v[160:163], v[200:203], v[26:29]
	v_mfma_f32_16x16x32_bf16 v[14:17], v[148:151], v[208:211], v[14:17]
	v_mfma_f32_16x16x32_bf16 v[10:13], v[160:163], v[208:211], v[10:13]
	v_mfma_f32_16x16x32_bf16 v[54:57], v[164:167], v[180:183], v[54:57]
	v_mfma_f32_16x16x32_bf16 v[50:53], v[172:175], v[180:183], v[50:53]
	v_mfma_f32_16x16x32_bf16 v[38:41], v[164:167], v[188:191], v[38:41]
	v_mfma_f32_16x16x32_bf16 v[34:37], v[172:175], v[188:191], v[34:37]
	v_mfma_f32_16x16x32_bf16 v[22:25], v[164:167], v[196:199], v[22:25]
	v_mfma_f32_16x16x32_bf16 v[18:21], v[172:175], v[196:199], v[18:21]
	v_mfma_f32_16x16x32_bf16 v[6:9], v[164:167], v[204:207], v[6:9]
	v_mfma_f32_16x16x32_bf16 v[2:5], v[172:175], v[204:207], v[2:5]
	v_mfma_f32_16x16x32_bf16 v[54:57], v[168:171], v[184:187], v[54:57]
	v_mfma_f32_16x16x32_bf16 v[50:53], v[176:179], v[184:187], v[50:53]
	v_mfma_f32_16x16x32_bf16 v[38:41], v[168:171], v[192:195], v[38:41]
	v_mfma_f32_16x16x32_bf16 v[34:37], v[176:179], v[192:195], v[34:37]
	v_mfma_f32_16x16x32_bf16 v[22:25], v[168:171], v[200:203], v[22:25]
	v_mfma_f32_16x16x32_bf16 v[18:21], v[176:179], v[200:203], v[18:21]
	v_mfma_f32_16x16x32_bf16 v[6:9], v[168:171], v[208:211], v[6:9]
	v_mfma_f32_16x16x32_bf16 v[2:5], v[176:179], v[208:211], v[2:5]
	s_barrier
	s_add_i32 s70, s70, 2
	s_add_u32 s20, s20, 0x100
	s_addc_u32 s21, s21, 0
	s_add_u32 s68, s68, 0x100
	s_addc_u32 s69, s69, 0
	s_cmp_gt_u32 s70, 13
	s_cbranch_scc0 .LBB0_445
	s_and_b64 vcc, exec, s[8:9]
	s_cbranch_vccz .LBB0_448
	s_barrier

.LBB0_534:
	s_add_u32 s24, s22, 0xfff00080
	s_addc_u32 s25, s23, -1
	s_add_i32 s56, 0, 0x10000
	s_cmp_eq_u32 s69, 60
	s_cselect_b32 s27, s13, s25
	s_cselect_b32 s26, s19, s24
	v_add_u32_e32 v152, s56, v159
	s_cselect_b32 s25, s11, s68
	s_cselect_b32 s24, s21, s40
	s_add_i32 s70, 0, 0x14000
	ds_read_b128 v[130:133], v152
	ds_read_b128 v[134:137], v152 offset:1024
	ds_read_b128 v[148:151], v152 offset:2048
	ds_read_b128 v[162:165], v152 offset:3072
	v_add_u32_e32 v152, s70, v159
	ds_read_b128 v[166:169], v152
	ds_read_b128 v[170:173], v152 offset:1024
	ds_read_b128 v[174:177], v152 offset:2048
	ds_read_b128 v[178:181], v152 offset:3072
	v_lshl_add_u64 v[152:153], s[22:23], 0, v[144:145]
	s_add_i32 m0, s38, 0xc000
	ds_read_b128 v[182:185], v161
	ds_read_b128 v[186:189], v161 offset:1024
	ds_read_b128 v[190:193], v161 offset:2048
	ds_read_b128 v[194:197], v161 offset:3072
	ds_read_b128 v[198:201], v161 offset:4096
	ds_read_b128 v[202:205], v161 offset:5120
	ds_read_b128 v[206:209], v161 offset:6144
	ds_read_b128 v[210:213], v161 offset:7168
	global_load_lds_dwordx4 v[152:153], off
	v_lshl_add_u64 v[152:153], s[22:23], 0, v[146:147]
	s_add_i32 m0, s38, 0xe000
	s_nop 0
	global_load_lds_dwordx4 v[152:153], off
	s_waitcnt vmcnt(8)
	s_waitcnt lgkmcnt(0)
	s_barrier
	s_waitcnt lgkmcnt(0)
	v_mfma_f32_16x16x32_bf16 v[126:129], v[130:133], v[182:185], v[126:129]
	v_mfma_f32_16x16x32_bf16 v[122:125], v[148:151], v[182:185], v[122:125]
	v_mfma_f32_16x16x32_bf16 v[110:113], v[130:133], v[190:193], v[110:113]
	v_mfma_f32_16x16x32_bf16 v[106:109], v[148:151], v[190:193], v[106:109]
	v_mfma_f32_16x16x32_bf16 v[94:97], v[130:133], v[198:201], v[94:97]
	v_mfma_f32_16x16x32_bf16 v[90:93], v[148:151], v[198:201], v[90:93]
	v_mfma_f32_16x16x32_bf16 v[78:81], v[130:133], v[206:209], v[78:81]
	v_mfma_f32_16x16x32_bf16 v[74:77], v[148:151], v[206:209], v[74:77]
	v_mfma_f32_16x16x32_bf16 v[126:129], v[134:137], v[186:189], v[126:129]
	v_mfma_f32_16x16x32_bf16 v[122:125], v[162:165], v[186:189], v[122:125]
	v_mfma_f32_16x16x32_bf16 v[110:113], v[134:137], v[194:197], v[110:113]
	v_mfma_f32_16x16x32_bf16 v[106:109], v[162:165], v[194:197], v[106:109]
	v_mfma_f32_16x16x32_bf16 v[94:97], v[134:137], v[202:205], v[94:97]
	v_mfma_f32_16x16x32_bf16 v[90:93], v[162:165], v[202:205], v[90:93]
	v_mfma_f32_16x16x32_bf16 v[78:81], v[134:137], v[210:213], v[78:81]
	v_mfma_f32_16x16x32_bf16 v[74:77], v[162:165], v[210:213], v[74:77]
	v_mfma_f32_16x16x32_bf16 v[118:121], v[166:169], v[182:185], v[118:121]
	v_mfma_f32_16x16x32_bf16 v[114:117], v[174:177], v[182:185], v[114:117]
	v_mfma_f32_16x16x32_bf16 v[102:105], v[166:169], v[190:193], v[102:105]
	v_mfma_f32_16x16x32_bf16 v[98:101], v[174:177], v[190:193], v[98:101]
	v_mfma_f32_16x16x32_bf16 v[86:89], v[166:169], v[198:201], v[86:89]
	v_mfma_f32_16x16x32_bf16 v[82:85], v[174:177], v[198:201], v[82:85]
	v_mfma_f32_16x16x32_bf16 v[70:73], v[166:169], v[206:209], v[70:73]
	v_mfma_f32_16x16x32_bf16 v[66:69], v[174:177], v[206:209], v[66:69]
	v_mfma_f32_16x16x32_bf16 v[118:121], v[170:173], v[186:189], v[118:121]
	v_mfma_f32_16x16x32_bf16 v[114:117], v[178:181], v[186:189], v[114:117]
	v_mfma_f32_16x16x32_bf16 v[102:105], v[170:173], v[194:197], v[102:105]
	v_mfma_f32_16x16x32_bf16 v[98:101], v[178:181], v[194:197], v[98:101]
	v_mfma_f32_16x16x32_bf16 v[86:89], v[170:173], v[202:205], v[86:89]
	v_mfma_f32_16x16x32_bf16 v[82:85], v[178:181], v[202:205], v[82:85]
	v_mfma_f32_16x16x32_bf16 v[70:73], v[170:173], v[210:213], v[70:73]
	v_mfma_f32_16x16x32_bf16 v[66:69], v[178:181], v[210:213], v[66:69]
	s_barrier
	s_add_i32 s56, s56, s37
	v_lshl_add_u64 v[152:153], s[24:25], 0, v[154:155]
	s_mov_b32 m0, s56
	ds_read_b128 v[182:185], v161 offset:16384
	ds_read_b128 v[186:189], v161 offset:17408
	ds_read_b128 v[190:193], v161 offset:18432
	ds_read_b128 v[194:197], v161 offset:19456
	ds_read_b128 v[198:201], v161 offset:20480
	ds_read_b128 v[202:205], v161 offset:21504
	ds_read_b128 v[206:209], v161 offset:22528
	ds_read_b128 v[210:213], v161 offset:23552
	global_load_lds_dwordx4 v[152:153], off
	s_add_i32 m0, s56, 0x2000
	s_add_u32 s56, s24, 0x100000
	v_lshl_add_u64 v[156:157], s[24:25], 0, v[142:143]
	s_addc_u32 s57, s25, 0
	s_add_i32 s70, s70, s37
	global_load_lds_dwordx4 v[156:157], off
	v_lshl_add_u64 v[214:215], s[56:57], 0, v[154:155]
	s_mov_b32 m0, s70
	v_lshl_add_u64 v[216:217], s[26:27], 0, v[140:141]
	global_load_lds_dwordx4 v[214:215], off
	v_lshl_add_u64 v[214:215], s[56:57], 0, v[142:143]
	s_add_i32 m0, s70, 0x2000
	s_nop 0
	global_load_lds_dwordx4 v[214:215], off
	v_lshl_add_u64 v[214:215], s[26:27], 0, v[138:139]
	s_mov_b32 m0, s38
	s_nop 0
	global_load_lds_dwordx4 v[214:215], off
	s_mov_b32 m0, s39
	s_nop 0
	global_load_lds_dwordx4 v[216:217], off
	s_waitcnt vmcnt(8)
	s_waitcnt lgkmcnt(0)
	s_barrier
	s_waitcnt lgkmcnt(0)
	v_mfma_f32_16x16x32_bf16 v[62:65], v[130:133], v[182:185], v[62:65]
	v_mfma_f32_16x16x32_bf16 v[58:61], v[148:151], v[182:185], v[58:61]
	v_mfma_f32_16x16x32_bf16 v[46:49], v[130:133], v[190:193], v[46:49]
	v_mfma_f32_16x16x32_bf16 v[42:45], v[148:151], v[190:193], v[42:45]
	v_mfma_f32_16x16x32_bf16 v[30:33], v[130:133], v[198:201], v[30:33]
	v_mfma_f32_16x16x32_bf16 v[26:29], v[148:151], v[198:201], v[26:29]
	v_mfma_f32_16x16x32_bf16 v[14:17], v[130:133], v[206:209], v[14:17]
	v_mfma_f32_16x16x32_bf16 v[10:13], v[148:151], v[206:209], v[10:13]
	v_mfma_f32_16x16x32_bf16 v[62:65], v[134:137], v[186:189], v[62:65]
	v_mfma_f32_16x16x32_bf16 v[58:61], v[162:165], v[186:189], v[58:61]
	v_mfma_f32_16x16x32_bf16 v[46:49], v[134:137], v[194:197], v[46:49]
	v_mfma_f32_16x16x32_bf16 v[42:45], v[162:165], v[194:197], v[42:45]
	v_mfma_f32_16x16x32_bf16 v[30:33], v[134:137], v[202:205], v[30:33]
	v_mfma_f32_16x16x32_bf16 v[26:29], v[162:165], v[202:205], v[26:29]
	v_mfma_f32_16x16x32_bf16 v[14:17], v[134:137], v[210:213], v[14:17]
	v_mfma_f32_16x16x32_bf16 v[10:13], v[162:165], v[210:213], v[10:13]
	v_mfma_f32_16x16x32_bf16 v[54:57], v[166:169], v[182:185], v[54:57]
	v_mfma_f32_16x16x32_bf16 v[50:53], v[174:177], v[182:185], v[50:53]
	v_mfma_f32_16x16x32_bf16 v[38:41], v[166:169], v[190:193], v[38:41]
	v_mfma_f32_16x16x32_bf16 v[34:37], v[174:177], v[190:193], v[34:37]
	v_mfma_f32_16x16x32_bf16 v[22:25], v[166:169], v[198:201], v[22:25]
	v_mfma_f32_16x16x32_bf16 v[18:21], v[174:177], v[198:201], v[18:21]
	v_mfma_f32_16x16x32_bf16 v[6:9], v[166:169], v[206:209], v[6:9]
	v_mfma_f32_16x16x32_bf16 v[2:5], v[174:177], v[206:209], v[2:5]
	v_mfma_f32_16x16x32_bf16 v[54:57], v[170:173], v[186:189], v[54:57]
	v_mfma_f32_16x16x32_bf16 v[50:53], v[178:181], v[186:189], v[50:53]
	v_mfma_f32_16x16x32_bf16 v[38:41], v[170:173], v[194:197], v[38:41]
	v_mfma_f32_16x16x32_bf16 v[34:37], v[178:181], v[194:197], v[34:37]
	v_mfma_f32_16x16x32_bf16 v[22:25], v[170:173], v[202:205], v[22:25]
	v_mfma_f32_16x16x32_bf16 v[18:21], v[178:181], v[202:205], v[18:21]
	v_mfma_f32_16x16x32_bf16 v[6:9], v[170:173], v[210:213], v[6:9]
	v_mfma_f32_16x16x32_bf16 v[2:5], v[178:181], v[210:213], v[2:5]
	s_barrier
	s_add_i32 s56, 0, 0x18000
	s_add_i32 s57, 0, 0x1c000
	v_add_u32_e32 v162, s56, v159
	v_add_u32_e32 v178, s57, v159
	ds_read_b128 v[130:133], v162
	ds_read_b128 v[134:137], v162 offset:1024
	ds_read_b128 v[148:151], v162 offset:2048
	ds_read_b128 v[162:165], v162 offset:3072
	ds_read_b128 v[166:169], v178
	ds_read_b128 v[170:173], v178 offset:1024
	ds_read_b128 v[174:177], v178 offset:2048
	ds_read_b128 v[178:181], v178 offset:3072
	s_add_u32 s26, s26, 0x100000
	s_addc_u32 s27, s27, 0
	s_mov_b32 m0, s44
	v_lshl_add_u64 v[218:219], s[26:27], 0, v[138:139]
	ds_read_b128 v[182:185], v161 offset:32768
	ds_read_b128 v[186:189], v161 offset:33792
	ds_read_b128 v[190:193], v161 offset:34816
	ds_read_b128 v[194:197], v161 offset:35840
	ds_read_b128 v[198:201], v161 offset:36864
	ds_read_b128 v[202:205], v161 offset:37888
	ds_read_b128 v[206:209], v161 offset:38912
	ds_read_b128 v[210:213], v161 offset:39936
	global_load_lds_dwordx4 v[218:219], off
	v_lshl_add_u64 v[218:219], s[26:27], 0, v[140:141]
	s_mov_b32 m0, s45
	s_nop 0
	global_load_lds_dwordx4 v[218:219], off
	s_waitcnt vmcnt(8)
	s_waitcnt lgkmcnt(0)
	s_barrier
	s_waitcnt lgkmcnt(0)
	v_mfma_f32_16x16x32_bf16 v[126:129], v[130:133], v[182:185], v[126:129]
	v_mfma_f32_16x16x32_bf16 v[122:125], v[148:151], v[182:185], v[122:125]
	v_mfma_f32_16x16x32_bf16 v[110:113], v[130:133], v[190:193], v[110:113]
	v_mfma_f32_16x16x32_bf16 v[106:109], v[148:151], v[190:193], v[106:109]
	v_mfma_f32_16x16x32_bf16 v[94:97], v[130:133], v[198:201], v[94:97]
	v_mfma_f32_16x16x32_bf16 v[90:93], v[148:151], v[198:201], v[90:93]
	v_mfma_f32_16x16x32_bf16 v[78:81], v[130:133], v[206:209], v[78:81]
	v_mfma_f32_16x16x32_bf16 v[74:77], v[148:151], v[206:209], v[74:77]
	v_mfma_f32_16x16x32_bf16 v[126:129], v[134:137], v[186:189], v[126:129]
	v_mfma_f32_16x16x32_bf16 v[122:125], v[162:165], v[186:189], v[122:125]
	v_mfma_f32_16x16x32_bf16 v[110:113], v[134:137], v[194:197], v[110:113]
	v_mfma_f32_16x16x32_bf16 v[106:109], v[162:165], v[194:197], v[106:109]
	v_mfma_f32_16x16x32_bf16 v[94:97], v[134:137], v[202:205], v[94:97]
	v_mfma_f32_16x16x32_bf16 v[90:93], v[162:165], v[202:205], v[90:93]
	v_mfma_f32_16x16x32_bf16 v[78:81], v[134:137], v[210:213], v[78:81]
	v_mfma_f32_16x16x32_bf16 v[74:77], v[162:165], v[210:213], v[74:77]
	v_mfma_f32_16x16x32_bf16 v[118:121], v[166:169], v[182:185], v[118:121]
	v_mfma_f32_16x16x32_bf16 v[114:117], v[174:177], v[182:185], v[114:117]
	v_mfma_f32_16x16x32_bf16 v[102:105], v[166:169], v[190:193], v[102:105]
	v_mfma_f32_16x16x32_bf16 v[98:101], v[174:177], v[190:193], v[98:101]
	v_mfma_f32_16x16x32_bf16 v[86:89], v[166:169], v[198:201], v[86:89]
	v_mfma_f32_16x16x32_bf16 v[82:85], v[174:177], v[198:201], v[82:85]
	v_mfma_f32_16x16x32_bf16 v[70:73], v[166:169], v[206:209], v[70:73]
	v_mfma_f32_16x16x32_bf16 v[66:69], v[174:177], v[206:209], v[66:69]
	v_mfma_f32_16x16x32_bf16 v[118:121], v[170:173], v[186:189], v[118:121]
	v_mfma_f32_16x16x32_bf16 v[114:117], v[178:181], v[186:189], v[114:117]
	v_mfma_f32_16x16x32_bf16 v[102:105], v[170:173], v[194:197], v[102:105]
	v_mfma_f32_16x16x32_bf16 v[98:101], v[178:181], v[194:197], v[98:101]
	v_mfma_f32_16x16x32_bf16 v[86:89], v[170:173], v[202:205], v[86:89]
	v_mfma_f32_16x16x32_bf16 v[82:85], v[178:181], v[202:205], v[82:85]
	v_mfma_f32_16x16x32_bf16 v[70:73], v[170:173], v[210:213], v[70:73]
	v_mfma_f32_16x16x32_bf16 v[66:69], v[178:181], v[210:213], v[66:69]
	s_barrier
	s_add_i32 s26, s56, s37
	v_lshl_add_u64 v[152:153], v[152:153], 0, s[62:63]
	s_mov_b32 m0, s26
	ds_read_b128 v[182:185], v161 offset:49152
	ds_read_b128 v[186:189], v161 offset:50176
	ds_read_b128 v[190:193], v161 offset:51200
	ds_read_b128 v[194:197], v161 offset:52224
	ds_read_b128 v[198:201], v161 offset:53248
	ds_read_b128 v[202:205], v161 offset:54272
	ds_read_b128 v[206:209], v161 offset:55296
	ds_read_b128 v[210:213], v161 offset:56320
	global_load_lds_dwordx4 v[152:153], off
	s_add_i32 m0, s26, 0x2000
	s_add_u32 s24, s24, 0x100080
	v_lshl_add_u64 v[152:153], v[156:157], 0, s[62:63]
	s_addc_u32 s25, s25, 0
	s_add_i32 s26, s57, s37
	global_load_lds_dwordx4 v[152:153], off
	v_lshl_add_u64 v[152:153], s[24:25], 0, v[154:155]
	s_mov_b32 m0, s26
	s_nop 0
	global_load_lds_dwordx4 v[152:153], off
	v_lshl_add_u64 v[152:153], s[24:25], 0, v[142:143]
	s_add_i32 m0, s26, 0x2000
	s_nop 0
	global_load_lds_dwordx4 v[152:153], off
	v_lshl_add_u64 v[152:153], v[214:215], 0, s[62:63]
	s_mov_b32 m0, s53
	s_nop 0
	global_load_lds_dwordx4 v[152:153], off
	v_lshl_add_u64 v[152:153], v[216:217], 0, s[62:63]
	s_mov_b32 m0, s55
	s_nop 0
	global_load_lds_dwordx4 v[152:153], off
	s_waitcnt vmcnt(8)
	s_waitcnt lgkmcnt(0)
	s_barrier
	s_waitcnt lgkmcnt(0)
	v_mfma_f32_16x16x32_bf16 v[62:65], v[130:133], v[182:185], v[62:65]
	v_mfma_f32_16x16x32_bf16 v[58:61], v[148:151], v[182:185], v[58:61]
	v_mfma_f32_16x16x32_bf16 v[46:49], v[130:133], v[190:193], v[46:49]
	v_mfma_f32_16x16x32_bf16 v[42:45], v[148:151], v[190:193], v[42:45]
	v_mfma_f32_16x16x32_bf16 v[30:33], v[130:133], v[198:201], v[30:33]
	v_mfma_f32_16x16x32_bf16 v[26:29], v[148:151], v[198:201], v[26:29]
	v_mfma_f32_16x16x32_bf16 v[14:17], v[130:133], v[206:209], v[14:17]
	v_mfma_f32_16x16x32_bf16 v[10:13], v[148:151], v[206:209], v[10:13]
	v_mfma_f32_16x16x32_bf16 v[62:65], v[134:137], v[186:189], v[62:65]
	v_mfma_f32_16x16x32_bf16 v[58:61], v[162:165], v[186:189], v[58:61]
	v_mfma_f32_16x16x32_bf16 v[46:49], v[134:137], v[194:197], v[46:49]
	v_mfma_f32_16x16x32_bf16 v[42:45], v[162:165], v[194:197], v[42:45]
	v_mfma_f32_16x16x32_bf16 v[30:33], v[134:137], v[202:205], v[30:33]
	v_mfma_f32_16x16x32_bf16 v[26:29], v[162:165], v[202:205], v[26:29]
	v_mfma_f32_16x16x32_bf16 v[14:17], v[134:137], v[210:213], v[14:17]
	v_mfma_f32_16x16x32_bf16 v[10:13], v[162:165], v[210:213], v[10:13]
	v_mfma_f32_16x16x32_bf16 v[54:57], v[166:169], v[182:185], v[54:57]
	v_mfma_f32_16x16x32_bf16 v[50:53], v[174:177], v[182:185], v[50:53]
	v_mfma_f32_16x16x32_bf16 v[38:41], v[166:169], v[190:193], v[38:41]
	v_mfma_f32_16x16x32_bf16 v[34:37], v[174:177], v[190:193], v[34:37]
	v_mfma_f32_16x16x32_bf16 v[22:25], v[166:169], v[198:201], v[22:25]
	v_mfma_f32_16x16x32_bf16 v[18:21], v[174:177], v[198:201], v[18:21]
	v_mfma_f32_16x16x32_bf16 v[6:9], v[166:169], v[206:209], v[6:9]
	v_mfma_f32_16x16x32_bf16 v[2:5], v[174:177], v[206:209], v[2:5]
	v_mfma_f32_16x16x32_bf16 v[54:57], v[170:173], v[186:189], v[54:57]
	v_mfma_f32_16x16x32_bf16 v[50:53], v[178:181], v[186:189], v[50:53]
	v_mfma_f32_16x16x32_bf16 v[38:41], v[170:173], v[194:197], v[38:41]
	v_mfma_f32_16x16x32_bf16 v[34:37], v[178:181], v[194:197], v[34:37]
	v_mfma_f32_16x16x32_bf16 v[22:25], v[170:173], v[202:205], v[22:25]
	v_mfma_f32_16x16x32_bf16 v[18:21], v[178:181], v[202:205], v[18:21]
	v_mfma_f32_16x16x32_bf16 v[6:9], v[170:173], v[210:213], v[6:9]
	v_mfma_f32_16x16x32_bf16 v[2:5], v[178:181], v[210:213], v[2:5]
	s_barrier
	s_add_i32 s69, s69, 2
	s_add_u32 s22, s22, 0x100
	s_addc_u32 s23, s23, 0
	s_add_u32 s40, s40, 0x100
	s_addc_u32 s68, s68, 0
	s_cmp_gt_u32 s69, 61
	s_cbranch_scc0 .LBB0_534
	v_lshl_add_u32 v148, s20, 8, v158
	v_lshl_or_b32 v150, s18, 8, v160
	v_ashrrev_i32_e32 v149, 31, v148
	v_lshlrev_b64 v[130:131], 11, v[148:149]
	v_ashrrev_i32_e32 v151, 31, v150
	v_lshl_add_u64 v[130:131], s[8:9], 0, v[130:131]
	v_lshlrev_b64 v[132:133], 1, v[150:151]
	v_lshl_add_u64 v[172:173], v[130:131], 0, v[132:133]
	global_load_dwordx4 v[164:167], v[172:173], off
	global_load_dwordx4 v[168:171], v[172:173], off offset:256
	v_or_b32_e32 v152, 16, v148
	v_ashrrev_i32_e32 v153, 31, v152
	v_lshlrev_b64 v[130:131], 11, v[152:153]
	v_lshl_add_u64 v[130:131], s[8:9], 0, v[130:131]
	v_lshl_add_u64 v[156:157], v[130:131], 0, v[132:133]
	global_load_dwordx4 v[134:137], v[156:157], off
	global_load_dwordx4 v[130:133], v[156:157], off offset:256
	v_and_b32_e32 v163, 64, v1
	v_xor_b32_e32 v162, 16, v1
	v_add_u32_e32 v163, 64, v163
	v_xor_b32_e32 v174, 32, v1
	v_cmp_lt_i32_e32 vcc, v162, v163
	s_lshl_b32 s18, s18, 2
	s_ashr_i32 s19, s18, 31
	v_cndmask_b32_e32 v162, v1, v162, vcc
	v_cmp_lt_i32_e32 vcc, v174, v163
	v_lshlrev_b32_e32 v162, 2, v162
	s_waitcnt vmcnt(0)
	v_and_b32_e32 v175, 0xffff0000, v164
	v_cndmask_b32_e32 v163, v1, v174, vcc
	v_lshlrev_b32_e32 v174, 16, v164
	v_lshlrev_b32_e32 v164, 16, v165
	v_and_b32_e32 v165, 0xffff0000, v165
	v_lshlrev_b32_e32 v176, 16, v166
	v_and_b32_e32 v177, 0xffff0000, v166
	v_lshlrev_b32_e32 v166, 16, v167
	v_and_b32_e32 v167, 0xffff0000, v167
	v_lshlrev_b32_e32 v178, 16, v168
	v_and_b32_e32 v179, 0xffff0000, v168
	v_lshlrev_b32_e32 v168, 16, v169
	v_and_b32_e32 v169, 0xffff0000, v169
	v_lshlrev_b32_e32 v180, 16, v170
	v_and_b32_e32 v181, 0xffff0000, v170
	v_lshlrev_b32_e32 v170, 16, v171
	v_and_b32_e32 v171, 0xffff0000, v171
	v_pk_add_f32 v[128:129], v[128:129], v[164:165]
	v_pk_add_f32 v[126:127], v[126:127], v[174:175]
	v_pk_add_f32 v[122:123], v[122:123], v[176:177]
	v_pk_add_f32 v[124:125], v[124:125], v[166:167]
	v_pk_add_f32 v[120:121], v[120:121], v[168:169]
	v_pk_add_f32 v[118:119], v[118:119], v[178:179]
	v_pk_add_f32 v[164:165], v[114:115], v[180:181]
	v_pk_add_f32 v[166:167], v[116:117], v[170:171]
	v_cvt_pk_bf16_f32 v114, v126, v127
	v_cvt_pk_bf16_f32 v115, v128, v129
	v_mul_f32_e32 v116, v126, v126
	v_mul_f32_e32 v117, v128, v128
	v_mul_f32_e32 v126, v122, v122
	v_mul_f32_e32 v128, v125, v125
	v_mul_f32_e32 v168, v118, v118
	v_mul_f32_e32 v169, v120, v120
	v_mul_f32_e32 v170, v164, v164
	v_mul_f32_e32 v171, v167, v167
	v_fmac_f32_e32 v116, v127, v127
	v_fmac_f32_e32 v117, v129, v129
	v_fmac_f32_e32 v126, v123, v123
	v_fmac_f32_e32 v128, v124, v124
	v_fmac_f32_e32 v168, v119, v119
	v_fmac_f32_e32 v169, v121, v121
	v_fmac_f32_e32 v170, v165, v165
	v_fmac_f32_e32 v171, v166, v166
	v_add_f32_e32 v116, v117, v116
	v_add_f32_e32 v117, v128, v126
	v_add_f32_e32 v126, v169, v168
	v_add_f32_e32 v127, v171, v170
	v_add_f32_e32 v116, v117, v116
	v_add_f32_e32 v117, v127, v126
	v_add_f32_e32 v126, v116, v117
	ds_bpermute_b32 v127, v162, v126
	v_cvt_pk_bf16_f32 v116, v122, v123
	v_cvt_pk_bf16_f32 v117, v124, v125
	global_store_dwordx4 v[172:173], v[114:117], off
	s_waitcnt lgkmcnt(0)
	s_nop 0
	v_add_f32_e32 v114, v126, v127
	v_lshlrev_b32_e32 v126, 2, v163
	ds_bpermute_b32 v115, v126, v114
	v_cvt_pk_bf16_f32 v116, v118, v119
	v_cvt_pk_bf16_f32 v117, v120, v121
	v_cvt_pk_bf16_f32 v118, v164, v165
	v_cvt_pk_bf16_f32 v119, v166, v167
	global_store_dwordx4 v[172:173], v[116:119], off offset:256
	s_and_saveexec_b64 s[20:21], s[0:1]
	s_cbranch_execz .LBB0_537
	v_lshlrev_b64 v[116:117], 7, v[148:149]
	v_lshl_add_u64 v[116:117], s[6:7], 0, v[116:117]
	v_lshl_add_u64 v[116:117], s[18:19], 2, v[116:117]
	s_lshl_b32 s40, s51, 2
	v_lshl_add_u64 v[116:117], v[116:117], 0, s[40:41]
	s_waitcnt lgkmcnt(0)
	v_add_f32_e32 v114, v114, v115
	global_store_dword v[116:117], v114, off

.LBB0_559:
	s_and_b32 s4, s10, 0x60
	s_or_b32 s11, s4, s7
	v_readfirstlane_b32 s12, v4
	v_readfirstlane_b32 s13, v5
	v_readfirstlane_b32 s14, v2
	v_readfirstlane_b32 s15, v3
	s_and_b32 s16, s9, -16
	v_and_b32_e32 v233, 63, v0
	v_lshrrev_b32_e32 v232, 2, v233
	v_and_b32_e32 v226, 3, v233
	v_lshlrev_b32_e32 v226, 4, v226
	v_add_u32_e32 v228, s16, v232
	v_lshl_add_u32 v228, v228, 13, v226
	v_add_u32_e32 v233, s11, v232
	v_lshl_add_u32 v226, v233, 13, v226
	v_and_b32_e32 v233, 63, v0
	v_and_b32_e32 v232, 15, v233
	v_lshrrev_b32_e32 v233, 4, v233
	v_lshl_add_u32 v232, v232, 2, v233
	v_lshlrev_b32_e32 v232, 2, v232
	global_load_dwordx4 v[16:19], v226, s[12:13]
	global_load_dwordx4 v[20:23], v228, s[14:15]
	global_load_dwordx4 v[24:27], v226, s[12:13] offset:64
	global_load_dwordx4 v[28:31], v228, s[14:15] offset:64
	global_load_dwordx4 v[32:35], v226, s[12:13] offset:128
	global_load_dwordx4 v[36:39], v228, s[14:15] offset:128
	global_load_dwordx4 v[40:43], v226, s[12:13] offset:192
	global_load_dwordx4 v[44:47], v228, s[14:15] offset:192
	global_load_dwordx4 v[48:51], v226, s[12:13] offset:256
	global_load_dwordx4 v[52:55], v228, s[14:15] offset:256
	global_load_dwordx4 v[56:59], v226, s[12:13] offset:320
	global_load_dwordx4 v[60:63], v228, s[14:15] offset:320
	global_load_dwordx4 v[64:67], v226, s[12:13] offset:384
	global_load_dwordx4 v[68:71], v228, s[14:15] offset:384
	global_load_dwordx4 v[72:75], v226, s[12:13] offset:448
	global_load_dwordx4 v[76:79], v228, s[14:15] offset:448
	global_load_dwordx4 v[80:83], v226, s[12:13] offset:512
	global_load_dwordx4 v[84:87], v228, s[14:15] offset:512
	global_load_dwordx4 v[88:91], v226, s[12:13] offset:576
	global_load_dwordx4 v[92:95], v228, s[14:15] offset:576
	global_load_dwordx4 v[96:99], v226, s[12:13] offset:640
	global_load_dwordx4 v[100:103], v228, s[14:15] offset:640
	global_load_dwordx4 v[104:107], v226, s[12:13] offset:704
	global_load_dwordx4 v[108:111], v228, s[14:15] offset:704
	global_load_dwordx4 v[112:115], v226, s[12:13] offset:768
	global_load_dwordx4 v[116:119], v228, s[14:15] offset:768
	global_load_dwordx4 v[120:123], v226, s[12:13] offset:832
	global_load_dwordx4 v[124:127], v228, s[14:15] offset:832
	global_load_dwordx4 v[128:131], v226, s[12:13] offset:896
	global_load_dwordx4 v[132:135], v228, s[14:15] offset:896
	global_load_dwordx4 v[136:139], v226, s[12:13] offset:960
	global_load_dwordx4 v[140:143], v228, s[14:15] offset:960
	global_load_dwordx4 v[144:147], v226, s[12:13] offset:1024
	global_load_dwordx4 v[148:151], v228, s[14:15] offset:1024
	global_load_dwordx4 v[156:159], v226, s[12:13] offset:1088
	global_load_dwordx4 v[160:163], v228, s[14:15] offset:1088
	global_load_dwordx4 v[164:167], v226, s[12:13] offset:1152
	global_load_dwordx4 v[168:171], v228, s[14:15] offset:1152
	global_load_dwordx4 v[172:175], v226, s[12:13] offset:1216
	global_load_dwordx4 v[176:179], v228, s[14:15] offset:1216
	s_waitcnt vmcnt(38)
	ds_bpermute_b32 v196, v232, v16
	ds_bpermute_b32 v197, v232, v17
	ds_bpermute_b32 v198, v232, v18
	ds_bpermute_b32 v199, v232, v19
	ds_bpermute_b32 v200, v232, v20
	ds_bpermute_b32 v201, v232, v21
	ds_bpermute_b32 v202, v232, v22
	ds_bpermute_b32 v203, v232, v23
	global_load_dwordx4 v[16:19], v226, s[12:13] offset:1280
	global_load_dwordx4 v[20:23], v228, s[14:15] offset:1280
	s_waitcnt vmcnt(38)
	ds_bpermute_b32 v204, v232, v24
	ds_bpermute_b32 v205, v232, v25
	ds_bpermute_b32 v206, v232, v26
	ds_bpermute_b32 v207, v232, v27
	s_waitcnt lgkmcnt(4)
	v_mfma_f32_16x16x32_bf16 v[12:15], v[196:199], v[200:203], 0
	ds_bpermute_b32 v208, v232, v28
	ds_bpermute_b32 v209, v232, v29
	ds_bpermute_b32 v210, v232, v30
	ds_bpermute_b32 v211, v232, v31
	global_load_dwordx4 v[24:27], v226, s[12:13] offset:1344
	global_load_dwordx4 v[28:31], v228, s[14:15] offset:1344
	s_waitcnt vmcnt(38)
	ds_bpermute_b32 v212, v232, v32
	ds_bpermute_b32 v213, v232, v33
	ds_bpermute_b32 v214, v232, v34
	ds_bpermute_b32 v215, v232, v35
	s_waitcnt lgkmcnt(4)
	v_mfma_f32_16x16x32_bf16 v[12:15], v[204:207], v[208:211], v[12:15]
	ds_bpermute_b32 v216, v232, v36
	ds_bpermute_b32 v217, v232, v37
	ds_bpermute_b32 v218, v232, v38
	ds_bpermute_b32 v219, v232, v39
	global_load_dwordx4 v[32:35], v226, s[12:13] offset:1408
	global_load_dwordx4 v[36:39], v228, s[14:15] offset:1408
	s_waitcnt vmcnt(38)
	ds_bpermute_b32 v196, v232, v40
	ds_bpermute_b32 v197, v232, v41
	ds_bpermute_b32 v198, v232, v42
	ds_bpermute_b32 v199, v232, v43
	s_waitcnt lgkmcnt(4)
	v_mfma_f32_16x16x32_bf16 v[12:15], v[212:215], v[216:219], v[12:15]
	ds_bpermute_b32 v200, v232, v44
	ds_bpermute_b32 v201, v232, v45
	ds_bpermute_b32 v202, v232, v46
	ds_bpermute_b32 v203, v232, v47
	global_load_dwordx4 v[40:43], v226, s[12:13] offset:1472
	global_load_dwordx4 v[44:47], v228, s[14:15] offset:1472
	s_waitcnt vmcnt(38)
	ds_bpermute_b32 v204, v232, v48
	ds_bpermute_b32 v205, v232, v49
	ds_bpermute_b32 v206, v232, v50
	ds_bpermute_b32 v207, v232, v51
	s_waitcnt lgkmcnt(4)
	v_mfma_f32_16x16x32_bf16 v[12:15], v[196:199], v[200:203], v[12:15]
	ds_bpermute_b32 v208, v232, v52
	ds_bpermute_b32 v209, v232, v53
	ds_bpermute_b32 v210, v232, v54
	ds_bpermute_b32 v211, v232, v55
	global_load_dwordx4 v[48:51], v226, s[12:13] offset:1536
	global_load_dwordx4 v[52:55], v228, s[14:15] offset:1536
	s_waitcnt vmcnt(38)
	ds_bpermute_b32 v212, v232, v56
	ds_bpermute_b32 v213, v232, v57
	ds_bpermute_b32 v214, v232, v58
	ds_bpermute_b32 v215, v232, v59
	s_waitcnt lgkmcnt(4)
	v_mfma_f32_16x16x32_bf16 v[12:15], v[204:207], v[208:211], v[12:15]
	ds_bpermute_b32 v216, v232, v60
	ds_bpermute_b32 v217, v232, v61
	ds_bpermute_b32 v218, v232, v62
	ds_bpermute_b32 v219, v232, v63
	global_load_dwordx4 v[56:59], v226, s[12:13] offset:1600
	global_load_dwordx4 v[60:63], v228, s[14:15] offset:1600
	s_waitcnt vmcnt(38)
	ds_bpermute_b32 v196, v232, v64
	ds_bpermute_b32 v197, v232, v65
	ds_bpermute_b32 v198, v232, v66
	ds_bpermute_b32 v199, v232, v67
	s_waitcnt lgkmcnt(4)
	v_mfma_f32_16x16x32_bf16 v[12:15], v[212:215], v[216:219], v[12:15]
	ds_bpermute_b32 v200, v232, v68
	ds_bpermute_b32 v201, v232, v69
	ds_bpermute_b32 v202, v232, v70
	ds_bpermute_b32 v203, v232, v71
	global_load_dwordx4 v[64:67], v226, s[12:13] offset:1664
	global_load_dwordx4 v[68:71], v228, s[14:15] offset:1664
	s_waitcnt vmcnt(38)
	ds_bpermute_b32 v204, v232, v72
	ds_bpermute_b32 v205, v232, v73
	ds_bpermute_b32 v206, v232, v74
	ds_bpermute_b32 v207, v232, v75
	s_waitcnt lgkmcnt(4)
	v_mfma_f32_16x16x32_bf16 v[12:15], v[196:199], v[200:203], v[12:15]
	ds_bpermute_b32 v208, v232, v76
	ds_bpermute_b32 v209, v232, v77
	ds_bpermute_b32 v210, v232, v78
	ds_bpermute_b32 v211, v232, v79
	global_load_dwordx4 v[72:75], v226, s[12:13] offset:1728
	global_load_dwordx4 v[76:79], v228, s[14:15] offset:1728
	s_waitcnt vmcnt(38)
	ds_bpermute_b32 v212, v232, v80
	ds_bpermute_b32 v213, v232, v81
	ds_bpermute_b32 v214, v232, v82
	ds_bpermute_b32 v215, v232, v83
	s_waitcnt lgkmcnt(4)
	v_mfma_f32_16x16x32_bf16 v[12:15], v[204:207], v[208:211], v[12:15]
	ds_bpermute_b32 v216, v232, v84
	ds_bpermute_b32 v217, v232, v85
	ds_bpermute_b32 v218, v232, v86
	ds_bpermute_b32 v219, v232, v87
	global_load_dwordx4 v[80:83], v226, s[12:13] offset:1792
	global_load_dwordx4 v[84:87], v228, s[14:15] offset:1792
	s_waitcnt vmcnt(38)
	ds_bpermute_b32 v196, v232, v88
	ds_bpermute_b32 v197, v232, v89
	ds_bpermute_b32 v198, v232, v90
	ds_bpermute_b32 v199, v232, v91
	s_waitcnt lgkmcnt(4)
	v_mfma_f32_16x16x32_bf16 v[12:15], v[212:215], v[216:219], v[12:15]
	ds_bpermute_b32 v200, v232, v92
	ds_bpermute_b32 v201, v232, v93
	ds_bpermute_b32 v202, v232, v94
	ds_bpermute_b32 v203, v232, v95
	global_load_dwordx4 v[88:91], v226, s[12:13] offset:1856
	global_load_dwordx4 v[92:95], v228, s[14:15] offset:1856
	s_waitcnt vmcnt(38)
	ds_bpermute_b32 v204, v232, v96
	ds_bpermute_b32 v205, v232, v97
	ds_bpermute_b32 v206, v232, v98
	ds_bpermute_b32 v207, v232, v99
	s_waitcnt lgkmcnt(4)
	v_mfma_f32_16x16x32_bf16 v[12:15], v[196:199], v[200:203], v[12:15]
	ds_bpermute_b32 v208, v232, v100
	ds_bpermute_b32 v209, v232, v101
	ds_bpermute_b32 v210, v232, v102
	ds_bpermute_b32 v211, v232, v103
	global_load_dwordx4 v[96:99], v226, s[12:13] offset:1920
	global_load_dwordx4 v[100:103], v228, s[14:15] offset:1920
	s_waitcnt vmcnt(38)
	ds_bpermute_b32 v212, v232, v104
	ds_bpermute_b32 v213, v232, v105
	ds_bpermute_b32 v214, v232, v106
	ds_bpermute_b32 v215, v232, v107
	s_waitcnt lgkmcnt(4)
	v_mfma_f32_16x16x32_bf16 v[12:15], v[204:207], v[208:211], v[12:15]
	ds_bpermute_b32 v216, v232, v108
	ds_bpermute_b32 v217, v232, v109
	ds_bpermute_b32 v218, v232, v110
	ds_bpermute_b32 v219, v232, v111
	global_load_dwordx4 v[104:107], v226, s[12:13] offset:1984
	global_load_dwordx4 v[108:111], v228, s[14:15] offset:1984
	s_waitcnt vmcnt(38)
	ds_bpermute_b32 v196, v232, v112
	ds_bpermute_b32 v197, v232, v113
	ds_bpermute_b32 v198, v232, v114
	ds_bpermute_b32 v199, v232, v115
	s_waitcnt lgkmcnt(4)
	v_mfma_f32_16x16x32_bf16 v[12:15], v[212:215], v[216:219], v[12:15]
	ds_bpermute_b32 v200, v232, v116
	ds_bpermute_b32 v201, v232, v117
	ds_bpermute_b32 v202, v232, v118
	ds_bpermute_b32 v203, v232, v119
	s_waitcnt vmcnt(36)
	ds_bpermute_b32 v204, v232, v120
	ds_bpermute_b32 v205, v232, v121
	ds_bpermute_b32 v206, v232, v122
	ds_bpermute_b32 v207, v232, v123
	s_waitcnt lgkmcnt(4)
	v_mfma_f32_16x16x32_bf16 v[12:15], v[196:199], v[200:203], v[12:15]
	ds_bpermute_b32 v208, v232, v124
	ds_bpermute_b32 v209, v232, v125
	ds_bpermute_b32 v210, v232, v126
	ds_bpermute_b32 v211, v232, v127
	s_waitcnt vmcnt(34)
	ds_bpermute_b32 v212, v232, v128
	ds_bpermute_b32 v213, v232, v129
	ds_bpermute_b32 v214, v232, v130
	ds_bpermute_b32 v215, v232, v131
	s_waitcnt lgkmcnt(4)
	v_mfma_f32_16x16x32_bf16 v[12:15], v[204:207], v[208:211], v[12:15]
	ds_bpermute_b32 v216, v232, v132
	ds_bpermute_b32 v217, v232, v133
	ds_bpermute_b32 v218, v232, v134
	ds_bpermute_b32 v219, v232, v135
	s_waitcnt vmcnt(32)
	ds_bpermute_b32 v196, v232, v136
	ds_bpermute_b32 v197, v232, v137
	ds_bpermute_b32 v198, v232, v138
	ds_bpermute_b32 v199, v232, v139
	s_waitcnt lgkmcnt(4)
	v_mfma_f32_16x16x32_bf16 v[12:15], v[212:215], v[216:219], v[12:15]
	ds_bpermute_b32 v200, v232, v140
	ds_bpermute_b32 v201, v232, v141
	ds_bpermute_b32 v202, v232, v142
	ds_bpermute_b32 v203, v232, v143
	s_waitcnt vmcnt(30)
	ds_bpermute_b32 v204, v232, v144
	ds_bpermute_b32 v205, v232, v145
	ds_bpermute_b32 v206, v232, v146
	ds_bpermute_b32 v207, v232, v147
	s_waitcnt lgkmcnt(4)
	v_mfma_f32_16x16x32_bf16 v[12:15], v[196:199], v[200:203], v[12:15]
	ds_bpermute_b32 v208, v232, v148
	ds_bpermute_b32 v209, v232, v149
	ds_bpermute_b32 v210, v232, v150
	ds_bpermute_b32 v211, v232, v151
	s_waitcnt vmcnt(28)
	ds_bpermute_b32 v212, v232, v156
	ds_bpermute_b32 v213, v232, v157
	ds_bpermute_b32 v214, v232, v158
	ds_bpermute_b32 v215, v232, v159
	s_waitcnt lgkmcnt(4)
	v_mfma_f32_16x16x32_bf16 v[12:15], v[204:207], v[208:211], v[12:15]
	ds_bpermute_b32 v216, v232, v160
	ds_bpermute_b32 v217, v232, v161
	ds_bpermute_b32 v218, v232, v162
	ds_bpermute_b32 v219, v232, v163
	s_waitcnt vmcnt(26)
	ds_bpermute_b32 v196, v232, v164
	ds_bpermute_b32 v197, v232, v165
	ds_bpermute_b32 v198, v232, v166
	ds_bpermute_b32 v199, v232, v167
	s_waitcnt lgkmcnt(4)
	v_mfma_f32_16x16x32_bf16 v[12:15], v[212:215], v[216:219], v[12:15]
	ds_bpermute_b32 v200, v232, v168
	ds_bpermute_b32 v201, v232, v169
	ds_bpermute_b32 v202, v232, v170
	ds_bpermute_b32 v203, v232, v171
	s_waitcnt vmcnt(24)
	ds_bpermute_b32 v204, v232, v172
	ds_bpermute_b32 v205, v232, v173
	ds_bpermute_b32 v206, v232, v174
	ds_bpermute_b32 v207, v232, v175
	s_waitcnt lgkmcnt(4)
	v_mfma_f32_16x16x32_bf16 v[12:15], v[196:199], v[200:203], v[12:15]
	ds_bpermute_b32 v208, v232, v176
	ds_bpermute_b32 v209, v232, v177
	ds_bpermute_b32 v210, v232, v178
	ds_bpermute_b32 v211, v232, v179
	s_waitcnt vmcnt(22)
	ds_bpermute_b32 v212, v232, v16
	ds_bpermute_b32 v213, v232, v17
	ds_bpermute_b32 v214, v232, v18
	ds_bpermute_b32 v215, v232, v19
	s_waitcnt lgkmcnt(4)
	v_mfma_f32_16x16x32_bf16 v[12:15], v[204:207], v[208:211], v[12:15]
	ds_bpermute_b32 v216, v232, v20
	ds_bpermute_b32 v217, v232, v21
	ds_bpermute_b32 v218, v232, v22
	ds_bpermute_b32 v219, v232, v23
	s_waitcnt vmcnt(20)
	ds_bpermute_b32 v196, v232, v24
	ds_bpermute_b32 v197, v232, v25
	ds_bpermute_b32 v198, v232, v26
	ds_bpermute_b32 v199, v232, v27
	s_waitcnt lgkmcnt(4)
	v_mfma_f32_16x16x32_bf16 v[12:15], v[212:215], v[216:219], v[12:15]
	ds_bpermute_b32 v200, v232, v28
	ds_bpermute_b32 v201, v232, v29
	ds_bpermute_b32 v202, v232, v30
	ds_bpermute_b32 v203, v232, v31
	s_waitcnt vmcnt(18)
	ds_bpermute_b32 v204, v232, v32
	ds_bpermute_b32 v205, v232, v33
	ds_bpermute_b32 v206, v232, v34
	ds_bpermute_b32 v207, v232, v35
	s_waitcnt lgkmcnt(4)
	v_mfma_f32_16x16x32_bf16 v[12:15], v[196:199], v[200:203], v[12:15]
	ds_bpermute_b32 v208, v232, v36
	ds_bpermute_b32 v209, v232, v37
	ds_bpermute_b32 v210, v232, v38
	ds_bpermute_b32 v211, v232, v39
	s_waitcnt vmcnt(16)
	ds_bpermute_b32 v212, v232, v40
	ds_bpermute_b32 v213, v232, v41
	ds_bpermute_b32 v214, v232, v42
	ds_bpermute_b32 v215, v232, v43
	s_waitcnt lgkmcnt(4)
	v_mfma_f32_16x16x32_bf16 v[12:15], v[204:207], v[208:211], v[12:15]
	ds_bpermute_b32 v216, v232, v44
	ds_bpermute_b32 v217, v232, v45
	ds_bpermute_b32 v218, v232, v46
	ds_bpermute_b32 v219, v232, v47
	s_waitcnt vmcnt(14)
	ds_bpermute_b32 v196, v232, v48
	ds_bpermute_b32 v197, v232, v49
	ds_bpermute_b32 v198, v232, v50
	ds_bpermute_b32 v199, v232, v51
	s_waitcnt lgkmcnt(4)
	v_mfma_f32_16x16x32_bf16 v[12:15], v[212:215], v[216:219], v[12:15]
	ds_bpermute_b32 v200, v232, v52
	ds_bpermute_b32 v201, v232, v53
	ds_bpermute_b32 v202, v232, v54
	ds_bpermute_b32 v203, v232, v55
	s_waitcnt vmcnt(12)
	ds_bpermute_b32 v204, v232, v56
	ds_bpermute_b32 v205, v232, v57
	ds_bpermute_b32 v206, v232, v58
	ds_bpermute_b32 v207, v232, v59
	s_waitcnt lgkmcnt(4)
	v_mfma_f32_16x16x32_bf16 v[12:15], v[196:199], v[200:203], v[12:15]
	ds_bpermute_b32 v208, v232, v60
	ds_bpermute_b32 v209, v232, v61
	ds_bpermute_b32 v210, v232, v62
	ds_bpermute_b32 v211, v232, v63
	s_waitcnt vmcnt(10)
	ds_bpermute_b32 v212, v232, v64
	ds_bpermute_b32 v213, v232, v65
	ds_bpermute_b32 v214, v232, v66
	ds_bpermute_b32 v215, v232, v67
	s_waitcnt lgkmcnt(4)
	v_mfma_f32_16x16x32_bf16 v[12:15], v[204:207], v[208:211], v[12:15]
	ds_bpermute_b32 v216, v232, v68
	ds_bpermute_b32 v217, v232, v69
	ds_bpermute_b32 v218, v232, v70
	ds_bpermute_b32 v219, v232, v71
	s_waitcnt vmcnt(8)
	ds_bpermute_b32 v196, v232, v72
	ds_bpermute_b32 v197, v232, v73
	ds_bpermute_b32 v198, v232, v74
	ds_bpermute_b32 v199, v232, v75
	s_waitcnt lgkmcnt(4)
	v_mfma_f32_16x16x32_bf16 v[12:15], v[212:215], v[216:219], v[12:15]
	ds_bpermute_b32 v200, v232, v76
	ds_bpermute_b32 v201, v232, v77
	ds_bpermute_b32 v202, v232, v78
	ds_bpermute_b32 v203, v232, v79
	s_waitcnt vmcnt(6)
	ds_bpermute_b32 v204, v232, v80
	ds_bpermute_b32 v205, v232, v81
	ds_bpermute_b32 v206, v232, v82
	ds_bpermute_b32 v207, v232, v83
	s_waitcnt lgkmcnt(4)
	v_mfma_f32_16x16x32_bf16 v[12:15], v[196:199], v[200:203], v[12:15]
	ds_bpermute_b32 v208, v232, v84
	ds_bpermute_b32 v209, v232, v85
	ds_bpermute_b32 v210, v232, v86
	ds_bpermute_b32 v211, v232, v87
	s_waitcnt vmcnt(4)
	ds_bpermute_b32 v212, v232, v88
	ds_bpermute_b32 v213, v232, v89
	ds_bpermute_b32 v214, v232, v90
	ds_bpermute_b32 v215, v232, v91
	s_waitcnt lgkmcnt(4)
	v_mfma_f32_16x16x32_bf16 v[12:15], v[204:207], v[208:211], v[12:15]
	ds_bpermute_b32 v216, v232, v92
	ds_bpermute_b32 v217, v232, v93
	ds_bpermute_b32 v218, v232, v94
	ds_bpermute_b32 v219, v232, v95
	s_waitcnt vmcnt(2)
	ds_bpermute_b32 v196, v232, v96
	ds_bpermute_b32 v197, v232, v97
	ds_bpermute_b32 v198, v232, v98
	ds_bpermute_b32 v199, v232, v99
	s_waitcnt lgkmcnt(4)
	v_mfma_f32_16x16x32_bf16 v[12:15], v[212:215], v[216:219], v[12:15]
	ds_bpermute_b32 v200, v232, v100
	ds_bpermute_b32 v201, v232, v101
	ds_bpermute_b32 v202, v232, v102
	ds_bpermute_b32 v203, v232, v103
	s_waitcnt vmcnt(0)
	ds_bpermute_b32 v204, v232, v104
	ds_bpermute_b32 v205, v232, v105
	ds_bpermute_b32 v206, v232, v106
	ds_bpermute_b32 v207, v232, v107
	s_waitcnt lgkmcnt(4)
	v_mfma_f32_16x16x32_bf16 v[12:15], v[196:199], v[200:203], v[12:15]
	ds_bpermute_b32 v208, v232, v108
	ds_bpermute_b32 v209, v232, v109
	ds_bpermute_b32 v210, v232, v110
	ds_bpermute_b32 v211, v232, v111
	s_waitcnt lgkmcnt(0)
	v_mfma_f32_16x16x32_bf16 v[12:15], v[204:207], v[208:211], v[12:15]
	s_and_b32 s4, s9, -16
	s_andn2_b64 vcc, exec, s[0:1]
	v_add_u32_e32 v36, s8, v8
	s_barrier
	s_nop 7
	ds_write_b128 v11, v[12:15]
	ds_write_b32 v36, v155 offset:32768
	s_waitcnt lgkmcnt(0)
	s_barrier
	s_cbranch_vccnz .LBB0_558
	s_ashr_i32 s5, s4, 31
	v_lshl_add_u64 v[12:13], s[4:5], 2, v[6:7]
	v_lshl_or_b32 v154, s11, 12, v10
	v_lshl_add_u64 v[28:29], v[12:13], 0, v[154:155]
	v_add_co_u32_e32 v30, vcc, s96, v28
	s_nop 1
	v_addc_co_u32_e32 v31, vcc, 0, v29, vcc
	v_add_co_u32_e32 v32, vcc, 0x3000, v28
	global_load_dword v34, v[28:29], off
	global_load_dword v35, v[30:31], off offset:-4096
	global_load_dword v36, v[30:31], off
	v_addc_co_u32_e32 v33, vcc, 0, v29, vcc
	global_load_dword v37, v[32:33], off
	ds_read_b128 v[12:15], v11
	ds_read_b128 v[16:19], v11 offset:2048
	ds_read_b128 v[20:23], v11 offset:4096
	ds_read_b128 v[24:27], v11 offset:6144
	s_waitcnt lgkmcnt(2)
	v_add_f32_e32 v12, v12, v16
	v_add_f32_e32 v13, v13, v17
	s_waitcnt lgkmcnt(0)
	v_add_f32_e32 v16, v20, v24
	v_add_f32_e32 v17, v21, v25
	v_add_f32_e32 v12, v12, v16
	v_add_f32_e32 v14, v14, v18
	v_add_f32_e32 v18, v22, v26
	v_add_f32_e32 v15, v15, v19
	v_add_f32_e32 v19, v23, v27
	v_add_f32_e32 v13, v13, v17
	v_add_f32_e32 v14, v14, v18
	v_add_f32_e32 v15, v15, v19
	s_waitcnt vmcnt(3)
	v_add_f32_e32 v12, v34, v12
	global_store_dword v[28:29], v12, off
	s_waitcnt vmcnt(3)
	v_add_f32_e32 v12, v13, v35
	s_waitcnt vmcnt(2)
	v_add_f32_e32 v13, v14, v36
	global_store_dword v[30:31], v12, off offset:-4096
	global_store_dword v[30:31], v13, off
	s_waitcnt vmcnt(3)
	v_add_f32_e32 v12, v15, v37
	global_store_dword v[32:33], v12, off
	s_branch .LBB0_558

.LBB0_631:
	s_add_u32 s28, s26, 0xfffc0080
	s_addc_u32 s29, s27, -1
	s_add_i32 s62, 0, 0x10000
	s_cmp_eq_u32 s61, 12
	s_cselect_b32 s31, s3, s29
	s_cselect_b32 s30, s19, s28
	s_cselect_b32 s29, s17, s60
	s_cselect_b32 s28, s58, s59
	s_add_i32 s64, 0, 0x14000
	v_add_u32_e32 v142, s62, v246
	v_add_u32_e32 v158, s64, v246
	ds_read_b128 v[130:133], v142
	ds_read_b128 v[134:137], v142 offset:1024
	ds_read_b128 v[138:141], v142 offset:2048
	ds_read_b128 v[142:145], v142 offset:3072
	ds_read_b128 v[146:149], v158
	ds_read_b128 v[150:153], v158 offset:1024
	ds_read_b128 v[154:157], v158 offset:2048
	ds_read_b128 v[158:161], v158 offset:3072
	v_lshl_add_u64 v[192:193], s[26:27], 0, v[184:185]
	s_add_i32 m0, s25, 0xc000
	ds_read_b128 v[162:165], v247
	ds_read_b128 v[188:191], v247 offset:1024
	ds_read_b128 v[202:205], v247 offset:2048
	ds_read_b128 v[206:209], v247 offset:3072
	ds_read_b128 v[210:213], v247 offset:4096
	ds_read_b128 v[214:217], v247 offset:5120
	ds_read_b128 v[218:221], v247 offset:6144
	ds_read_b128 v[222:225], v247 offset:7168
	global_load_lds_dwordx4 v[192:193], off
	v_lshl_add_u64 v[192:193], s[26:27], 0, v[186:187]
	s_add_i32 m0, s25, 0xe000
	s_nop 0
	global_load_lds_dwordx4 v[192:193], off
	s_waitcnt vmcnt(8)
	s_waitcnt lgkmcnt(0)
	s_barrier
	s_waitcnt lgkmcnt(0)
	v_mfma_f32_16x16x32_bf16 v[126:129], v[130:133], v[162:165], v[126:129]
	v_mfma_f32_16x16x32_bf16 v[122:125], v[138:141], v[162:165], v[122:125]
	v_mfma_f32_16x16x32_bf16 v[110:113], v[130:133], v[202:205], v[110:113]
	v_mfma_f32_16x16x32_bf16 v[106:109], v[138:141], v[202:205], v[106:109]
	v_mfma_f32_16x16x32_bf16 v[94:97], v[130:133], v[210:213], v[94:97]
	v_mfma_f32_16x16x32_bf16 v[90:93], v[138:141], v[210:213], v[90:93]
	v_mfma_f32_16x16x32_bf16 v[78:81], v[130:133], v[218:221], v[78:81]
	v_mfma_f32_16x16x32_bf16 v[74:77], v[138:141], v[218:221], v[74:77]
	v_mfma_f32_16x16x32_bf16 v[126:129], v[134:137], v[188:191], v[126:129]
	v_mfma_f32_16x16x32_bf16 v[122:125], v[142:145], v[188:191], v[122:125]
	v_mfma_f32_16x16x32_bf16 v[110:113], v[134:137], v[206:209], v[110:113]
	v_mfma_f32_16x16x32_bf16 v[106:109], v[142:145], v[206:209], v[106:109]
	v_mfma_f32_16x16x32_bf16 v[94:97], v[134:137], v[214:217], v[94:97]
	v_mfma_f32_16x16x32_bf16 v[90:93], v[142:145], v[214:217], v[90:93]
	v_mfma_f32_16x16x32_bf16 v[78:81], v[134:137], v[222:225], v[78:81]
	v_mfma_f32_16x16x32_bf16 v[74:77], v[142:145], v[222:225], v[74:77]
	v_mfma_f32_16x16x32_bf16 v[118:121], v[146:149], v[162:165], v[118:121]
	v_mfma_f32_16x16x32_bf16 v[114:117], v[154:157], v[162:165], v[114:117]
	v_mfma_f32_16x16x32_bf16 v[102:105], v[146:149], v[202:205], v[102:105]
	v_mfma_f32_16x16x32_bf16 v[98:101], v[154:157], v[202:205], v[98:101]
	v_mfma_f32_16x16x32_bf16 v[86:89], v[146:149], v[210:213], v[86:89]
	v_mfma_f32_16x16x32_bf16 v[82:85], v[154:157], v[210:213], v[82:85]
	v_mfma_f32_16x16x32_bf16 v[70:73], v[146:149], v[218:221], v[70:73]
	v_mfma_f32_16x16x32_bf16 v[66:69], v[154:157], v[218:221], v[66:69]
	v_mfma_f32_16x16x32_bf16 v[118:121], v[150:153], v[188:191], v[118:121]
	v_mfma_f32_16x16x32_bf16 v[114:117], v[158:161], v[188:191], v[114:117]
	v_mfma_f32_16x16x32_bf16 v[102:105], v[150:153], v[206:209], v[102:105]
	v_mfma_f32_16x16x32_bf16 v[98:101], v[158:161], v[206:209], v[98:101]
	v_mfma_f32_16x16x32_bf16 v[86:89], v[150:153], v[214:217], v[86:89]
	v_mfma_f32_16x16x32_bf16 v[82:85], v[158:161], v[214:217], v[82:85]
	v_mfma_f32_16x16x32_bf16 v[70:73], v[150:153], v[222:225], v[70:73]
	v_mfma_f32_16x16x32_bf16 v[66:69], v[158:161], v[222:225], v[66:69]
	s_barrier
	s_add_i32 s62, s62, s45
	v_lshl_add_u64 v[192:193], s[28:29], 0, v[168:169]
	s_mov_b32 m0, s62
	ds_read_b128 v[162:165], v247 offset:16384
	ds_read_b128 v[188:191], v247 offset:17408
	ds_read_b128 v[202:205], v247 offset:18432
	ds_read_b128 v[206:209], v247 offset:19456
	ds_read_b128 v[210:213], v247 offset:20480
	ds_read_b128 v[214:217], v247 offset:21504
	ds_read_b128 v[218:221], v247 offset:22528
	ds_read_b128 v[222:225], v247 offset:23552
	global_load_lds_dwordx4 v[192:193], off
	s_add_i32 m0, s62, 0x2000
	s_add_u32 s62, s28, 0x40000
	v_lshl_add_u64 v[226:227], s[28:29], 0, v[172:173]
	s_addc_u32 s63, s29, 0
	s_add_i32 s64, s64, s45
	global_load_lds_dwordx4 v[226:227], off
	v_lshl_add_u64 v[228:229], s[62:63], 0, v[168:169]
	s_mov_b32 m0, s64
	v_lshl_add_u64 v[248:249], s[30:31], 0, v[170:171]
	global_load_lds_dwordx4 v[228:229], off
	v_lshl_add_u64 v[228:229], s[62:63], 0, v[172:173]
	s_add_i32 m0, s64, 0x2000
	s_nop 0
	global_load_lds_dwordx4 v[228:229], off
	v_lshl_add_u64 v[228:229], s[30:31], 0, v[166:167]
	s_mov_b32 m0, s25
	s_nop 0
	global_load_lds_dwordx4 v[228:229], off
	s_mov_b32 m0, s46
	s_nop 0
	global_load_lds_dwordx4 v[248:249], off
	s_waitcnt vmcnt(8)
	s_waitcnt lgkmcnt(0)
	s_barrier
	s_waitcnt lgkmcnt(0)
	v_mfma_f32_16x16x32_bf16 v[62:65], v[130:133], v[162:165], v[62:65]
	v_mfma_f32_16x16x32_bf16 v[58:61], v[138:141], v[162:165], v[58:61]
	v_mfma_f32_16x16x32_bf16 v[46:49], v[130:133], v[202:205], v[46:49]
	v_mfma_f32_16x16x32_bf16 v[42:45], v[138:141], v[202:205], v[42:45]
	v_mfma_f32_16x16x32_bf16 v[30:33], v[130:133], v[210:213], v[30:33]
	v_mfma_f32_16x16x32_bf16 v[26:29], v[138:141], v[210:213], v[26:29]
	v_mfma_f32_16x16x32_bf16 v[14:17], v[130:133], v[218:221], v[14:17]
	v_mfma_f32_16x16x32_bf16 v[10:13], v[138:141], v[218:221], v[10:13]
	v_mfma_f32_16x16x32_bf16 v[62:65], v[134:137], v[188:191], v[62:65]
	v_mfma_f32_16x16x32_bf16 v[58:61], v[142:145], v[188:191], v[58:61]
	v_mfma_f32_16x16x32_bf16 v[46:49], v[134:137], v[206:209], v[46:49]
	v_mfma_f32_16x16x32_bf16 v[42:45], v[142:145], v[206:209], v[42:45]
	v_mfma_f32_16x16x32_bf16 v[30:33], v[134:137], v[214:217], v[30:33]
	v_mfma_f32_16x16x32_bf16 v[26:29], v[142:145], v[214:217], v[26:29]
	v_mfma_f32_16x16x32_bf16 v[14:17], v[134:137], v[222:225], v[14:17]
	v_mfma_f32_16x16x32_bf16 v[10:13], v[142:145], v[222:225], v[10:13]
	v_mfma_f32_16x16x32_bf16 v[54:57], v[146:149], v[162:165], v[54:57]
	v_mfma_f32_16x16x32_bf16 v[50:53], v[154:157], v[162:165], v[50:53]
	v_mfma_f32_16x16x32_bf16 v[38:41], v[146:149], v[202:205], v[38:41]
	v_mfma_f32_16x16x32_bf16 v[34:37], v[154:157], v[202:205], v[34:37]
	v_mfma_f32_16x16x32_bf16 v[22:25], v[146:149], v[210:213], v[22:25]
	v_mfma_f32_16x16x32_bf16 v[18:21], v[154:157], v[210:213], v[18:21]
	v_mfma_f32_16x16x32_bf16 v[6:9], v[146:149], v[218:221], v[6:9]
	v_mfma_f32_16x16x32_bf16 v[2:5], v[154:157], v[218:221], v[2:5]
	v_mfma_f32_16x16x32_bf16 v[54:57], v[150:153], v[188:191], v[54:57]
	v_mfma_f32_16x16x32_bf16 v[50:53], v[158:161], v[188:191], v[50:53]
	v_mfma_f32_16x16x32_bf16 v[38:41], v[150:153], v[206:209], v[38:41]
	v_mfma_f32_16x16x32_bf16 v[34:37], v[158:161], v[206:209], v[34:37]
	v_mfma_f32_16x16x32_bf16 v[22:25], v[150:153], v[214:217], v[22:25]
	v_mfma_f32_16x16x32_bf16 v[18:21], v[158:161], v[214:217], v[18:21]
	v_mfma_f32_16x16x32_bf16 v[6:9], v[150:153], v[222:225], v[6:9]
	v_mfma_f32_16x16x32_bf16 v[2:5], v[158:161], v[222:225], v[2:5]
	s_barrier
	s_add_i32 s62, 0, 0x18000
	s_add_i32 s63, 0, 0x1c000
	v_add_u32_e32 v142, s62, v246
	v_add_u32_e32 v158, s63, v246
	ds_read_b128 v[130:133], v142
	ds_read_b128 v[134:137], v142 offset:1024
	ds_read_b128 v[138:141], v142 offset:2048
	ds_read_b128 v[142:145], v142 offset:3072
	ds_read_b128 v[146:149], v158
	ds_read_b128 v[150:153], v158 offset:1024
	ds_read_b128 v[154:157], v158 offset:2048
	ds_read_b128 v[158:161], v158 offset:3072
	s_add_u32 s30, s30, 0x40000
	s_addc_u32 s31, s31, 0
	s_mov_b32 m0, s47
	v_lshl_add_u64 v[250:251], s[30:31], 0, v[166:167]
	ds_read_b128 v[162:165], v247 offset:32768
	ds_read_b128 v[188:191], v247 offset:33792
	ds_read_b128 v[202:205], v247 offset:34816
	ds_read_b128 v[206:209], v247 offset:35840
	ds_read_b128 v[210:213], v247 offset:36864
	ds_read_b128 v[214:217], v247 offset:37888
	ds_read_b128 v[218:221], v247 offset:38912
	ds_read_b128 v[222:225], v247 offset:39936
	global_load_lds_dwordx4 v[250:251], off
	v_lshl_add_u64 v[250:251], s[30:31], 0, v[170:171]
	s_mov_b32 m0, s48
	s_nop 0
	global_load_lds_dwordx4 v[250:251], off
	s_waitcnt vmcnt(8)
	s_waitcnt lgkmcnt(0)
	s_barrier
	s_waitcnt lgkmcnt(0)
	v_mfma_f32_16x16x32_bf16 v[126:129], v[130:133], v[162:165], v[126:129]
	v_mfma_f32_16x16x32_bf16 v[122:125], v[138:141], v[162:165], v[122:125]
	v_mfma_f32_16x16x32_bf16 v[110:113], v[130:133], v[202:205], v[110:113]
	v_mfma_f32_16x16x32_bf16 v[106:109], v[138:141], v[202:205], v[106:109]
	v_mfma_f32_16x16x32_bf16 v[94:97], v[130:133], v[210:213], v[94:97]
	v_mfma_f32_16x16x32_bf16 v[90:93], v[138:141], v[210:213], v[90:93]
	v_mfma_f32_16x16x32_bf16 v[78:81], v[130:133], v[218:221], v[78:81]
	v_mfma_f32_16x16x32_bf16 v[74:77], v[138:141], v[218:221], v[74:77]
	v_mfma_f32_16x16x32_bf16 v[126:129], v[134:137], v[188:191], v[126:129]
	v_mfma_f32_16x16x32_bf16 v[122:125], v[142:145], v[188:191], v[122:125]
	v_mfma_f32_16x16x32_bf16 v[110:113], v[134:137], v[206:209], v[110:113]
	v_mfma_f32_16x16x32_bf16 v[106:109], v[142:145], v[206:209], v[106:109]
	v_mfma_f32_16x16x32_bf16 v[94:97], v[134:137], v[214:217], v[94:97]
	v_mfma_f32_16x16x32_bf16 v[90:93], v[142:145], v[214:217], v[90:93]
	v_mfma_f32_16x16x32_bf16 v[78:81], v[134:137], v[222:225], v[78:81]
	v_mfma_f32_16x16x32_bf16 v[74:77], v[142:145], v[222:225], v[74:77]
	v_mfma_f32_16x16x32_bf16 v[118:121], v[146:149], v[162:165], v[118:121]
	v_mfma_f32_16x16x32_bf16 v[114:117], v[154:157], v[162:165], v[114:117]
	v_mfma_f32_16x16x32_bf16 v[102:105], v[146:149], v[202:205], v[102:105]
	v_mfma_f32_16x16x32_bf16 v[98:101], v[154:157], v[202:205], v[98:101]
	v_mfma_f32_16x16x32_bf16 v[86:89], v[146:149], v[210:213], v[86:89]
	v_mfma_f32_16x16x32_bf16 v[82:85], v[154:157], v[210:213], v[82:85]
	v_mfma_f32_16x16x32_bf16 v[70:73], v[146:149], v[218:221], v[70:73]
	v_mfma_f32_16x16x32_bf16 v[66:69], v[154:157], v[218:221], v[66:69]
	v_mfma_f32_16x16x32_bf16 v[118:121], v[150:153], v[188:191], v[118:121]
	v_mfma_f32_16x16x32_bf16 v[114:117], v[158:161], v[188:191], v[114:117]
	v_mfma_f32_16x16x32_bf16 v[102:105], v[150:153], v[206:209], v[102:105]
	v_mfma_f32_16x16x32_bf16 v[98:101], v[158:161], v[206:209], v[98:101]
	v_mfma_f32_16x16x32_bf16 v[86:89], v[150:153], v[214:217], v[86:89]
	v_mfma_f32_16x16x32_bf16 v[82:85], v[158:161], v[214:217], v[82:85]
	v_mfma_f32_16x16x32_bf16 v[70:73], v[150:153], v[222:225], v[70:73]
	v_mfma_f32_16x16x32_bf16 v[66:69], v[158:161], v[222:225], v[66:69]
	s_barrier
	s_add_i32 s30, s62, s45
	v_lshl_add_u64 v[192:193], v[192:193], 0, s[92:93]
	s_mov_b32 m0, s30
	ds_read_b128 v[162:165], v247 offset:49152
	ds_read_b128 v[188:191], v247 offset:50176
	ds_read_b128 v[202:205], v247 offset:51200
	ds_read_b128 v[206:209], v247 offset:52224
	ds_read_b128 v[210:213], v247 offset:53248
	ds_read_b128 v[214:217], v247 offset:54272
	ds_read_b128 v[218:221], v247 offset:55296
	ds_read_b128 v[222:225], v247 offset:56320
	global_load_lds_dwordx4 v[192:193], off
	s_add_i32 m0, s30, 0x2000
	s_add_u32 s28, s28, 0x40080
	v_lshl_add_u64 v[192:193], v[226:227], 0, s[92:93]
	s_addc_u32 s29, s29, 0
	s_add_i32 s30, s63, s45
	global_load_lds_dwordx4 v[192:193], off
	v_lshl_add_u64 v[192:193], s[28:29], 0, v[168:169]
	s_mov_b32 m0, s30
	s_nop 0
	global_load_lds_dwordx4 v[192:193], off
	v_lshl_add_u64 v[192:193], s[28:29], 0, v[172:173]
	s_add_i32 m0, s30, 0x2000
	s_nop 0
	global_load_lds_dwordx4 v[192:193], off
	v_lshl_add_u64 v[192:193], v[228:229], 0, s[92:93]
	s_mov_b32 m0, s52
	s_nop 0
	global_load_lds_dwordx4 v[192:193], off
	v_lshl_add_u64 v[192:193], v[248:249], 0, s[92:93]
	s_mov_b32 m0, s53
	s_nop 0
	global_load_lds_dwordx4 v[192:193], off
	s_waitcnt vmcnt(8)
	s_waitcnt lgkmcnt(0)
	s_barrier
	s_waitcnt lgkmcnt(0)
	v_mfma_f32_16x16x32_bf16 v[62:65], v[130:133], v[162:165], v[62:65]
	v_mfma_f32_16x16x32_bf16 v[58:61], v[138:141], v[162:165], v[58:61]
	v_mfma_f32_16x16x32_bf16 v[46:49], v[130:133], v[202:205], v[46:49]
	v_mfma_f32_16x16x32_bf16 v[42:45], v[138:141], v[202:205], v[42:45]
	v_mfma_f32_16x16x32_bf16 v[30:33], v[130:133], v[210:213], v[30:33]
	v_mfma_f32_16x16x32_bf16 v[26:29], v[138:141], v[210:213], v[26:29]
	v_mfma_f32_16x16x32_bf16 v[14:17], v[130:133], v[218:221], v[14:17]
	v_mfma_f32_16x16x32_bf16 v[10:13], v[138:141], v[218:221], v[10:13]
	v_mfma_f32_16x16x32_bf16 v[62:65], v[134:137], v[188:191], v[62:65]
	v_mfma_f32_16x16x32_bf16 v[58:61], v[142:145], v[188:191], v[58:61]
	v_mfma_f32_16x16x32_bf16 v[46:49], v[134:137], v[206:209], v[46:49]
	v_mfma_f32_16x16x32_bf16 v[42:45], v[142:145], v[206:209], v[42:45]
	v_mfma_f32_16x16x32_bf16 v[30:33], v[134:137], v[214:217], v[30:33]
	v_mfma_f32_16x16x32_bf16 v[26:29], v[142:145], v[214:217], v[26:29]
	v_mfma_f32_16x16x32_bf16 v[14:17], v[134:137], v[222:225], v[14:17]
	v_mfma_f32_16x16x32_bf16 v[10:13], v[142:145], v[222:225], v[10:13]
	v_mfma_f32_16x16x32_bf16 v[54:57], v[146:149], v[162:165], v[54:57]
	v_mfma_f32_16x16x32_bf16 v[50:53], v[154:157], v[162:165], v[50:53]
	v_mfma_f32_16x16x32_bf16 v[38:41], v[146:149], v[202:205], v[38:41]
	v_mfma_f32_16x16x32_bf16 v[34:37], v[154:157], v[202:205], v[34:37]
	v_mfma_f32_16x16x32_bf16 v[22:25], v[146:149], v[210:213], v[22:25]
	v_mfma_f32_16x16x32_bf16 v[18:21], v[154:157], v[210:213], v[18:21]
	v_mfma_f32_16x16x32_bf16 v[6:9], v[146:149], v[218:221], v[6:9]
	v_mfma_f32_16x16x32_bf16 v[2:5], v[154:157], v[218:221], v[2:5]
	v_mfma_f32_16x16x32_bf16 v[54:57], v[150:153], v[188:191], v[54:57]
	v_mfma_f32_16x16x32_bf16 v[50:53], v[158:161], v[188:191], v[50:53]
	v_mfma_f32_16x16x32_bf16 v[38:41], v[150:153], v[206:209], v[38:41]
	v_mfma_f32_16x16x32_bf16 v[34:37], v[158:161], v[206:209], v[34:37]
	v_mfma_f32_16x16x32_bf16 v[22:25], v[150:153], v[214:217], v[22:25]
	v_mfma_f32_16x16x32_bf16 v[18:21], v[158:161], v[214:217], v[18:21]
	v_mfma_f32_16x16x32_bf16 v[6:9], v[150:153], v[222:225], v[6:9]
	v_mfma_f32_16x16x32_bf16 v[2:5], v[158:161], v[222:225], v[2:5]
	s_barrier
	s_add_i32 s61, s61, 2
	s_add_u32 s26, s26, 0x100
	s_addc_u32 s27, s27, 0
	s_add_u32 s59, s59, 0x100
	s_addc_u32 s60, s60, 0
	s_cmp_gt_u32 s61, 13
	s_cbranch_scc0 .LBB0_631
	s_and_b64 vcc, exec, s[14:15]
	s_cbranch_vccnz .LBB0_636
	s_cmp_gt_i32 s2, 4
	s_mov_b64 s[26:27], -1
	s_cbranch_scc0 .LBB0_637

.LBB0_939:
	s_add_u32 s24, s22, 0xfffc0080
	s_addc_u32 s25, s23, -1
	s_add_i32 s52, 0, 0x10000
	s_cmp_eq_u32 s51, 12
	s_cselect_b32 s27, s13, s25
	s_cselect_b32 s26, s19, s24
	s_cselect_b32 s25, s11, s50
	s_cselect_b32 s24, s21, s49
	s_add_i32 s54, 0, 0x14000
	v_add_u32_e32 v142, s52, v167
	v_add_u32_e32 v164, s54, v167
	ds_read_b128 v[130:133], v142
	ds_read_b128 v[134:137], v142 offset:1024
	ds_read_b128 v[138:141], v142 offset:2048
	ds_read_b128 v[142:145], v142 offset:3072
	ds_read_b128 v[156:159], v164
	ds_read_b128 v[160:163], v164 offset:1024
	ds_read_b128 v[170:173], v164 offset:2048
	ds_read_b128 v[174:177], v164 offset:3072
	v_lshl_add_u64 v[164:165], s[22:23], 0, v[152:153]
	s_add_i32 m0, s38, 0xc000
	ds_read_b128 v[178:181], v169
	ds_read_b128 v[182:185], v169 offset:1024
	ds_read_b128 v[186:189], v169 offset:2048
	ds_read_b128 v[190:193], v169 offset:3072
	ds_read_b128 v[202:205], v169 offset:4096
	ds_read_b128 v[206:209], v169 offset:5120
	ds_read_b128 v[210:213], v169 offset:6144
	ds_read_b128 v[214:217], v169 offset:7168
	global_load_lds_dwordx4 v[164:165], off
	v_lshl_add_u64 v[164:165], s[22:23], 0, v[154:155]
	s_add_i32 m0, s38, 0xe000
	s_nop 0
	global_load_lds_dwordx4 v[164:165], off
	s_waitcnt vmcnt(8)
	s_waitcnt lgkmcnt(0)
	s_barrier
	s_waitcnt lgkmcnt(0)
	v_mfma_f32_16x16x32_bf16 v[126:129], v[130:133], v[178:181], v[126:129]
	v_mfma_f32_16x16x32_bf16 v[122:125], v[138:141], v[178:181], v[122:125]
	v_mfma_f32_16x16x32_bf16 v[110:113], v[130:133], v[186:189], v[110:113]
	v_mfma_f32_16x16x32_bf16 v[106:109], v[138:141], v[186:189], v[106:109]
	v_mfma_f32_16x16x32_bf16 v[94:97], v[130:133], v[202:205], v[94:97]
	v_mfma_f32_16x16x32_bf16 v[90:93], v[138:141], v[202:205], v[90:93]
	v_mfma_f32_16x16x32_bf16 v[78:81], v[130:133], v[210:213], v[78:81]
	v_mfma_f32_16x16x32_bf16 v[74:77], v[138:141], v[210:213], v[74:77]
	v_mfma_f32_16x16x32_bf16 v[126:129], v[134:137], v[182:185], v[126:129]
	v_mfma_f32_16x16x32_bf16 v[122:125], v[142:145], v[182:185], v[122:125]
	v_mfma_f32_16x16x32_bf16 v[110:113], v[134:137], v[190:193], v[110:113]
	v_mfma_f32_16x16x32_bf16 v[106:109], v[142:145], v[190:193], v[106:109]
	v_mfma_f32_16x16x32_bf16 v[94:97], v[134:137], v[206:209], v[94:97]
	v_mfma_f32_16x16x32_bf16 v[90:93], v[142:145], v[206:209], v[90:93]
	v_mfma_f32_16x16x32_bf16 v[78:81], v[134:137], v[214:217], v[78:81]
	v_mfma_f32_16x16x32_bf16 v[74:77], v[142:145], v[214:217], v[74:77]
	v_mfma_f32_16x16x32_bf16 v[118:121], v[156:159], v[178:181], v[118:121]
	v_mfma_f32_16x16x32_bf16 v[114:117], v[170:173], v[178:181], v[114:117]
	v_mfma_f32_16x16x32_bf16 v[102:105], v[156:159], v[186:189], v[102:105]
	v_mfma_f32_16x16x32_bf16 v[98:101], v[170:173], v[186:189], v[98:101]
	v_mfma_f32_16x16x32_bf16 v[86:89], v[156:159], v[202:205], v[86:89]
	v_mfma_f32_16x16x32_bf16 v[82:85], v[170:173], v[202:205], v[82:85]
	v_mfma_f32_16x16x32_bf16 v[70:73], v[156:159], v[210:213], v[70:73]
	v_mfma_f32_16x16x32_bf16 v[66:69], v[170:173], v[210:213], v[66:69]
	v_mfma_f32_16x16x32_bf16 v[118:121], v[160:163], v[182:185], v[118:121]
	v_mfma_f32_16x16x32_bf16 v[114:117], v[174:177], v[182:185], v[114:117]
	v_mfma_f32_16x16x32_bf16 v[102:105], v[160:163], v[190:193], v[102:105]
	v_mfma_f32_16x16x32_bf16 v[98:101], v[174:177], v[190:193], v[98:101]
	v_mfma_f32_16x16x32_bf16 v[86:89], v[160:163], v[206:209], v[86:89]
	v_mfma_f32_16x16x32_bf16 v[82:85], v[174:177], v[206:209], v[82:85]
	v_mfma_f32_16x16x32_bf16 v[70:73], v[160:163], v[214:217], v[70:73]
	v_mfma_f32_16x16x32_bf16 v[66:69], v[174:177], v[214:217], v[66:69]
	s_barrier
	s_add_i32 s52, s52, s37
	v_lshl_add_u64 v[164:165], s[24:25], 0, v[194:195]
	s_mov_b32 m0, s52
	ds_read_b128 v[178:181], v169 offset:16384
	ds_read_b128 v[182:185], v169 offset:17408
	ds_read_b128 v[186:189], v169 offset:18432
	ds_read_b128 v[190:193], v169 offset:19456
	ds_read_b128 v[202:205], v169 offset:20480
	ds_read_b128 v[206:209], v169 offset:21504
	ds_read_b128 v[210:213], v169 offset:22528
	ds_read_b128 v[214:217], v169 offset:23552
	global_load_lds_dwordx4 v[164:165], off
	s_add_i32 m0, s52, 0x2000
	s_add_u32 s52, s24, 0x40000
	v_lshl_add_u64 v[218:219], s[24:25], 0, v[150:151]
	s_addc_u32 s53, s25, 0
	s_add_i32 s54, s54, s37
	global_load_lds_dwordx4 v[218:219], off
	v_lshl_add_u64 v[220:221], s[52:53], 0, v[194:195]
	s_mov_b32 m0, s54
	v_lshl_add_u64 v[222:223], s[26:27], 0, v[148:149]
	global_load_lds_dwordx4 v[220:221], off
	v_lshl_add_u64 v[220:221], s[52:53], 0, v[150:151]
	s_add_i32 m0, s54, 0x2000
	s_nop 0
	global_load_lds_dwordx4 v[220:221], off
	v_lshl_add_u64 v[220:221], s[26:27], 0, v[146:147]
	s_mov_b32 m0, s38
	s_nop 0
	global_load_lds_dwordx4 v[220:221], off
	s_mov_b32 m0, s39
	s_nop 0
	global_load_lds_dwordx4 v[222:223], off
	s_waitcnt vmcnt(8)
	s_waitcnt lgkmcnt(0)
	s_barrier
	s_waitcnt lgkmcnt(0)
	v_mfma_f32_16x16x32_bf16 v[62:65], v[130:133], v[178:181], v[62:65]
	v_mfma_f32_16x16x32_bf16 v[58:61], v[138:141], v[178:181], v[58:61]
	v_mfma_f32_16x16x32_bf16 v[46:49], v[130:133], v[186:189], v[46:49]
	v_mfma_f32_16x16x32_bf16 v[42:45], v[138:141], v[186:189], v[42:45]
	v_mfma_f32_16x16x32_bf16 v[30:33], v[130:133], v[202:205], v[30:33]
	v_mfma_f32_16x16x32_bf16 v[26:29], v[138:141], v[202:205], v[26:29]
	v_mfma_f32_16x16x32_bf16 v[14:17], v[130:133], v[210:213], v[14:17]
	v_mfma_f32_16x16x32_bf16 v[10:13], v[138:141], v[210:213], v[10:13]
	v_mfma_f32_16x16x32_bf16 v[62:65], v[134:137], v[182:185], v[62:65]
	v_mfma_f32_16x16x32_bf16 v[58:61], v[142:145], v[182:185], v[58:61]
	v_mfma_f32_16x16x32_bf16 v[46:49], v[134:137], v[190:193], v[46:49]
	v_mfma_f32_16x16x32_bf16 v[42:45], v[142:145], v[190:193], v[42:45]
	v_mfma_f32_16x16x32_bf16 v[30:33], v[134:137], v[206:209], v[30:33]
	v_mfma_f32_16x16x32_bf16 v[26:29], v[142:145], v[206:209], v[26:29]
	v_mfma_f32_16x16x32_bf16 v[14:17], v[134:137], v[214:217], v[14:17]
	v_mfma_f32_16x16x32_bf16 v[10:13], v[142:145], v[214:217], v[10:13]
	v_mfma_f32_16x16x32_bf16 v[54:57], v[156:159], v[178:181], v[54:57]
	v_mfma_f32_16x16x32_bf16 v[50:53], v[170:173], v[178:181], v[50:53]
	v_mfma_f32_16x16x32_bf16 v[38:41], v[156:159], v[186:189], v[38:41]
	v_mfma_f32_16x16x32_bf16 v[34:37], v[170:173], v[186:189], v[34:37]
	v_mfma_f32_16x16x32_bf16 v[22:25], v[156:159], v[202:205], v[22:25]
	v_mfma_f32_16x16x32_bf16 v[18:21], v[170:173], v[202:205], v[18:21]
	v_mfma_f32_16x16x32_bf16 v[6:9], v[156:159], v[210:213], v[6:9]
	v_mfma_f32_16x16x32_bf16 v[2:5], v[170:173], v[210:213], v[2:5]
	v_mfma_f32_16x16x32_bf16 v[54:57], v[160:163], v[182:185], v[54:57]
	v_mfma_f32_16x16x32_bf16 v[50:53], v[174:177], v[182:185], v[50:53]
	v_mfma_f32_16x16x32_bf16 v[38:41], v[160:163], v[190:193], v[38:41]
	v_mfma_f32_16x16x32_bf16 v[34:37], v[174:177], v[190:193], v[34:37]
	v_mfma_f32_16x16x32_bf16 v[22:25], v[160:163], v[206:209], v[22:25]
	v_mfma_f32_16x16x32_bf16 v[18:21], v[174:177], v[206:209], v[18:21]
	v_mfma_f32_16x16x32_bf16 v[6:9], v[160:163], v[214:217], v[6:9]
	v_mfma_f32_16x16x32_bf16 v[2:5], v[174:177], v[214:217], v[2:5]
	s_barrier
	s_add_i32 s52, 0, 0x18000
	s_add_i32 s53, 0, 0x1c000
	v_add_u32_e32 v142, s52, v167
	v_add_u32_e32 v174, s53, v167
	ds_read_b128 v[130:133], v142
	ds_read_b128 v[134:137], v142 offset:1024
	ds_read_b128 v[138:141], v142 offset:2048
	ds_read_b128 v[142:145], v142 offset:3072
	ds_read_b128 v[156:159], v174
	ds_read_b128 v[160:163], v174 offset:1024
	ds_read_b128 v[170:173], v174 offset:2048
	ds_read_b128 v[174:177], v174 offset:3072
	s_add_u32 s26, s26, 0x40000
	s_addc_u32 s27, s27, 0
	s_mov_b32 m0, s42
	v_lshl_add_u64 v[224:225], s[26:27], 0, v[146:147]
	ds_read_b128 v[178:181], v169 offset:32768
	ds_read_b128 v[182:185], v169 offset:33792
	ds_read_b128 v[186:189], v169 offset:34816
	ds_read_b128 v[190:193], v169 offset:35840
	ds_read_b128 v[202:205], v169 offset:36864
	ds_read_b128 v[206:209], v169 offset:37888
	ds_read_b128 v[210:213], v169 offset:38912
	ds_read_b128 v[214:217], v169 offset:39936
	global_load_lds_dwordx4 v[224:225], off
	v_lshl_add_u64 v[224:225], s[26:27], 0, v[148:149]
	s_mov_b32 m0, s43
	s_nop 0
	global_load_lds_dwordx4 v[224:225], off
	s_waitcnt vmcnt(8)
	s_waitcnt lgkmcnt(0)
	s_barrier
	s_waitcnt lgkmcnt(0)
	v_mfma_f32_16x16x32_bf16 v[126:129], v[130:133], v[178:181], v[126:129]
	v_mfma_f32_16x16x32_bf16 v[122:125], v[138:141], v[178:181], v[122:125]
	v_mfma_f32_16x16x32_bf16 v[110:113], v[130:133], v[186:189], v[110:113]
	v_mfma_f32_16x16x32_bf16 v[106:109], v[138:141], v[186:189], v[106:109]
	v_mfma_f32_16x16x32_bf16 v[94:97], v[130:133], v[202:205], v[94:97]
	v_mfma_f32_16x16x32_bf16 v[90:93], v[138:141], v[202:205], v[90:93]
	v_mfma_f32_16x16x32_bf16 v[78:81], v[130:133], v[210:213], v[78:81]
	v_mfma_f32_16x16x32_bf16 v[74:77], v[138:141], v[210:213], v[74:77]
	v_mfma_f32_16x16x32_bf16 v[126:129], v[134:137], v[182:185], v[126:129]
	v_mfma_f32_16x16x32_bf16 v[122:125], v[142:145], v[182:185], v[122:125]
	v_mfma_f32_16x16x32_bf16 v[110:113], v[134:137], v[190:193], v[110:113]
	v_mfma_f32_16x16x32_bf16 v[106:109], v[142:145], v[190:193], v[106:109]
	v_mfma_f32_16x16x32_bf16 v[94:97], v[134:137], v[206:209], v[94:97]
	v_mfma_f32_16x16x32_bf16 v[90:93], v[142:145], v[206:209], v[90:93]
	v_mfma_f32_16x16x32_bf16 v[78:81], v[134:137], v[214:217], v[78:81]
	v_mfma_f32_16x16x32_bf16 v[74:77], v[142:145], v[214:217], v[74:77]
	v_mfma_f32_16x16x32_bf16 v[118:121], v[156:159], v[178:181], v[118:121]
	v_mfma_f32_16x16x32_bf16 v[114:117], v[170:173], v[178:181], v[114:117]
	v_mfma_f32_16x16x32_bf16 v[102:105], v[156:159], v[186:189], v[102:105]
	v_mfma_f32_16x16x32_bf16 v[98:101], v[170:173], v[186:189], v[98:101]
	v_mfma_f32_16x16x32_bf16 v[86:89], v[156:159], v[202:205], v[86:89]
	v_mfma_f32_16x16x32_bf16 v[82:85], v[170:173], v[202:205], v[82:85]
	v_mfma_f32_16x16x32_bf16 v[70:73], v[156:159], v[210:213], v[70:73]
	v_mfma_f32_16x16x32_bf16 v[66:69], v[170:173], v[210:213], v[66:69]
	v_mfma_f32_16x16x32_bf16 v[118:121], v[160:163], v[182:185], v[118:121]
	v_mfma_f32_16x16x32_bf16 v[114:117], v[174:177], v[182:185], v[114:117]
	v_mfma_f32_16x16x32_bf16 v[102:105], v[160:163], v[190:193], v[102:105]
	v_mfma_f32_16x16x32_bf16 v[98:101], v[174:177], v[190:193], v[98:101]
	v_mfma_f32_16x16x32_bf16 v[86:89], v[160:163], v[206:209], v[86:89]
	v_mfma_f32_16x16x32_bf16 v[82:85], v[174:177], v[206:209], v[82:85]
	v_mfma_f32_16x16x32_bf16 v[70:73], v[160:163], v[214:217], v[70:73]
	v_mfma_f32_16x16x32_bf16 v[66:69], v[174:177], v[214:217], v[66:69]
	s_barrier
	s_add_i32 s26, s52, s37
	v_lshl_add_u64 v[164:165], v[164:165], 0, s[92:93]
	s_mov_b32 m0, s26
	ds_read_b128 v[178:181], v169 offset:49152
	ds_read_b128 v[182:185], v169 offset:50176
	ds_read_b128 v[186:189], v169 offset:51200
	ds_read_b128 v[190:193], v169 offset:52224
	ds_read_b128 v[202:205], v169 offset:53248
	ds_read_b128 v[206:209], v169 offset:54272
	ds_read_b128 v[210:213], v169 offset:55296
	ds_read_b128 v[214:217], v169 offset:56320
	global_load_lds_dwordx4 v[164:165], off
	s_add_i32 m0, s26, 0x2000
	s_add_u32 s24, s24, 0x40080
	v_lshl_add_u64 v[164:165], v[218:219], 0, s[92:93]
	s_addc_u32 s25, s25, 0
	s_add_i32 s26, s53, s37
	global_load_lds_dwordx4 v[164:165], off
	v_lshl_add_u64 v[164:165], s[24:25], 0, v[194:195]
	s_mov_b32 m0, s26
	s_nop 0
	global_load_lds_dwordx4 v[164:165], off
	v_lshl_add_u64 v[164:165], s[24:25], 0, v[150:151]
	s_add_i32 m0, s26, 0x2000
	s_nop 0
	global_load_lds_dwordx4 v[164:165], off
	v_lshl_add_u64 v[164:165], v[220:221], 0, s[92:93]
	s_mov_b32 m0, s45
	s_nop 0
	global_load_lds_dwordx4 v[164:165], off
	v_lshl_add_u64 v[164:165], v[222:223], 0, s[92:93]
	s_mov_b32 m0, s46
	s_nop 0
	global_load_lds_dwordx4 v[164:165], off
	s_waitcnt vmcnt(8)
	s_waitcnt lgkmcnt(0)
	s_barrier
	s_waitcnt lgkmcnt(0)
	v_mfma_f32_16x16x32_bf16 v[62:65], v[130:133], v[178:181], v[62:65]
	v_mfma_f32_16x16x32_bf16 v[58:61], v[138:141], v[178:181], v[58:61]
	v_mfma_f32_16x16x32_bf16 v[46:49], v[130:133], v[186:189], v[46:49]
	v_mfma_f32_16x16x32_bf16 v[42:45], v[138:141], v[186:189], v[42:45]
	v_mfma_f32_16x16x32_bf16 v[30:33], v[130:133], v[202:205], v[30:33]
	v_mfma_f32_16x16x32_bf16 v[26:29], v[138:141], v[202:205], v[26:29]
	v_mfma_f32_16x16x32_bf16 v[14:17], v[130:133], v[210:213], v[14:17]
	v_mfma_f32_16x16x32_bf16 v[10:13], v[138:141], v[210:213], v[10:13]
	v_mfma_f32_16x16x32_bf16 v[62:65], v[134:137], v[182:185], v[62:65]
	v_mfma_f32_16x16x32_bf16 v[58:61], v[142:145], v[182:185], v[58:61]
	v_mfma_f32_16x16x32_bf16 v[46:49], v[134:137], v[190:193], v[46:49]
	v_mfma_f32_16x16x32_bf16 v[42:45], v[142:145], v[190:193], v[42:45]
	v_mfma_f32_16x16x32_bf16 v[30:33], v[134:137], v[206:209], v[30:33]
	v_mfma_f32_16x16x32_bf16 v[26:29], v[142:145], v[206:209], v[26:29]
	v_mfma_f32_16x16x32_bf16 v[14:17], v[134:137], v[214:217], v[14:17]
	v_mfma_f32_16x16x32_bf16 v[10:13], v[142:145], v[214:217], v[10:13]
	v_mfma_f32_16x16x32_bf16 v[54:57], v[156:159], v[178:181], v[54:57]
	v_mfma_f32_16x16x32_bf16 v[50:53], v[170:173], v[178:181], v[50:53]
	v_mfma_f32_16x16x32_bf16 v[38:41], v[156:159], v[186:189], v[38:41]
	v_mfma_f32_16x16x32_bf16 v[34:37], v[170:173], v[186:189], v[34:37]
	v_mfma_f32_16x16x32_bf16 v[22:25], v[156:159], v[202:205], v[22:25]
	v_mfma_f32_16x16x32_bf16 v[18:21], v[170:173], v[202:205], v[18:21]
	v_mfma_f32_16x16x32_bf16 v[6:9], v[156:159], v[210:213], v[6:9]
	v_mfma_f32_16x16x32_bf16 v[2:5], v[170:173], v[210:213], v[2:5]
	v_mfma_f32_16x16x32_bf16 v[54:57], v[160:163], v[182:185], v[54:57]
	v_mfma_f32_16x16x32_bf16 v[50:53], v[174:177], v[182:185], v[50:53]
	v_mfma_f32_16x16x32_bf16 v[38:41], v[160:163], v[190:193], v[38:41]
	v_mfma_f32_16x16x32_bf16 v[34:37], v[174:177], v[190:193], v[34:37]
	v_mfma_f32_16x16x32_bf16 v[22:25], v[160:163], v[206:209], v[22:25]
	v_mfma_f32_16x16x32_bf16 v[18:21], v[174:177], v[206:209], v[18:21]
	v_mfma_f32_16x16x32_bf16 v[6:9], v[160:163], v[214:217], v[6:9]
	v_mfma_f32_16x16x32_bf16 v[2:5], v[174:177], v[214:217], v[2:5]
	s_barrier
	s_add_i32 s51, s51, 2
	s_add_u32 s22, s22, 0x100
	s_addc_u32 s23, s23, 0
	s_add_u32 s49, s49, 0x100
	s_addc_u32 s50, s50, 0
	s_cmp_gt_u32 s51, 13
	s_cbranch_scc0 .LBB0_939
	v_lshl_add_u32 v156, s20, 8, v166
	v_lshl_or_b32 v158, s18, 8, v168
	v_ashrrev_i32_e32 v157, 31, v156
	v_lshlrev_b64 v[130:131], 11, v[156:157]
	v_ashrrev_i32_e32 v159, 31, v158
	v_lshl_add_u64 v[130:131], s[8:9], 0, v[130:131]
	v_lshlrev_b64 v[132:133], 1, v[158:159]
	v_lshl_add_u64 v[164:165], v[130:131], 0, v[132:133]
	global_load_dwordx4 v[142:145], v[164:165], off
	global_load_dwordx4 v[138:141], v[164:165], off offset:256
	v_or_b32_e32 v160, 16, v156
	v_ashrrev_i32_e32 v161, 31, v160
	v_lshlrev_b64 v[130:131], 11, v[160:161]
	v_lshl_add_u64 v[130:131], s[8:9], 0, v[130:131]
	v_lshl_add_u64 v[162:163], v[130:131], 0, v[132:133]
	global_load_dwordx4 v[134:137], v[162:163], off
	global_load_dwordx4 v[130:133], v[162:163], off offset:256
	v_and_b32_e32 v171, 64, v1
	v_xor_b32_e32 v170, 16, v1
	v_add_u32_e32 v171, 64, v171
	v_xor_b32_e32 v172, 32, v1
	v_cmp_lt_i32_e32 vcc, v170, v171
	s_lshl_b32 s18, s18, 2
	s_ashr_i32 s19, s18, 31
	v_cndmask_b32_e32 v170, v1, v170, vcc
	v_cmp_lt_i32_e32 vcc, v172, v171
	v_lshlrev_b32_e32 v170, 2, v170
	s_waitcnt vmcnt(0)
	v_and_b32_e32 v173, 0xffff0000, v142
	v_cndmask_b32_e32 v171, v1, v172, vcc
	v_lshlrev_b32_e32 v172, 16, v142
	v_lshlrev_b32_e32 v142, 16, v143
	v_and_b32_e32 v143, 0xffff0000, v143
	v_lshlrev_b32_e32 v174, 16, v144
	v_and_b32_e32 v175, 0xffff0000, v144
	v_lshlrev_b32_e32 v144, 16, v145
	v_and_b32_e32 v145, 0xffff0000, v145
	v_lshlrev_b32_e32 v176, 16, v138
	v_and_b32_e32 v177, 0xffff0000, v138
	v_lshlrev_b32_e32 v138, 16, v139
	v_and_b32_e32 v139, 0xffff0000, v139
	v_lshlrev_b32_e32 v178, 16, v140
	v_and_b32_e32 v179, 0xffff0000, v140
	v_lshlrev_b32_e32 v140, 16, v141
	v_and_b32_e32 v141, 0xffff0000, v141
	v_pk_add_f32 v[128:129], v[128:129], v[142:143]
	v_pk_add_f32 v[126:127], v[126:127], v[172:173]
	v_pk_add_f32 v[122:123], v[122:123], v[174:175]
	v_pk_add_f32 v[124:125], v[124:125], v[144:145]
	v_pk_add_f32 v[120:121], v[120:121], v[138:139]
	v_pk_add_f32 v[118:119], v[118:119], v[176:177]
	v_pk_add_f32 v[138:139], v[114:115], v[178:179]
	v_pk_add_f32 v[140:141], v[116:117], v[140:141]
	v_cvt_pk_bf16_f32 v114, v126, v127
	v_cvt_pk_bf16_f32 v115, v128, v129
	v_mul_f32_e32 v116, v126, v126
	v_mul_f32_e32 v117, v128, v128
	v_mul_f32_e32 v126, v122, v122
	v_mul_f32_e32 v128, v125, v125
	v_mul_f32_e32 v142, v118, v118
	v_mul_f32_e32 v143, v120, v120
	v_mul_f32_e32 v144, v138, v138
	v_mul_f32_e32 v145, v141, v141
	v_fmac_f32_e32 v116, v127, v127
	v_fmac_f32_e32 v117, v129, v129
	v_fmac_f32_e32 v126, v123, v123
	v_fmac_f32_e32 v128, v124, v124
	v_fmac_f32_e32 v142, v119, v119
	v_fmac_f32_e32 v143, v121, v121
	v_fmac_f32_e32 v144, v139, v139
	v_fmac_f32_e32 v145, v140, v140
	v_add_f32_e32 v116, v117, v116
	v_add_f32_e32 v117, v128, v126
	v_add_f32_e32 v126, v143, v142
	v_add_f32_e32 v127, v145, v144
	v_add_f32_e32 v116, v117, v116
	v_add_f32_e32 v117, v127, v126
	v_add_f32_e32 v126, v116, v117
	ds_bpermute_b32 v127, v170, v126
	v_cvt_pk_bf16_f32 v116, v122, v123
	v_cvt_pk_bf16_f32 v117, v124, v125
	global_store_dwordx4 v[164:165], v[114:117], off
	s_waitcnt lgkmcnt(0)
	s_nop 0
	v_add_f32_e32 v114, v126, v127
	v_lshlrev_b32_e32 v126, 2, v171
	ds_bpermute_b32 v115, v126, v114
	v_cvt_pk_bf16_f32 v116, v118, v119
	v_cvt_pk_bf16_f32 v117, v120, v121
	v_cvt_pk_bf16_f32 v118, v138, v139
	v_cvt_pk_bf16_f32 v119, v140, v141
	global_store_dwordx4 v[164:165], v[116:119], off offset:256
	s_and_saveexec_b64 s[20:21], s[0:1]
	s_cbranch_execz .LBB0_942
	v_lshlrev_b64 v[116:117], 7, v[156:157]
	v_lshl_add_u64 v[116:117], s[6:7], 0, v[116:117]
	v_lshl_add_u64 v[116:117], s[18:19], 2, v[116:117]
	s_lshl_b32 s94, s44, 2
	v_lshl_add_u64 v[116:117], v[116:117], 0, s[94:95]
	s_waitcnt lgkmcnt(0)
	v_add_f32_e32 v114, v114, v115
	global_store_dword v[116:117], v114, off

.LBB0_1040:
	s_add_u32 s22, s20, 0xfffc0080
	s_addc_u32 s23, s21, -1
	s_add_i32 s51, 0, 0x10000
	s_cmp_eq_u32 s50, 12
	s_cselect_b32 s25, s13, s23
	s_cselect_b32 s24, s46, s22
	s_cselect_b32 s23, s11, s49
	s_cselect_b32 s22, s47, s48
	s_add_i32 s54, 0, 0x14000
	v_add_u32_e32 v156, s51, v145
	v_add_u32_e32 v172, s54, v145
	ds_read_b128 v[140:143], v156
	ds_read_b128 v[148:151], v156 offset:1024
	ds_read_b128 v[152:155], v156 offset:2048
	ds_read_b128 v[156:159], v156 offset:3072
	ds_read_b128 v[160:163], v172
	ds_read_b128 v[164:167], v172 offset:1024
	ds_read_b128 v[168:171], v172 offset:2048
	ds_read_b128 v[172:175], v172 offset:3072
	v_lshl_add_u64 v[192:193], s[20:21], 0, v[136:137]
	s_add_i32 m0, s19, 0xc000
	ds_read_b128 v[176:179], v147
	ds_read_b128 v[180:183], v147 offset:1024
	ds_read_b128 v[184:187], v147 offset:2048
	ds_read_b128 v[188:191], v147 offset:3072
	ds_read_b128 v[202:205], v147 offset:4096
	ds_read_b128 v[206:209], v147 offset:5120
	ds_read_b128 v[210:213], v147 offset:6144
	ds_read_b128 v[214:217], v147 offset:7168
	global_load_lds_dwordx4 v[192:193], off
	v_lshl_add_u64 v[192:193], s[20:21], 0, v[138:139]
	s_add_i32 m0, s19, 0xe000
	s_nop 0
	global_load_lds_dwordx4 v[192:193], off
	s_waitcnt vmcnt(8)
	s_waitcnt lgkmcnt(0)
	s_barrier
	s_waitcnt lgkmcnt(0)
	v_mfma_f32_16x16x32_bf16 v[126:129], v[140:143], v[176:179], v[126:129]
	v_mfma_f32_16x16x32_bf16 v[122:125], v[152:155], v[176:179], v[122:125]
	v_mfma_f32_16x16x32_bf16 v[110:113], v[140:143], v[184:187], v[110:113]
	v_mfma_f32_16x16x32_bf16 v[106:109], v[152:155], v[184:187], v[106:109]
	v_mfma_f32_16x16x32_bf16 v[94:97], v[140:143], v[202:205], v[94:97]
	v_mfma_f32_16x16x32_bf16 v[90:93], v[152:155], v[202:205], v[90:93]
	v_mfma_f32_16x16x32_bf16 v[78:81], v[140:143], v[210:213], v[78:81]
	v_mfma_f32_16x16x32_bf16 v[74:77], v[152:155], v[210:213], v[74:77]
	v_mfma_f32_16x16x32_bf16 v[126:129], v[148:151], v[180:183], v[126:129]
	v_mfma_f32_16x16x32_bf16 v[122:125], v[156:159], v[180:183], v[122:125]
	v_mfma_f32_16x16x32_bf16 v[110:113], v[148:151], v[188:191], v[110:113]
	v_mfma_f32_16x16x32_bf16 v[106:109], v[156:159], v[188:191], v[106:109]
	v_mfma_f32_16x16x32_bf16 v[94:97], v[148:151], v[206:209], v[94:97]
	v_mfma_f32_16x16x32_bf16 v[90:93], v[156:159], v[206:209], v[90:93]
	v_mfma_f32_16x16x32_bf16 v[78:81], v[148:151], v[214:217], v[78:81]
	v_mfma_f32_16x16x32_bf16 v[74:77], v[156:159], v[214:217], v[74:77]
	v_mfma_f32_16x16x32_bf16 v[118:121], v[160:163], v[176:179], v[118:121]
	v_mfma_f32_16x16x32_bf16 v[114:117], v[168:171], v[176:179], v[114:117]
	v_mfma_f32_16x16x32_bf16 v[102:105], v[160:163], v[184:187], v[102:105]
	v_mfma_f32_16x16x32_bf16 v[98:101], v[168:171], v[184:187], v[98:101]
	v_mfma_f32_16x16x32_bf16 v[86:89], v[160:163], v[202:205], v[86:89]
	v_mfma_f32_16x16x32_bf16 v[82:85], v[168:171], v[202:205], v[82:85]
	v_mfma_f32_16x16x32_bf16 v[70:73], v[160:163], v[210:213], v[70:73]
	v_mfma_f32_16x16x32_bf16 v[66:69], v[168:171], v[210:213], v[66:69]
	v_mfma_f32_16x16x32_bf16 v[118:121], v[164:167], v[180:183], v[118:121]
	v_mfma_f32_16x16x32_bf16 v[114:117], v[172:175], v[180:183], v[114:117]
	v_mfma_f32_16x16x32_bf16 v[102:105], v[164:167], v[188:191], v[102:105]
	v_mfma_f32_16x16x32_bf16 v[98:101], v[172:175], v[188:191], v[98:101]
	v_mfma_f32_16x16x32_bf16 v[86:89], v[164:167], v[206:209], v[86:89]
	v_mfma_f32_16x16x32_bf16 v[82:85], v[172:175], v[206:209], v[82:85]
	v_mfma_f32_16x16x32_bf16 v[70:73], v[164:167], v[214:217], v[70:73]
	v_mfma_f32_16x16x32_bf16 v[66:69], v[172:175], v[214:217], v[66:69]
	s_barrier
	s_add_i32 s51, s51, s36
	v_lshl_add_u64 v[192:193], s[22:23], 0, v[194:195]
	s_mov_b32 m0, s51
	ds_read_b128 v[176:179], v147 offset:16384
	ds_read_b128 v[180:183], v147 offset:17408
	ds_read_b128 v[184:187], v147 offset:18432
	ds_read_b128 v[188:191], v147 offset:19456
	ds_read_b128 v[202:205], v147 offset:20480
	ds_read_b128 v[206:209], v147 offset:21504
	ds_read_b128 v[210:213], v147 offset:22528
	ds_read_b128 v[214:217], v147 offset:23552
	global_load_lds_dwordx4 v[192:193], off
	s_add_i32 m0, s51, 0x2000
	s_add_u32 s52, s22, 0x40000
	v_lshl_add_u64 v[218:219], s[22:23], 0, v[134:135]
	s_addc_u32 s53, s23, 0
	s_add_i32 s51, s54, s36
	global_load_lds_dwordx4 v[218:219], off
	v_lshl_add_u64 v[220:221], s[52:53], 0, v[194:195]
	s_mov_b32 m0, s51
	v_lshl_add_u64 v[222:223], s[24:25], 0, v[132:133]
	global_load_lds_dwordx4 v[220:221], off
	v_lshl_add_u64 v[220:221], s[52:53], 0, v[134:135]
	s_add_i32 m0, s51, 0x2000
	s_nop 0
	global_load_lds_dwordx4 v[220:221], off
	v_lshl_add_u64 v[220:221], s[24:25], 0, v[130:131]
	s_mov_b32 m0, s19
	s_nop 0
	global_load_lds_dwordx4 v[220:221], off
	s_mov_b32 m0, s37
	s_nop 0
	global_load_lds_dwordx4 v[222:223], off
	s_waitcnt vmcnt(8)
	s_waitcnt lgkmcnt(0)
	s_barrier
	s_waitcnt lgkmcnt(0)
	v_mfma_f32_16x16x32_bf16 v[62:65], v[140:143], v[176:179], v[62:65]
	v_mfma_f32_16x16x32_bf16 v[58:61], v[152:155], v[176:179], v[58:61]
	v_mfma_f32_16x16x32_bf16 v[46:49], v[140:143], v[184:187], v[46:49]
	v_mfma_f32_16x16x32_bf16 v[42:45], v[152:155], v[184:187], v[42:45]
	v_mfma_f32_16x16x32_bf16 v[30:33], v[140:143], v[202:205], v[30:33]
	v_mfma_f32_16x16x32_bf16 v[26:29], v[152:155], v[202:205], v[26:29]
	v_mfma_f32_16x16x32_bf16 v[14:17], v[140:143], v[210:213], v[14:17]
	v_mfma_f32_16x16x32_bf16 v[10:13], v[152:155], v[210:213], v[10:13]
	v_mfma_f32_16x16x32_bf16 v[62:65], v[148:151], v[180:183], v[62:65]
	v_mfma_f32_16x16x32_bf16 v[58:61], v[156:159], v[180:183], v[58:61]
	v_mfma_f32_16x16x32_bf16 v[46:49], v[148:151], v[188:191], v[46:49]
	v_mfma_f32_16x16x32_bf16 v[42:45], v[156:159], v[188:191], v[42:45]
	v_mfma_f32_16x16x32_bf16 v[30:33], v[148:151], v[206:209], v[30:33]
	v_mfma_f32_16x16x32_bf16 v[26:29], v[156:159], v[206:209], v[26:29]
	v_mfma_f32_16x16x32_bf16 v[14:17], v[148:151], v[214:217], v[14:17]
	v_mfma_f32_16x16x32_bf16 v[10:13], v[156:159], v[214:217], v[10:13]
	v_mfma_f32_16x16x32_bf16 v[54:57], v[160:163], v[176:179], v[54:57]
	v_mfma_f32_16x16x32_bf16 v[50:53], v[168:171], v[176:179], v[50:53]
	v_mfma_f32_16x16x32_bf16 v[38:41], v[160:163], v[184:187], v[38:41]
	v_mfma_f32_16x16x32_bf16 v[34:37], v[168:171], v[184:187], v[34:37]
	v_mfma_f32_16x16x32_bf16 v[22:25], v[160:163], v[202:205], v[22:25]
	v_mfma_f32_16x16x32_bf16 v[18:21], v[168:171], v[202:205], v[18:21]
	v_mfma_f32_16x16x32_bf16 v[6:9], v[160:163], v[210:213], v[6:9]
	v_mfma_f32_16x16x32_bf16 v[2:5], v[168:171], v[210:213], v[2:5]
	v_mfma_f32_16x16x32_bf16 v[54:57], v[164:167], v[180:183], v[54:57]
	v_mfma_f32_16x16x32_bf16 v[50:53], v[172:175], v[180:183], v[50:53]
	v_mfma_f32_16x16x32_bf16 v[38:41], v[164:167], v[188:191], v[38:41]
	v_mfma_f32_16x16x32_bf16 v[34:37], v[172:175], v[188:191], v[34:37]
	v_mfma_f32_16x16x32_bf16 v[22:25], v[164:167], v[206:209], v[22:25]
	v_mfma_f32_16x16x32_bf16 v[18:21], v[172:175], v[206:209], v[18:21]
	v_mfma_f32_16x16x32_bf16 v[6:9], v[164:167], v[214:217], v[6:9]
	v_mfma_f32_16x16x32_bf16 v[2:5], v[172:175], v[214:217], v[2:5]
	s_barrier
	s_add_i32 s51, 0, 0x18000
	s_add_i32 s52, 0, 0x1c000
	v_add_u32_e32 v156, s51, v145
	v_add_u32_e32 v172, s52, v145
	ds_read_b128 v[140:143], v156
	ds_read_b128 v[148:151], v156 offset:1024
	ds_read_b128 v[152:155], v156 offset:2048
	ds_read_b128 v[156:159], v156 offset:3072
	ds_read_b128 v[160:163], v172
	ds_read_b128 v[164:167], v172 offset:1024
	ds_read_b128 v[168:171], v172 offset:2048
	ds_read_b128 v[172:175], v172 offset:3072
	s_add_u32 s24, s24, 0x40000
	s_addc_u32 s25, s25, 0
	s_mov_b32 m0, s38
	v_lshl_add_u64 v[224:225], s[24:25], 0, v[130:131]
	ds_read_b128 v[176:179], v147 offset:32768
	ds_read_b128 v[180:183], v147 offset:33792
	ds_read_b128 v[184:187], v147 offset:34816
	ds_read_b128 v[188:191], v147 offset:35840
	ds_read_b128 v[202:205], v147 offset:36864
	ds_read_b128 v[206:209], v147 offset:37888
	ds_read_b128 v[210:213], v147 offset:38912
	ds_read_b128 v[214:217], v147 offset:39936
	global_load_lds_dwordx4 v[224:225], off
	v_lshl_add_u64 v[224:225], s[24:25], 0, v[132:133]
	s_mov_b32 m0, s39
	s_nop 0
	global_load_lds_dwordx4 v[224:225], off
	s_waitcnt vmcnt(8)
	s_waitcnt lgkmcnt(0)
	s_barrier
	s_waitcnt lgkmcnt(0)
	v_mfma_f32_16x16x32_bf16 v[126:129], v[140:143], v[176:179], v[126:129]
	v_mfma_f32_16x16x32_bf16 v[122:125], v[152:155], v[176:179], v[122:125]
	v_mfma_f32_16x16x32_bf16 v[110:113], v[140:143], v[184:187], v[110:113]
	v_mfma_f32_16x16x32_bf16 v[106:109], v[152:155], v[184:187], v[106:109]
	v_mfma_f32_16x16x32_bf16 v[94:97], v[140:143], v[202:205], v[94:97]
	v_mfma_f32_16x16x32_bf16 v[90:93], v[152:155], v[202:205], v[90:93]
	v_mfma_f32_16x16x32_bf16 v[78:81], v[140:143], v[210:213], v[78:81]
	v_mfma_f32_16x16x32_bf16 v[74:77], v[152:155], v[210:213], v[74:77]
	v_mfma_f32_16x16x32_bf16 v[126:129], v[148:151], v[180:183], v[126:129]
	v_mfma_f32_16x16x32_bf16 v[122:125], v[156:159], v[180:183], v[122:125]
	v_mfma_f32_16x16x32_bf16 v[110:113], v[148:151], v[188:191], v[110:113]
	v_mfma_f32_16x16x32_bf16 v[106:109], v[156:159], v[188:191], v[106:109]
	v_mfma_f32_16x16x32_bf16 v[94:97], v[148:151], v[206:209], v[94:97]
	v_mfma_f32_16x16x32_bf16 v[90:93], v[156:159], v[206:209], v[90:93]
	v_mfma_f32_16x16x32_bf16 v[78:81], v[148:151], v[214:217], v[78:81]
	v_mfma_f32_16x16x32_bf16 v[74:77], v[156:159], v[214:217], v[74:77]
	v_mfma_f32_16x16x32_bf16 v[118:121], v[160:163], v[176:179], v[118:121]
	v_mfma_f32_16x16x32_bf16 v[114:117], v[168:171], v[176:179], v[114:117]
	v_mfma_f32_16x16x32_bf16 v[102:105], v[160:163], v[184:187], v[102:105]
	v_mfma_f32_16x16x32_bf16 v[98:101], v[168:171], v[184:187], v[98:101]
	v_mfma_f32_16x16x32_bf16 v[86:89], v[160:163], v[202:205], v[86:89]
	v_mfma_f32_16x16x32_bf16 v[82:85], v[168:171], v[202:205], v[82:85]
	v_mfma_f32_16x16x32_bf16 v[70:73], v[160:163], v[210:213], v[70:73]
	v_mfma_f32_16x16x32_bf16 v[66:69], v[168:171], v[210:213], v[66:69]
	v_mfma_f32_16x16x32_bf16 v[118:121], v[164:167], v[180:183], v[118:121]
	v_mfma_f32_16x16x32_bf16 v[114:117], v[172:175], v[180:183], v[114:117]
	v_mfma_f32_16x16x32_bf16 v[102:105], v[164:167], v[188:191], v[102:105]
	v_mfma_f32_16x16x32_bf16 v[98:101], v[172:175], v[188:191], v[98:101]
	v_mfma_f32_16x16x32_bf16 v[86:89], v[164:167], v[206:209], v[86:89]
	v_mfma_f32_16x16x32_bf16 v[82:85], v[172:175], v[206:209], v[82:85]
	v_mfma_f32_16x16x32_bf16 v[70:73], v[164:167], v[214:217], v[70:73]
	v_mfma_f32_16x16x32_bf16 v[66:69], v[172:175], v[214:217], v[66:69]
	s_barrier
	s_add_i32 s24, s51, s36
	v_lshl_add_u64 v[192:193], v[192:193], 0, s[92:93]
	s_mov_b32 m0, s24
	ds_read_b128 v[176:179], v147 offset:49152
	ds_read_b128 v[180:183], v147 offset:50176
	ds_read_b128 v[184:187], v147 offset:51200
	ds_read_b128 v[188:191], v147 offset:52224
	ds_read_b128 v[202:205], v147 offset:53248
	ds_read_b128 v[206:209], v147 offset:54272
	ds_read_b128 v[210:213], v147 offset:55296
	ds_read_b128 v[214:217], v147 offset:56320
	global_load_lds_dwordx4 v[192:193], off
	s_add_i32 m0, s24, 0x2000
	s_add_u32 s22, s22, 0x40080
	v_lshl_add_u64 v[192:193], v[218:219], 0, s[92:93]
	s_addc_u32 s23, s23, 0
	s_add_i32 s24, s52, s36
	global_load_lds_dwordx4 v[192:193], off
	v_lshl_add_u64 v[192:193], s[22:23], 0, v[194:195]
	s_mov_b32 m0, s24
	s_nop 0
	global_load_lds_dwordx4 v[192:193], off
	v_lshl_add_u64 v[192:193], s[22:23], 0, v[134:135]
	s_add_i32 m0, s24, 0x2000
	s_nop 0
	global_load_lds_dwordx4 v[192:193], off
	v_lshl_add_u64 v[192:193], v[220:221], 0, s[92:93]
	s_mov_b32 m0, s42
	s_nop 0
	global_load_lds_dwordx4 v[192:193], off
	v_lshl_add_u64 v[192:193], v[222:223], 0, s[92:93]
	s_mov_b32 m0, s43
	s_nop 0
	global_load_lds_dwordx4 v[192:193], off
	s_waitcnt vmcnt(8)
	s_waitcnt lgkmcnt(0)
	s_barrier
	s_waitcnt lgkmcnt(0)
	v_mfma_f32_16x16x32_bf16 v[62:65], v[140:143], v[176:179], v[62:65]
	v_mfma_f32_16x16x32_bf16 v[58:61], v[152:155], v[176:179], v[58:61]
	v_mfma_f32_16x16x32_bf16 v[46:49], v[140:143], v[184:187], v[46:49]
	v_mfma_f32_16x16x32_bf16 v[42:45], v[152:155], v[184:187], v[42:45]
	v_mfma_f32_16x16x32_bf16 v[30:33], v[140:143], v[202:205], v[30:33]
	v_mfma_f32_16x16x32_bf16 v[26:29], v[152:155], v[202:205], v[26:29]
	v_mfma_f32_16x16x32_bf16 v[14:17], v[140:143], v[210:213], v[14:17]
	v_mfma_f32_16x16x32_bf16 v[10:13], v[152:155], v[210:213], v[10:13]
	v_mfma_f32_16x16x32_bf16 v[62:65], v[148:151], v[180:183], v[62:65]
	v_mfma_f32_16x16x32_bf16 v[58:61], v[156:159], v[180:183], v[58:61]
	v_mfma_f32_16x16x32_bf16 v[46:49], v[148:151], v[188:191], v[46:49]
	v_mfma_f32_16x16x32_bf16 v[42:45], v[156:159], v[188:191], v[42:45]
	v_mfma_f32_16x16x32_bf16 v[30:33], v[148:151], v[206:209], v[30:33]
	v_mfma_f32_16x16x32_bf16 v[26:29], v[156:159], v[206:209], v[26:29]
	v_mfma_f32_16x16x32_bf16 v[14:17], v[148:151], v[214:217], v[14:17]
	v_mfma_f32_16x16x32_bf16 v[10:13], v[156:159], v[214:217], v[10:13]
	v_mfma_f32_16x16x32_bf16 v[54:57], v[160:163], v[176:179], v[54:57]
	v_mfma_f32_16x16x32_bf16 v[50:53], v[168:171], v[176:179], v[50:53]
	v_mfma_f32_16x16x32_bf16 v[38:41], v[160:163], v[184:187], v[38:41]
	v_mfma_f32_16x16x32_bf16 v[34:37], v[168:171], v[184:187], v[34:37]
	v_mfma_f32_16x16x32_bf16 v[22:25], v[160:163], v[202:205], v[22:25]
	v_mfma_f32_16x16x32_bf16 v[18:21], v[168:171], v[202:205], v[18:21]
	v_mfma_f32_16x16x32_bf16 v[6:9], v[160:163], v[210:213], v[6:9]
	v_mfma_f32_16x16x32_bf16 v[2:5], v[168:171], v[210:213], v[2:5]
	v_mfma_f32_16x16x32_bf16 v[54:57], v[164:167], v[180:183], v[54:57]
	v_mfma_f32_16x16x32_bf16 v[50:53], v[172:175], v[180:183], v[50:53]
	v_mfma_f32_16x16x32_bf16 v[38:41], v[164:167], v[188:191], v[38:41]
	v_mfma_f32_16x16x32_bf16 v[34:37], v[172:175], v[188:191], v[34:37]
	v_mfma_f32_16x16x32_bf16 v[22:25], v[164:167], v[206:209], v[22:25]
	v_mfma_f32_16x16x32_bf16 v[18:21], v[172:175], v[206:209], v[18:21]
	v_mfma_f32_16x16x32_bf16 v[6:9], v[164:167], v[214:217], v[6:9]
	v_mfma_f32_16x16x32_bf16 v[2:5], v[172:175], v[214:217], v[2:5]
	s_barrier
	s_add_i32 s50, s50, 2
	s_add_u32 s20, s20, 0x100
	s_addc_u32 s21, s21, 0
	s_add_u32 s48, s48, 0x100
	s_addc_u32 s49, s49, 0
	s_cmp_gt_u32 s50, 13
	s_cbranch_scc0 .LBB0_1040
	s_and_b64 vcc, exec, s[8:9]
	s_cbranch_vccz .LBB0_1043
	s_barrier

.LBB0_1130:
	s_add_u32 s28, s26, 0xfff00080
	s_addc_u32 s29, s27, -1
	s_add_i32 s56, 0, 0x10000
	s_cmp_eq_u32 s55, 60
	s_cselect_b32 s31, s7, s29
	s_cselect_b32 s30, s9, s28
	s_cselect_b32 s29, s19, s54
	s_cselect_b32 s28, s21, s53
	s_add_i32 s58, 0, 0x14000
	v_add_u32_e32 v152, s56, v167
	v_add_u32_e32 v164, s58, v167
	ds_read_b128 v[130:133], v152
	ds_read_b128 v[134:137], v152 offset:1024
	ds_read_b128 v[138:141], v152 offset:2048
	ds_read_b128 v[152:155], v152 offset:3072
	ds_read_b128 v[156:159], v164
	ds_read_b128 v[160:163], v164 offset:1024
	ds_read_b128 v[170:173], v164 offset:2048
	ds_read_b128 v[174:177], v164 offset:3072
	v_lshl_add_u64 v[164:165], s[26:27], 0, v[148:149]
	s_add_i32 m0, s44, 0xc000
	ds_read_b128 v[178:181], v169
	ds_read_b128 v[182:185], v169 offset:1024
	ds_read_b128 v[186:189], v169 offset:2048
	ds_read_b128 v[190:193], v169 offset:3072
	ds_read_b128 v[202:205], v169 offset:4096
	ds_read_b128 v[206:209], v169 offset:5120
	ds_read_b128 v[210:213], v169 offset:6144
	ds_read_b128 v[214:217], v169 offset:7168
	global_load_lds_dwordx4 v[164:165], off
	v_lshl_add_u64 v[164:165], s[26:27], 0, v[150:151]
	s_add_i32 m0, s44, 0xe000
	s_nop 0
	global_load_lds_dwordx4 v[164:165], off
	s_waitcnt vmcnt(8)
	s_waitcnt lgkmcnt(0)
	s_barrier
	s_waitcnt lgkmcnt(0)
	v_mfma_f32_16x16x32_bf16 v[126:129], v[130:133], v[178:181], v[126:129]
	v_mfma_f32_16x16x32_bf16 v[122:125], v[138:141], v[178:181], v[122:125]
	v_mfma_f32_16x16x32_bf16 v[110:113], v[130:133], v[186:189], v[110:113]
	v_mfma_f32_16x16x32_bf16 v[106:109], v[138:141], v[186:189], v[106:109]
	v_mfma_f32_16x16x32_bf16 v[94:97], v[130:133], v[202:205], v[94:97]
	v_mfma_f32_16x16x32_bf16 v[90:93], v[138:141], v[202:205], v[90:93]
	v_mfma_f32_16x16x32_bf16 v[78:81], v[130:133], v[210:213], v[78:81]
	v_mfma_f32_16x16x32_bf16 v[74:77], v[138:141], v[210:213], v[74:77]
	v_mfma_f32_16x16x32_bf16 v[126:129], v[134:137], v[182:185], v[126:129]
	v_mfma_f32_16x16x32_bf16 v[122:125], v[152:155], v[182:185], v[122:125]
	v_mfma_f32_16x16x32_bf16 v[110:113], v[134:137], v[190:193], v[110:113]
	v_mfma_f32_16x16x32_bf16 v[106:109], v[152:155], v[190:193], v[106:109]
	v_mfma_f32_16x16x32_bf16 v[94:97], v[134:137], v[206:209], v[94:97]
	v_mfma_f32_16x16x32_bf16 v[90:93], v[152:155], v[206:209], v[90:93]
	v_mfma_f32_16x16x32_bf16 v[78:81], v[134:137], v[214:217], v[78:81]
	v_mfma_f32_16x16x32_bf16 v[74:77], v[152:155], v[214:217], v[74:77]
	v_mfma_f32_16x16x32_bf16 v[118:121], v[156:159], v[178:181], v[118:121]
	v_mfma_f32_16x16x32_bf16 v[114:117], v[170:173], v[178:181], v[114:117]
	v_mfma_f32_16x16x32_bf16 v[102:105], v[156:159], v[186:189], v[102:105]
	v_mfma_f32_16x16x32_bf16 v[98:101], v[170:173], v[186:189], v[98:101]
	v_mfma_f32_16x16x32_bf16 v[86:89], v[156:159], v[202:205], v[86:89]
	v_mfma_f32_16x16x32_bf16 v[82:85], v[170:173], v[202:205], v[82:85]
	v_mfma_f32_16x16x32_bf16 v[70:73], v[156:159], v[210:213], v[70:73]
	v_mfma_f32_16x16x32_bf16 v[66:69], v[170:173], v[210:213], v[66:69]
	v_mfma_f32_16x16x32_bf16 v[118:121], v[160:163], v[182:185], v[118:121]
	v_mfma_f32_16x16x32_bf16 v[114:117], v[174:177], v[182:185], v[114:117]
	v_mfma_f32_16x16x32_bf16 v[102:105], v[160:163], v[190:193], v[102:105]
	v_mfma_f32_16x16x32_bf16 v[98:101], v[174:177], v[190:193], v[98:101]
	v_mfma_f32_16x16x32_bf16 v[86:89], v[160:163], v[206:209], v[86:89]
	v_mfma_f32_16x16x32_bf16 v[82:85], v[174:177], v[206:209], v[82:85]
	v_mfma_f32_16x16x32_bf16 v[70:73], v[160:163], v[214:217], v[70:73]
	v_mfma_f32_16x16x32_bf16 v[66:69], v[174:177], v[214:217], v[66:69]
	s_barrier
	s_add_i32 s56, s56, s43
	v_lshl_add_u64 v[164:165], s[28:29], 0, v[194:195]
	s_mov_b32 m0, s56
	ds_read_b128 v[178:181], v169 offset:16384
	ds_read_b128 v[182:185], v169 offset:17408
	ds_read_b128 v[186:189], v169 offset:18432
	ds_read_b128 v[190:193], v169 offset:19456
	ds_read_b128 v[202:205], v169 offset:20480
	ds_read_b128 v[206:209], v169 offset:21504
	ds_read_b128 v[210:213], v169 offset:22528
	ds_read_b128 v[214:217], v169 offset:23552
	global_load_lds_dwordx4 v[164:165], off
	s_add_i32 m0, s56, 0x2000
	s_add_u32 s56, s28, 0x100000
	v_lshl_add_u64 v[218:219], s[28:29], 0, v[146:147]
	s_addc_u32 s57, s29, 0
	s_add_i32 s58, s58, s43
	global_load_lds_dwordx4 v[218:219], off
	v_lshl_add_u64 v[220:221], s[56:57], 0, v[194:195]
	s_mov_b32 m0, s58
	v_lshl_add_u64 v[222:223], s[30:31], 0, v[144:145]
	global_load_lds_dwordx4 v[220:221], off
	v_lshl_add_u64 v[220:221], s[56:57], 0, v[146:147]
	s_add_i32 m0, s58, 0x2000
	s_nop 0
	global_load_lds_dwordx4 v[220:221], off
	v_lshl_add_u64 v[220:221], s[30:31], 0, v[142:143]
	s_mov_b32 m0, s44
	s_nop 0
	global_load_lds_dwordx4 v[220:221], off
	s_mov_b32 m0, s45
	s_nop 0
	global_load_lds_dwordx4 v[222:223], off
	s_waitcnt vmcnt(8)
	s_waitcnt lgkmcnt(0)
	s_barrier
	s_waitcnt lgkmcnt(0)
	v_mfma_f32_16x16x32_bf16 v[62:65], v[130:133], v[178:181], v[62:65]
	v_mfma_f32_16x16x32_bf16 v[58:61], v[138:141], v[178:181], v[58:61]
	v_mfma_f32_16x16x32_bf16 v[46:49], v[130:133], v[186:189], v[46:49]
	v_mfma_f32_16x16x32_bf16 v[42:45], v[138:141], v[186:189], v[42:45]
	v_mfma_f32_16x16x32_bf16 v[30:33], v[130:133], v[202:205], v[30:33]
	v_mfma_f32_16x16x32_bf16 v[26:29], v[138:141], v[202:205], v[26:29]
	v_mfma_f32_16x16x32_bf16 v[14:17], v[130:133], v[210:213], v[14:17]
	v_mfma_f32_16x16x32_bf16 v[10:13], v[138:141], v[210:213], v[10:13]
	v_mfma_f32_16x16x32_bf16 v[62:65], v[134:137], v[182:185], v[62:65]
	v_mfma_f32_16x16x32_bf16 v[58:61], v[152:155], v[182:185], v[58:61]
	v_mfma_f32_16x16x32_bf16 v[46:49], v[134:137], v[190:193], v[46:49]
	v_mfma_f32_16x16x32_bf16 v[42:45], v[152:155], v[190:193], v[42:45]
	v_mfma_f32_16x16x32_bf16 v[30:33], v[134:137], v[206:209], v[30:33]
	v_mfma_f32_16x16x32_bf16 v[26:29], v[152:155], v[206:209], v[26:29]
	v_mfma_f32_16x16x32_bf16 v[14:17], v[134:137], v[214:217], v[14:17]
	v_mfma_f32_16x16x32_bf16 v[10:13], v[152:155], v[214:217], v[10:13]
	v_mfma_f32_16x16x32_bf16 v[54:57], v[156:159], v[178:181], v[54:57]
	v_mfma_f32_16x16x32_bf16 v[50:53], v[170:173], v[178:181], v[50:53]
	v_mfma_f32_16x16x32_bf16 v[38:41], v[156:159], v[186:189], v[38:41]
	v_mfma_f32_16x16x32_bf16 v[34:37], v[170:173], v[186:189], v[34:37]
	v_mfma_f32_16x16x32_bf16 v[22:25], v[156:159], v[202:205], v[22:25]
	v_mfma_f32_16x16x32_bf16 v[18:21], v[170:173], v[202:205], v[18:21]
	v_mfma_f32_16x16x32_bf16 v[6:9], v[156:159], v[210:213], v[6:9]
	v_mfma_f32_16x16x32_bf16 v[2:5], v[170:173], v[210:213], v[2:5]
	v_mfma_f32_16x16x32_bf16 v[54:57], v[160:163], v[182:185], v[54:57]
	v_mfma_f32_16x16x32_bf16 v[50:53], v[174:177], v[182:185], v[50:53]
	v_mfma_f32_16x16x32_bf16 v[38:41], v[160:163], v[190:193], v[38:41]
	v_mfma_f32_16x16x32_bf16 v[34:37], v[174:177], v[190:193], v[34:37]
	v_mfma_f32_16x16x32_bf16 v[22:25], v[160:163], v[206:209], v[22:25]
	v_mfma_f32_16x16x32_bf16 v[18:21], v[174:177], v[206:209], v[18:21]
	v_mfma_f32_16x16x32_bf16 v[6:9], v[160:163], v[214:217], v[6:9]
	v_mfma_f32_16x16x32_bf16 v[2:5], v[174:177], v[214:217], v[2:5]
	s_barrier
	s_add_i32 s56, 0, 0x18000
	s_add_i32 s57, 0, 0x1c000
	v_add_u32_e32 v152, s56, v167
	v_add_u32_e32 v174, s57, v167
	ds_read_b128 v[130:133], v152
	ds_read_b128 v[134:137], v152 offset:1024
	ds_read_b128 v[138:141], v152 offset:2048
	ds_read_b128 v[152:155], v152 offset:3072
	ds_read_b128 v[156:159], v174
	ds_read_b128 v[160:163], v174 offset:1024
	ds_read_b128 v[170:173], v174 offset:2048
	ds_read_b128 v[174:177], v174 offset:3072
	s_add_u32 s30, s30, 0x100000
	s_addc_u32 s31, s31, 0
	s_mov_b32 m0, s46
	v_lshl_add_u64 v[224:225], s[30:31], 0, v[142:143]
	ds_read_b128 v[178:181], v169 offset:32768
	ds_read_b128 v[182:185], v169 offset:33792
	ds_read_b128 v[186:189], v169 offset:34816
	ds_read_b128 v[190:193], v169 offset:35840
	ds_read_b128 v[202:205], v169 offset:36864
	ds_read_b128 v[206:209], v169 offset:37888
	ds_read_b128 v[210:213], v169 offset:38912
	ds_read_b128 v[214:217], v169 offset:39936
	global_load_lds_dwordx4 v[224:225], off
	v_lshl_add_u64 v[224:225], s[30:31], 0, v[144:145]
	s_mov_b32 m0, s47
	s_nop 0
	global_load_lds_dwordx4 v[224:225], off
	s_waitcnt vmcnt(8)
	s_waitcnt lgkmcnt(0)
	s_barrier
	s_waitcnt lgkmcnt(0)
	v_mfma_f32_16x16x32_bf16 v[126:129], v[130:133], v[178:181], v[126:129]
	v_mfma_f32_16x16x32_bf16 v[122:125], v[138:141], v[178:181], v[122:125]
	v_mfma_f32_16x16x32_bf16 v[110:113], v[130:133], v[186:189], v[110:113]
	v_mfma_f32_16x16x32_bf16 v[106:109], v[138:141], v[186:189], v[106:109]
	v_mfma_f32_16x16x32_bf16 v[94:97], v[130:133], v[202:205], v[94:97]
	v_mfma_f32_16x16x32_bf16 v[90:93], v[138:141], v[202:205], v[90:93]
	v_mfma_f32_16x16x32_bf16 v[78:81], v[130:133], v[210:213], v[78:81]
	v_mfma_f32_16x16x32_bf16 v[74:77], v[138:141], v[210:213], v[74:77]
	v_mfma_f32_16x16x32_bf16 v[126:129], v[134:137], v[182:185], v[126:129]
	v_mfma_f32_16x16x32_bf16 v[122:125], v[152:155], v[182:185], v[122:125]
	v_mfma_f32_16x16x32_bf16 v[110:113], v[134:137], v[190:193], v[110:113]
	v_mfma_f32_16x16x32_bf16 v[106:109], v[152:155], v[190:193], v[106:109]
	v_mfma_f32_16x16x32_bf16 v[94:97], v[134:137], v[206:209], v[94:97]
	v_mfma_f32_16x16x32_bf16 v[90:93], v[152:155], v[206:209], v[90:93]
	v_mfma_f32_16x16x32_bf16 v[78:81], v[134:137], v[214:217], v[78:81]
	v_mfma_f32_16x16x32_bf16 v[74:77], v[152:155], v[214:217], v[74:77]
	v_mfma_f32_16x16x32_bf16 v[118:121], v[156:159], v[178:181], v[118:121]
	v_mfma_f32_16x16x32_bf16 v[114:117], v[170:173], v[178:181], v[114:117]
	v_mfma_f32_16x16x32_bf16 v[102:105], v[156:159], v[186:189], v[102:105]
	v_mfma_f32_16x16x32_bf16 v[98:101], v[170:173], v[186:189], v[98:101]
	v_mfma_f32_16x16x32_bf16 v[86:89], v[156:159], v[202:205], v[86:89]
	v_mfma_f32_16x16x32_bf16 v[82:85], v[170:173], v[202:205], v[82:85]
	v_mfma_f32_16x16x32_bf16 v[70:73], v[156:159], v[210:213], v[70:73]
	v_mfma_f32_16x16x32_bf16 v[66:69], v[170:173], v[210:213], v[66:69]
	v_mfma_f32_16x16x32_bf16 v[118:121], v[160:163], v[182:185], v[118:121]
	v_mfma_f32_16x16x32_bf16 v[114:117], v[174:177], v[182:185], v[114:117]
	v_mfma_f32_16x16x32_bf16 v[102:105], v[160:163], v[190:193], v[102:105]
	v_mfma_f32_16x16x32_bf16 v[98:101], v[174:177], v[190:193], v[98:101]
	v_mfma_f32_16x16x32_bf16 v[86:89], v[160:163], v[206:209], v[86:89]
	v_mfma_f32_16x16x32_bf16 v[82:85], v[174:177], v[206:209], v[82:85]
	v_mfma_f32_16x16x32_bf16 v[70:73], v[160:163], v[214:217], v[70:73]
	v_mfma_f32_16x16x32_bf16 v[66:69], v[174:177], v[214:217], v[66:69]
	s_barrier
	s_add_i32 s30, s56, s43
	v_lshl_add_u64 v[164:165], v[164:165], 0, s[92:93]
	s_mov_b32 m0, s30
	ds_read_b128 v[178:181], v169 offset:49152
	ds_read_b128 v[182:185], v169 offset:50176
	ds_read_b128 v[186:189], v169 offset:51200
	ds_read_b128 v[190:193], v169 offset:52224
	ds_read_b128 v[202:205], v169 offset:53248
	ds_read_b128 v[206:209], v169 offset:54272
	ds_read_b128 v[210:213], v169 offset:55296
	ds_read_b128 v[214:217], v169 offset:56320
	global_load_lds_dwordx4 v[164:165], off
	s_add_i32 m0, s30, 0x2000
	s_add_u32 s28, s28, 0x100080
	v_lshl_add_u64 v[164:165], v[218:219], 0, s[92:93]
	s_addc_u32 s29, s29, 0
	s_add_i32 s30, s57, s43
	global_load_lds_dwordx4 v[164:165], off
	v_lshl_add_u64 v[164:165], s[28:29], 0, v[194:195]
	s_mov_b32 m0, s30
	s_nop 0
	global_load_lds_dwordx4 v[164:165], off
	v_lshl_add_u64 v[164:165], s[28:29], 0, v[146:147]
	s_add_i32 m0, s30, 0x2000
	s_nop 0
	global_load_lds_dwordx4 v[164:165], off
	v_lshl_add_u64 v[164:165], v[220:221], 0, s[92:93]
	s_mov_b32 m0, s49
	s_nop 0
	global_load_lds_dwordx4 v[164:165], off
	v_lshl_add_u64 v[164:165], v[222:223], 0, s[92:93]
	s_mov_b32 m0, s50
	s_nop 0
	global_load_lds_dwordx4 v[164:165], off
	s_waitcnt vmcnt(8)
	s_waitcnt lgkmcnt(0)
	s_barrier
	s_waitcnt lgkmcnt(0)
	v_mfma_f32_16x16x32_bf16 v[62:65], v[130:133], v[178:181], v[62:65]
	v_mfma_f32_16x16x32_bf16 v[58:61], v[138:141], v[178:181], v[58:61]
	v_mfma_f32_16x16x32_bf16 v[46:49], v[130:133], v[186:189], v[46:49]
	v_mfma_f32_16x16x32_bf16 v[42:45], v[138:141], v[186:189], v[42:45]
	v_mfma_f32_16x16x32_bf16 v[30:33], v[130:133], v[202:205], v[30:33]
	v_mfma_f32_16x16x32_bf16 v[26:29], v[138:141], v[202:205], v[26:29]
	v_mfma_f32_16x16x32_bf16 v[14:17], v[130:133], v[210:213], v[14:17]
	v_mfma_f32_16x16x32_bf16 v[10:13], v[138:141], v[210:213], v[10:13]
	v_mfma_f32_16x16x32_bf16 v[62:65], v[134:137], v[182:185], v[62:65]
	v_mfma_f32_16x16x32_bf16 v[58:61], v[152:155], v[182:185], v[58:61]
	v_mfma_f32_16x16x32_bf16 v[46:49], v[134:137], v[190:193], v[46:49]
	v_mfma_f32_16x16x32_bf16 v[42:45], v[152:155], v[190:193], v[42:45]
	v_mfma_f32_16x16x32_bf16 v[30:33], v[134:137], v[206:209], v[30:33]
	v_mfma_f32_16x16x32_bf16 v[26:29], v[152:155], v[206:209], v[26:29]
	v_mfma_f32_16x16x32_bf16 v[14:17], v[134:137], v[214:217], v[14:17]
	v_mfma_f32_16x16x32_bf16 v[10:13], v[152:155], v[214:217], v[10:13]
	v_mfma_f32_16x16x32_bf16 v[54:57], v[156:159], v[178:181], v[54:57]
	v_mfma_f32_16x16x32_bf16 v[50:53], v[170:173], v[178:181], v[50:53]
	v_mfma_f32_16x16x32_bf16 v[38:41], v[156:159], v[186:189], v[38:41]
	v_mfma_f32_16x16x32_bf16 v[34:37], v[170:173], v[186:189], v[34:37]
	v_mfma_f32_16x16x32_bf16 v[22:25], v[156:159], v[202:205], v[22:25]
	v_mfma_f32_16x16x32_bf16 v[18:21], v[170:173], v[202:205], v[18:21]
	v_mfma_f32_16x16x32_bf16 v[6:9], v[156:159], v[210:213], v[6:9]
	v_mfma_f32_16x16x32_bf16 v[2:5], v[170:173], v[210:213], v[2:5]
	v_mfma_f32_16x16x32_bf16 v[54:57], v[160:163], v[182:185], v[54:57]
	v_mfma_f32_16x16x32_bf16 v[50:53], v[174:177], v[182:185], v[50:53]
	v_mfma_f32_16x16x32_bf16 v[38:41], v[160:163], v[190:193], v[38:41]
	v_mfma_f32_16x16x32_bf16 v[34:37], v[174:177], v[190:193], v[34:37]
	v_mfma_f32_16x16x32_bf16 v[22:25], v[160:163], v[206:209], v[22:25]
	v_mfma_f32_16x16x32_bf16 v[18:21], v[174:177], v[206:209], v[18:21]
	v_mfma_f32_16x16x32_bf16 v[6:9], v[160:163], v[214:217], v[6:9]
	v_mfma_f32_16x16x32_bf16 v[2:5], v[174:177], v[214:217], v[2:5]
	s_barrier
	s_add_i32 s55, s55, 2
	s_add_u32 s26, s26, 0x100
	s_addc_u32 s27, s27, 0
	s_add_u32 s53, s53, 0x100
	s_addc_u32 s54, s54, 0
	s_cmp_gt_u32 s55, 61
	s_cbranch_scc0 .LBB0_1130
	v_lshl_add_u32 v154, s6, 8, v166
	v_lshl_or_b32 v152, s8, 8, v168
	v_ashrrev_i32_e32 v155, 31, v154
	v_lshlrev_b64 v[130:131], 11, v[154:155]
	v_ashrrev_i32_e32 v153, 31, v152
	v_or_b32_e32 v156, 16, v154
	v_lshl_add_u64 v[130:131], s[12:13], 0, v[130:131]
	v_lshlrev_b64 v[132:133], 1, v[152:153]
	v_ashrrev_i32_e32 v157, 31, v156
	v_lshl_add_u64 v[160:161], v[130:131], 0, v[132:133]
	v_lshlrev_b64 v[130:131], 11, v[156:157]
	global_load_dwordx4 v[170:173], v[160:161], off
	global_load_dwordx4 v[138:141], v[160:161], off offset:256
	v_lshl_add_u64 v[130:131], s[12:13], 0, v[130:131]
	v_lshl_add_u64 v[158:159], v[130:131], 0, v[132:133]
	global_load_dwordx4 v[134:137], v[158:159], off
	global_load_dwordx4 v[130:133], v[158:159], off offset:256
	v_cndmask_b32_e64 v162, 0, 1, s[16:17]
	v_cmp_ne_u32_e64 s[6:7], 1, v162
	v_lshlrev_b64 v[162:163], 10, v[154:155]
	v_lshl_add_u64 v[162:163], v[162:163], 0, v[152:153]
	s_andn2_b64 vcc, exec, s[16:17]
	s_waitcnt vmcnt(0)
	v_lshlrev_b32_e32 v164, 16, v170
	v_and_b32_e32 v165, 0xffff0000, v170
	v_lshlrev_b32_e32 v170, 16, v171
	v_and_b32_e32 v171, 0xffff0000, v171
	v_lshlrev_b32_e32 v174, 16, v172
	v_and_b32_e32 v175, 0xffff0000, v172
	v_lshlrev_b32_e32 v172, 16, v173
	v_and_b32_e32 v173, 0xffff0000, v173
	v_pk_add_f32 v[126:127], v[126:127], v[164:165]
	v_pk_add_f32 v[128:129], v[128:129], v[170:171]
	v_pk_add_f32 v[122:123], v[122:123], v[174:175]
	v_pk_add_f32 v[124:125], v[124:125], v[172:173]
	v_lshl_add_u64 v[164:165], v[162:163], 2, s[14:15]
	s_cbranch_vccnz .LBB0_1210
	global_store_dwordx4 v[164:165], v[126:129], off
	global_store_dwordx4 v[164:165], v[122:125], off offset:16
	s_cbranch_execnz .LBB0_1134

.LBB0_1234:
	s_and_b32 s4, s10, 0x60
	s_or_b32 s11, s4, s7
	v_readfirstlane_b32 s12, v4
	v_readfirstlane_b32 s13, v5
	v_readfirstlane_b32 s14, v2
	v_readfirstlane_b32 s15, v3
	s_and_b32 s16, s9, -16
	v_and_b32_e32 v249, 63, v0
	v_lshrrev_b32_e32 v248, 2, v249
	v_and_b32_e32 v246, 3, v249
	v_lshlrev_b32_e32 v246, 4, v246
	v_add_u32_e32 v247, s16, v248
	v_lshl_add_u32 v247, v247, 13, v246
	v_add_u32_e32 v249, s11, v248
	v_lshl_add_u32 v246, v249, 13, v246
	v_and_b32_e32 v249, 63, v0
	v_and_b32_e32 v248, 15, v249
	v_lshrrev_b32_e32 v249, 4, v249
	v_lshl_add_u32 v248, v248, 2, v249
	v_lshlrev_b32_e32 v248, 2, v248
	global_load_dwordx4 v[16:19], v246, s[12:13]
	global_load_dwordx4 v[20:23], v247, s[14:15]
	global_load_dwordx4 v[24:27], v246, s[12:13] offset:64
	global_load_dwordx4 v[28:31], v247, s[14:15] offset:64
	global_load_dwordx4 v[32:35], v246, s[12:13] offset:128
	global_load_dwordx4 v[36:39], v247, s[14:15] offset:128
	global_load_dwordx4 v[40:43], v246, s[12:13] offset:192
	global_load_dwordx4 v[44:47], v247, s[14:15] offset:192
	global_load_dwordx4 v[48:51], v246, s[12:13] offset:256
	global_load_dwordx4 v[52:55], v247, s[14:15] offset:256
	global_load_dwordx4 v[56:59], v246, s[12:13] offset:320
	global_load_dwordx4 v[60:63], v247, s[14:15] offset:320
	global_load_dwordx4 v[64:67], v246, s[12:13] offset:384
	global_load_dwordx4 v[68:71], v247, s[14:15] offset:384
	global_load_dwordx4 v[72:75], v246, s[12:13] offset:448
	global_load_dwordx4 v[76:79], v247, s[14:15] offset:448
	global_load_dwordx4 v[80:83], v246, s[12:13] offset:512
	global_load_dwordx4 v[84:87], v247, s[14:15] offset:512
	global_load_dwordx4 v[88:91], v246, s[12:13] offset:576
	global_load_dwordx4 v[92:95], v247, s[14:15] offset:576
	global_load_dwordx4 v[96:99], v246, s[12:13] offset:640
	global_load_dwordx4 v[100:103], v247, s[14:15] offset:640
	global_load_dwordx4 v[104:107], v246, s[12:13] offset:704
	global_load_dwordx4 v[108:111], v247, s[14:15] offset:704
	global_load_dwordx4 v[112:115], v246, s[12:13] offset:768
	global_load_dwordx4 v[116:119], v247, s[14:15] offset:768
	global_load_dwordx4 v[120:123], v246, s[12:13] offset:832
	global_load_dwordx4 v[124:127], v247, s[14:15] offset:832
	global_load_dwordx4 v[128:131], v246, s[12:13] offset:896
	global_load_dwordx4 v[132:135], v247, s[14:15] offset:896
	global_load_dwordx4 v[136:139], v246, s[12:13] offset:960
	global_load_dwordx4 v[140:143], v247, s[14:15] offset:960
	global_load_dwordx4 v[144:147], v246, s[12:13] offset:1024
	global_load_dwordx4 v[148:151], v247, s[14:15] offset:1024
	global_load_dwordx4 v[152:155], v246, s[12:13] offset:1088
	global_load_dwordx4 v[156:159], v247, s[14:15] offset:1088
	global_load_dwordx4 v[160:163], v246, s[12:13] offset:1152
	global_load_dwordx4 v[164:167], v247, s[14:15] offset:1152
	global_load_dwordx4 v[168:171], v246, s[12:13] offset:1216
	global_load_dwordx4 v[172:175], v247, s[14:15] offset:1216
	s_waitcnt vmcnt(38)
	ds_bpermute_b32 v206, v248, v16
	ds_bpermute_b32 v207, v248, v17
	ds_bpermute_b32 v208, v248, v18
	ds_bpermute_b32 v209, v248, v19
	ds_bpermute_b32 v210, v248, v20
	ds_bpermute_b32 v211, v248, v21
	ds_bpermute_b32 v212, v248, v22
	ds_bpermute_b32 v213, v248, v23
	global_load_dwordx4 v[16:19], v246, s[12:13] offset:1280
	global_load_dwordx4 v[20:23], v247, s[14:15] offset:1280
	s_waitcnt vmcnt(38)
	ds_bpermute_b32 v214, v248, v24
	ds_bpermute_b32 v215, v248, v25
	ds_bpermute_b32 v216, v248, v26
	ds_bpermute_b32 v217, v248, v27
	s_waitcnt lgkmcnt(4)
	v_mfma_f32_16x16x32_bf16 v[12:15], v[206:209], v[210:213], 0
	ds_bpermute_b32 v218, v248, v28
	ds_bpermute_b32 v219, v248, v29
	ds_bpermute_b32 v220, v248, v30
	ds_bpermute_b32 v221, v248, v31
	global_load_dwordx4 v[24:27], v246, s[12:13] offset:1344
	global_load_dwordx4 v[28:31], v247, s[14:15] offset:1344
	s_waitcnt vmcnt(38)
	ds_bpermute_b32 v222, v248, v32
	ds_bpermute_b32 v223, v248, v33
	ds_bpermute_b32 v224, v248, v34
	ds_bpermute_b32 v225, v248, v35
	s_waitcnt lgkmcnt(4)
	v_mfma_f32_16x16x32_bf16 v[12:15], v[214:217], v[218:221], v[12:15]
	ds_bpermute_b32 v226, v248, v36
	ds_bpermute_b32 v227, v248, v37
	ds_bpermute_b32 v228, v248, v38
	ds_bpermute_b32 v229, v248, v39
	global_load_dwordx4 v[32:35], v246, s[12:13] offset:1408
	global_load_dwordx4 v[36:39], v247, s[14:15] offset:1408
	s_waitcnt vmcnt(38)
	ds_bpermute_b32 v206, v248, v40
	ds_bpermute_b32 v207, v248, v41
	ds_bpermute_b32 v208, v248, v42
	ds_bpermute_b32 v209, v248, v43
	s_waitcnt lgkmcnt(4)
	v_mfma_f32_16x16x32_bf16 v[12:15], v[222:225], v[226:229], v[12:15]
	ds_bpermute_b32 v210, v248, v44
	ds_bpermute_b32 v211, v248, v45
	ds_bpermute_b32 v212, v248, v46
	ds_bpermute_b32 v213, v248, v47
	global_load_dwordx4 v[40:43], v246, s[12:13] offset:1472
	global_load_dwordx4 v[44:47], v247, s[14:15] offset:1472
	s_waitcnt vmcnt(38)
	ds_bpermute_b32 v214, v248, v48
	ds_bpermute_b32 v215, v248, v49
	ds_bpermute_b32 v216, v248, v50
	ds_bpermute_b32 v217, v248, v51
	s_waitcnt lgkmcnt(4)
	v_mfma_f32_16x16x32_bf16 v[12:15], v[206:209], v[210:213], v[12:15]
	ds_bpermute_b32 v218, v248, v52
	ds_bpermute_b32 v219, v248, v53
	ds_bpermute_b32 v220, v248, v54
	ds_bpermute_b32 v221, v248, v55
	global_load_dwordx4 v[48:51], v246, s[12:13] offset:1536
	global_load_dwordx4 v[52:55], v247, s[14:15] offset:1536
	s_waitcnt vmcnt(38)
	ds_bpermute_b32 v222, v248, v56
	ds_bpermute_b32 v223, v248, v57
	ds_bpermute_b32 v224, v248, v58
	ds_bpermute_b32 v225, v248, v59
	s_waitcnt lgkmcnt(4)
	v_mfma_f32_16x16x32_bf16 v[12:15], v[214:217], v[218:221], v[12:15]
	ds_bpermute_b32 v226, v248, v60
	ds_bpermute_b32 v227, v248, v61
	ds_bpermute_b32 v228, v248, v62
	ds_bpermute_b32 v229, v248, v63
	global_load_dwordx4 v[56:59], v246, s[12:13] offset:1600
	global_load_dwordx4 v[60:63], v247, s[14:15] offset:1600
	s_waitcnt vmcnt(38)
	ds_bpermute_b32 v206, v248, v64
	ds_bpermute_b32 v207, v248, v65
	ds_bpermute_b32 v208, v248, v66
	ds_bpermute_b32 v209, v248, v67
	s_waitcnt lgkmcnt(4)
	v_mfma_f32_16x16x32_bf16 v[12:15], v[222:225], v[226:229], v[12:15]
	ds_bpermute_b32 v210, v248, v68
	ds_bpermute_b32 v211, v248, v69
	ds_bpermute_b32 v212, v248, v70
	ds_bpermute_b32 v213, v248, v71
	global_load_dwordx4 v[64:67], v246, s[12:13] offset:1664
	global_load_dwordx4 v[68:71], v247, s[14:15] offset:1664
	s_waitcnt vmcnt(38)
	ds_bpermute_b32 v214, v248, v72
	ds_bpermute_b32 v215, v248, v73
	ds_bpermute_b32 v216, v248, v74
	ds_bpermute_b32 v217, v248, v75
	s_waitcnt lgkmcnt(4)
	v_mfma_f32_16x16x32_bf16 v[12:15], v[206:209], v[210:213], v[12:15]
	ds_bpermute_b32 v218, v248, v76
	ds_bpermute_b32 v219, v248, v77
	ds_bpermute_b32 v220, v248, v78
	ds_bpermute_b32 v221, v248, v79
	global_load_dwordx4 v[72:75], v246, s[12:13] offset:1728
	global_load_dwordx4 v[76:79], v247, s[14:15] offset:1728
	s_waitcnt vmcnt(38)
	ds_bpermute_b32 v222, v248, v80
	ds_bpermute_b32 v223, v248, v81
	ds_bpermute_b32 v224, v248, v82
	ds_bpermute_b32 v225, v248, v83
	s_waitcnt lgkmcnt(4)
	v_mfma_f32_16x16x32_bf16 v[12:15], v[214:217], v[218:221], v[12:15]
	ds_bpermute_b32 v226, v248, v84
	ds_bpermute_b32 v227, v248, v85
	ds_bpermute_b32 v228, v248, v86
	ds_bpermute_b32 v229, v248, v87
	global_load_dwordx4 v[80:83], v246, s[12:13] offset:1792
	global_load_dwordx4 v[84:87], v247, s[14:15] offset:1792
	s_waitcnt vmcnt(38)
	ds_bpermute_b32 v206, v248, v88
	ds_bpermute_b32 v207, v248, v89
	ds_bpermute_b32 v208, v248, v90
	ds_bpermute_b32 v209, v248, v91
	s_waitcnt lgkmcnt(4)
	v_mfma_f32_16x16x32_bf16 v[12:15], v[222:225], v[226:229], v[12:15]
	ds_bpermute_b32 v210, v248, v92
	ds_bpermute_b32 v211, v248, v93
	ds_bpermute_b32 v212, v248, v94
	ds_bpermute_b32 v213, v248, v95
	global_load_dwordx4 v[88:91], v246, s[12:13] offset:1856
	global_load_dwordx4 v[92:95], v247, s[14:15] offset:1856
	s_waitcnt vmcnt(38)
	ds_bpermute_b32 v214, v248, v96
	ds_bpermute_b32 v215, v248, v97
	ds_bpermute_b32 v216, v248, v98
	ds_bpermute_b32 v217, v248, v99
	s_waitcnt lgkmcnt(4)
	v_mfma_f32_16x16x32_bf16 v[12:15], v[206:209], v[210:213], v[12:15]
	ds_bpermute_b32 v218, v248, v100
	ds_bpermute_b32 v219, v248, v101
	ds_bpermute_b32 v220, v248, v102
	ds_bpermute_b32 v221, v248, v103
	global_load_dwordx4 v[96:99], v246, s[12:13] offset:1920
	global_load_dwordx4 v[100:103], v247, s[14:15] offset:1920
	s_waitcnt vmcnt(38)
	ds_bpermute_b32 v222, v248, v104
	ds_bpermute_b32 v223, v248, v105
	ds_bpermute_b32 v224, v248, v106
	ds_bpermute_b32 v225, v248, v107
	s_waitcnt lgkmcnt(4)
	v_mfma_f32_16x16x32_bf16 v[12:15], v[214:217], v[218:221], v[12:15]
	ds_bpermute_b32 v226, v248, v108
	ds_bpermute_b32 v227, v248, v109
	ds_bpermute_b32 v228, v248, v110
	ds_bpermute_b32 v229, v248, v111
	global_load_dwordx4 v[104:107], v246, s[12:13] offset:1984
	global_load_dwordx4 v[108:111], v247, s[14:15] offset:1984
	s_waitcnt vmcnt(38)
	ds_bpermute_b32 v206, v248, v112
	ds_bpermute_b32 v207, v248, v113
	ds_bpermute_b32 v208, v248, v114
	ds_bpermute_b32 v209, v248, v115
	s_waitcnt lgkmcnt(4)
	v_mfma_f32_16x16x32_bf16 v[12:15], v[222:225], v[226:229], v[12:15]
	ds_bpermute_b32 v210, v248, v116
	ds_bpermute_b32 v211, v248, v117
	ds_bpermute_b32 v212, v248, v118
	ds_bpermute_b32 v213, v248, v119
	s_waitcnt vmcnt(36)
	ds_bpermute_b32 v214, v248, v120
	ds_bpermute_b32 v215, v248, v121
	ds_bpermute_b32 v216, v248, v122
	ds_bpermute_b32 v217, v248, v123
	s_waitcnt lgkmcnt(4)
	v_mfma_f32_16x16x32_bf16 v[12:15], v[206:209], v[210:213], v[12:15]
	ds_bpermute_b32 v218, v248, v124
	ds_bpermute_b32 v219, v248, v125
	ds_bpermute_b32 v220, v248, v126
	ds_bpermute_b32 v221, v248, v127
	s_waitcnt vmcnt(34)
	ds_bpermute_b32 v222, v248, v128
	ds_bpermute_b32 v223, v248, v129
	ds_bpermute_b32 v224, v248, v130
	ds_bpermute_b32 v225, v248, v131
	s_waitcnt lgkmcnt(4)
	v_mfma_f32_16x16x32_bf16 v[12:15], v[214:217], v[218:221], v[12:15]
	ds_bpermute_b32 v226, v248, v132
	ds_bpermute_b32 v227, v248, v133
	ds_bpermute_b32 v228, v248, v134
	ds_bpermute_b32 v229, v248, v135
	s_waitcnt vmcnt(32)
	ds_bpermute_b32 v206, v248, v136
	ds_bpermute_b32 v207, v248, v137
	ds_bpermute_b32 v208, v248, v138
	ds_bpermute_b32 v209, v248, v139
	s_waitcnt lgkmcnt(4)
	v_mfma_f32_16x16x32_bf16 v[12:15], v[222:225], v[226:229], v[12:15]
	ds_bpermute_b32 v210, v248, v140
	ds_bpermute_b32 v211, v248, v141
	ds_bpermute_b32 v212, v248, v142
	ds_bpermute_b32 v213, v248, v143
	s_waitcnt vmcnt(30)
	ds_bpermute_b32 v214, v248, v144
	ds_bpermute_b32 v215, v248, v145
	ds_bpermute_b32 v216, v248, v146
	ds_bpermute_b32 v217, v248, v147
	s_waitcnt lgkmcnt(4)
	v_mfma_f32_16x16x32_bf16 v[12:15], v[206:209], v[210:213], v[12:15]
	ds_bpermute_b32 v218, v248, v148
	ds_bpermute_b32 v219, v248, v149
	ds_bpermute_b32 v220, v248, v150
	ds_bpermute_b32 v221, v248, v151
	s_waitcnt vmcnt(28)
	ds_bpermute_b32 v222, v248, v152
	ds_bpermute_b32 v223, v248, v153
	ds_bpermute_b32 v224, v248, v154
	ds_bpermute_b32 v225, v248, v155
	s_waitcnt lgkmcnt(4)
	v_mfma_f32_16x16x32_bf16 v[12:15], v[214:217], v[218:221], v[12:15]
	ds_bpermute_b32 v226, v248, v156
	ds_bpermute_b32 v227, v248, v157
	ds_bpermute_b32 v228, v248, v158
	ds_bpermute_b32 v229, v248, v159
	s_waitcnt vmcnt(26)
	ds_bpermute_b32 v206, v248, v160
	ds_bpermute_b32 v207, v248, v161
	ds_bpermute_b32 v208, v248, v162
	ds_bpermute_b32 v209, v248, v163
	s_waitcnt lgkmcnt(4)
	v_mfma_f32_16x16x32_bf16 v[12:15], v[222:225], v[226:229], v[12:15]
	ds_bpermute_b32 v210, v248, v164
	ds_bpermute_b32 v211, v248, v165
	ds_bpermute_b32 v212, v248, v166
	ds_bpermute_b32 v213, v248, v167
	s_waitcnt vmcnt(24)
	ds_bpermute_b32 v214, v248, v168
	ds_bpermute_b32 v215, v248, v169
	ds_bpermute_b32 v216, v248, v170
	ds_bpermute_b32 v217, v248, v171
	s_waitcnt lgkmcnt(4)
	v_mfma_f32_16x16x32_bf16 v[12:15], v[206:209], v[210:213], v[12:15]
	ds_bpermute_b32 v218, v248, v172
	ds_bpermute_b32 v219, v248, v173
	ds_bpermute_b32 v220, v248, v174
	ds_bpermute_b32 v221, v248, v175
	s_waitcnt vmcnt(22)
	ds_bpermute_b32 v222, v248, v16
	ds_bpermute_b32 v223, v248, v17
	ds_bpermute_b32 v224, v248, v18
	ds_bpermute_b32 v225, v248, v19
	s_waitcnt lgkmcnt(4)
	v_mfma_f32_16x16x32_bf16 v[12:15], v[214:217], v[218:221], v[12:15]
	ds_bpermute_b32 v226, v248, v20
	ds_bpermute_b32 v227, v248, v21
	ds_bpermute_b32 v228, v248, v22
	ds_bpermute_b32 v229, v248, v23
	s_waitcnt vmcnt(20)
	ds_bpermute_b32 v206, v248, v24
	ds_bpermute_b32 v207, v248, v25
	ds_bpermute_b32 v208, v248, v26
	ds_bpermute_b32 v209, v248, v27
	s_waitcnt lgkmcnt(4)
	v_mfma_f32_16x16x32_bf16 v[12:15], v[222:225], v[226:229], v[12:15]
	ds_bpermute_b32 v210, v248, v28
	ds_bpermute_b32 v211, v248, v29
	ds_bpermute_b32 v212, v248, v30
	ds_bpermute_b32 v213, v248, v31
	s_waitcnt vmcnt(18)
	ds_bpermute_b32 v214, v248, v32
	ds_bpermute_b32 v215, v248, v33
	ds_bpermute_b32 v216, v248, v34
	ds_bpermute_b32 v217, v248, v35
	s_waitcnt lgkmcnt(4)
	v_mfma_f32_16x16x32_bf16 v[12:15], v[206:209], v[210:213], v[12:15]
	ds_bpermute_b32 v218, v248, v36
	ds_bpermute_b32 v219, v248, v37
	ds_bpermute_b32 v220, v248, v38
	ds_bpermute_b32 v221, v248, v39
	s_waitcnt vmcnt(16)
	ds_bpermute_b32 v222, v248, v40
	ds_bpermute_b32 v223, v248, v41
	ds_bpermute_b32 v224, v248, v42
	ds_bpermute_b32 v225, v248, v43
	s_waitcnt lgkmcnt(4)
	v_mfma_f32_16x16x32_bf16 v[12:15], v[214:217], v[218:221], v[12:15]
	ds_bpermute_b32 v226, v248, v44
	ds_bpermute_b32 v227, v248, v45
	ds_bpermute_b32 v228, v248, v46
	ds_bpermute_b32 v229, v248, v47
	s_waitcnt vmcnt(14)
	ds_bpermute_b32 v206, v248, v48
	ds_bpermute_b32 v207, v248, v49
	ds_bpermute_b32 v208, v248, v50
	ds_bpermute_b32 v209, v248, v51
	s_waitcnt lgkmcnt(4)
	v_mfma_f32_16x16x32_bf16 v[12:15], v[222:225], v[226:229], v[12:15]
	ds_bpermute_b32 v210, v248, v52
	ds_bpermute_b32 v211, v248, v53
	ds_bpermute_b32 v212, v248, v54
	ds_bpermute_b32 v213, v248, v55
	s_waitcnt vmcnt(12)
	ds_bpermute_b32 v214, v248, v56
	ds_bpermute_b32 v215, v248, v57
	ds_bpermute_b32 v216, v248, v58
	ds_bpermute_b32 v217, v248, v59
	s_waitcnt lgkmcnt(4)
	v_mfma_f32_16x16x32_bf16 v[12:15], v[206:209], v[210:213], v[12:15]
	ds_bpermute_b32 v218, v248, v60
	ds_bpermute_b32 v219, v248, v61
	ds_bpermute_b32 v220, v248, v62
	ds_bpermute_b32 v221, v248, v63
	s_waitcnt vmcnt(10)
	ds_bpermute_b32 v222, v248, v64
	ds_bpermute_b32 v223, v248, v65
	ds_bpermute_b32 v224, v248, v66
	ds_bpermute_b32 v225, v248, v67
	s_waitcnt lgkmcnt(4)
	v_mfma_f32_16x16x32_bf16 v[12:15], v[214:217], v[218:221], v[12:15]
	ds_bpermute_b32 v226, v248, v68
	ds_bpermute_b32 v227, v248, v69
	ds_bpermute_b32 v228, v248, v70
	ds_bpermute_b32 v229, v248, v71
	s_waitcnt vmcnt(8)
	ds_bpermute_b32 v206, v248, v72
	ds_bpermute_b32 v207, v248, v73
	ds_bpermute_b32 v208, v248, v74
	ds_bpermute_b32 v209, v248, v75
	s_waitcnt lgkmcnt(4)
	v_mfma_f32_16x16x32_bf16 v[12:15], v[222:225], v[226:229], v[12:15]
	ds_bpermute_b32 v210, v248, v76
	ds_bpermute_b32 v211, v248, v77
	ds_bpermute_b32 v212, v248, v78
	ds_bpermute_b32 v213, v248, v79
	s_waitcnt vmcnt(6)
	ds_bpermute_b32 v214, v248, v80
	ds_bpermute_b32 v215, v248, v81
	ds_bpermute_b32 v216, v248, v82
	ds_bpermute_b32 v217, v248, v83
	s_waitcnt lgkmcnt(4)
	v_mfma_f32_16x16x32_bf16 v[12:15], v[206:209], v[210:213], v[12:15]
	ds_bpermute_b32 v218, v248, v84
	ds_bpermute_b32 v219, v248, v85
	ds_bpermute_b32 v220, v248, v86
	ds_bpermute_b32 v221, v248, v87
	s_waitcnt vmcnt(4)
	ds_bpermute_b32 v222, v248, v88
	ds_bpermute_b32 v223, v248, v89
	ds_bpermute_b32 v224, v248, v90
	ds_bpermute_b32 v225, v248, v91
	s_waitcnt lgkmcnt(4)
	v_mfma_f32_16x16x32_bf16 v[12:15], v[214:217], v[218:221], v[12:15]
	ds_bpermute_b32 v226, v248, v92
	ds_bpermute_b32 v227, v248, v93
	ds_bpermute_b32 v228, v248, v94
	ds_bpermute_b32 v229, v248, v95
	s_waitcnt vmcnt(2)
	ds_bpermute_b32 v206, v248, v96
	ds_bpermute_b32 v207, v248, v97
	ds_bpermute_b32 v208, v248, v98
	ds_bpermute_b32 v209, v248, v99
	s_waitcnt lgkmcnt(4)
	v_mfma_f32_16x16x32_bf16 v[12:15], v[222:225], v[226:229], v[12:15]
	ds_bpermute_b32 v210, v248, v100
	ds_bpermute_b32 v211, v248, v101
	ds_bpermute_b32 v212, v248, v102
	ds_bpermute_b32 v213, v248, v103
	s_waitcnt vmcnt(0)
	ds_bpermute_b32 v214, v248, v104
	ds_bpermute_b32 v215, v248, v105
	ds_bpermute_b32 v216, v248, v106
	ds_bpermute_b32 v217, v248, v107
	s_waitcnt lgkmcnt(4)
	v_mfma_f32_16x16x32_bf16 v[12:15], v[206:209], v[210:213], v[12:15]
	ds_bpermute_b32 v218, v248, v108
	ds_bpermute_b32 v219, v248, v109
	ds_bpermute_b32 v220, v248, v110
	ds_bpermute_b32 v221, v248, v111
	s_waitcnt lgkmcnt(0)
	v_mfma_f32_16x16x32_bf16 v[12:15], v[214:217], v[218:221], v[12:15]
	s_and_b32 s4, s9, -16
	s_andn2_b64 vcc, exec, s[0:1]
	v_add_u32_e32 v36, s8, v8
	s_barrier
	s_nop 7
	ds_write_b128 v11, v[12:15]
	ds_write_b32 v36, v195 offset:32768
	s_waitcnt lgkmcnt(0)
	s_barrier
	s_cbranch_vccnz .LBB0_1233
	s_ashr_i32 s5, s4, 31
	v_lshl_add_u64 v[12:13], s[4:5], 2, v[6:7]
	v_lshl_or_b32 v194, s11, 12, v10
	v_lshl_add_u64 v[28:29], v[12:13], 0, v[194:195]
	s_movk_i32 s4, 0x2000
	v_add_co_u32_e32 v30, vcc, s4, v28
	s_nop 1
	v_addc_co_u32_e32 v31, vcc, 0, v29, vcc
	v_add_co_u32_e32 v32, vcc, 0x3000, v28
	global_load_dword v34, v[28:29], off
	global_load_dword v35, v[30:31], off offset:-4096
	global_load_dword v36, v[30:31], off
	v_addc_co_u32_e32 v33, vcc, 0, v29, vcc
	global_load_dword v37, v[32:33], off
	ds_read_b128 v[12:15], v11
	ds_read_b128 v[16:19], v11 offset:2048
	ds_read_b128 v[20:23], v11 offset:4096
	ds_read_b128 v[24:27], v11 offset:6144
	s_waitcnt lgkmcnt(2)
	v_add_f32_e32 v12, v12, v16
	v_add_f32_e32 v13, v13, v17
	s_waitcnt lgkmcnt(0)
	v_add_f32_e32 v16, v20, v24
	v_add_f32_e32 v17, v21, v25
	v_add_f32_e32 v12, v12, v16
	v_add_f32_e32 v14, v14, v18
	v_add_f32_e32 v18, v22, v26
	v_add_f32_e32 v15, v15, v19
	v_add_f32_e32 v19, v23, v27
	v_add_f32_e32 v13, v13, v17
	v_add_f32_e32 v14, v14, v18
	v_add_f32_e32 v15, v15, v19
	s_waitcnt vmcnt(3)
	v_add_f32_e32 v12, v34, v12
	global_store_dword v[28:29], v12, off
	s_waitcnt vmcnt(3)
	v_add_f32_e32 v12, v13, v35
	s_waitcnt vmcnt(2)
	v_add_f32_e32 v13, v14, v36
	global_store_dword v[30:31], v12, off offset:-4096
	global_store_dword v[30:31], v13, off
	s_waitcnt vmcnt(3)
	v_add_f32_e32 v12, v15, v37
	global_store_dword v[32:33], v12, off
	s_branch .LBB0_1233
